# v4
# baseline (speedup 1.0000x reference)
.LBB0_263:
	s_add_u32 s8, s88, 0x114db700
	s_addc_u32 s9, s89, 0
	s_add_u32 s10, s88, 0x196db700
	s_addc_u32 s11, s89, 0
	s_add_u32 s12, s88, 0x19edb700
	s_addc_u32 s13, s89, 0
	s_lshl_b32 s6, s85, 5
	s_and_b32 s15, s6, 0x60
	s_add_i32 m0, s58, 0x18000
	v_lshl_add_u64 v[6:7], v[6:7], 0, s[54:55]
	s_lshl_b32 s14, s5, 6
	s_lshl_b32 s5, s5, 13
	s_lshl_b32 s16, s15, 7
	s_waitcnt vmcnt(4)
	s_barrier
	global_load_lds_dwordx4 v[6:7], off
	v_lshl_add_u64 v[4:5], v[4:5], 0, s[54:55]
	s_add_i32 m0, s58, 0x1a000
	s_add_i32 s62, s58, 0x8000
	s_add_i32 s63, s58, 0xa000
	global_load_lds_dwordx4 v[4:5], off
	v_lshl_add_u64 v[2:3], v[2:3], 0, s[54:55]
	s_mov_b32 m0, s62
	s_add_u32 s6, s26, 0x80080
	global_load_lds_dwordx4 v[2:3], off
	v_lshl_add_u64 v[0:1], v[0:1], 0, s[54:55]
	s_mov_b32 m0, s63
	s_addc_u32 s7, s27, 0
	global_load_lds_dwordx4 v[0:1], off
	s_add_i32 m0, s58, 0x1c000
	global_load_lds_dwordx4 v130, s[6:7]
	s_add_i32 m0, s58, 0x1e000
	v_lshlrev_b32_e32 v3, 2, v8
	global_load_lds_dwordx4 v134, s[6:7]
	v_lshrrev_b32_e32 v1, 1, v8
	v_and_b32_e32 v1, 24, v1
	v_and_b32_e32 v0, 15, v8
	v_lshlrev_b32_e32 v2, 1, v1
	v_or_b32_e32 v136, s15, v1
	v_mov_b32_e32 v1, 0x4f
	v_or_b32_e32 v137, s14, v0
	v_lshl_or_b32 v2, v0, 6, v2
	v_bitop3_b32 v0, s14, v1, v0 bitop3:0xc8
	v_subrev_u32_e32 v1, 64, v0
	v_cmp_lt_u32_e32 vcc, 64, v0
	v_and_b32_e32 v3, 32, v3
	s_waitcnt vmcnt(6)
	v_bitop3_b32 v4, v2, s5, v3 bitop3:0xde
	v_cndmask_b32_e32 v155, v0, v1, vcc
	v_mov_b32_e32 v0, 0x1000
	v_cndmask_b32_e32 v178, 0, v0, vcc
	v_mov_b32_e32 v0, 0x200
	v_cndmask_b32_e32 v0, 0, v0, vcc
	v_mov_b32_e32 v1, v179
	v_lshl_add_u64 v[140:141], s[10:11], 0, v[0:1]
	v_lshlrev_b32_e32 v0, 15, v12
	v_and_b32_e32 v0, 0xffff0000, v0
	v_lshl_add_u32 v0, v13, 12, v0
	v_and_b32_e32 v1, 1, v12
	v_lshl_or_b32 v0, v1, 6, v0
	v_lshl_add_u32 v144, v14, 1, v0
	v_lshlrev_b32_e32 v0, 15, v9
	v_and_b32_e32 v0, 0xffff0000, v0
	v_lshl_add_u32 v0, v10, 12, v0
	v_and_b32_e32 v1, 1, v9
	v_lshl_add_u64 v[138:139], s[12:13], 0, v[178:179]
	v_lshlrev_b32_e32 v178, 1, v136
	v_lshl_or_b32 v0, v1, 6, v0
	v_bitop3_b32 v154, v2, s16, v3 bitop3:0xde
	s_mov_b32 s66, 0
	v_lshl_add_u64 v[142:143], v[140:141], 0, v[178:179]
	v_mov_b32_e32 v145, v179
	v_lshl_add_u32 v146, v11, 1, v0
	v_mov_b32_e32 v147, v179
	v_add_u32_e32 v156, 0, v4
	s_barrier
	s_branch .LBB0_266

.LBB0_269:
	s_add_u32 s26, s24, 0xfff80080
	s_addc_u32 s27, s25, -1
	s_add_i32 s70, 0, 0x10000
	v_add_u32_e32 v148, s70, v154
	ds_read_b128 v[150:153], v148
	ds_read_b128 v[158:161], v148 offset:1024
	ds_read_b128 v[162:165], v148 offset:2048
	ds_read_b128 v[166:169], v148 offset:3072
	s_cmp_eq_u32 s69, 28
	s_cselect_b32 s29, s7, s27
	s_cselect_b32 s28, s6, s26
	s_cselect_b32 s27, s23, s17
	s_cselect_b32 s26, s22, s5
	s_add_i32 m0, s58, 0xc000
	ds_read_b128 v[170:173], v156
	ds_read_b128 v[174:177], v156 offset:1024
	ds_read_b128 v[180:183], v156 offset:2048
	ds_read_b128 v[184:187], v156 offset:3072
	ds_read_b128 v[188:191], v156 offset:4096
	ds_read_b128 v[192:195], v156 offset:5120
	ds_read_b128 v[196:199], v156 offset:6144
	ds_read_b128 v[224:227], v156 offset:7168
	global_load_lds_dwordx4 v146, s[24:25]
	s_add_i32 m0, s58, 0xe000
	s_nop 0
	global_load_lds_dwordx4 v144, s[24:25]
	s_waitcnt lgkmcnt(8)
	s_barrier
	s_waitcnt lgkmcnt(0)
	s_setprio 1
	s_waitcnt lgkmcnt(0)
	v_mfma_f32_16x16x32_bf16 v[124:127], v[150:153], v[170:173], v[124:127]
	v_mfma_f32_16x16x32_bf16 v[120:123], v[162:165], v[170:173], v[120:123]
	v_mfma_f32_16x16x32_bf16 v[108:111], v[150:153], v[180:183], v[108:111]
	v_mfma_f32_16x16x32_bf16 v[104:107], v[162:165], v[180:183], v[104:107]
	v_mfma_f32_16x16x32_bf16 v[92:95], v[150:153], v[188:191], v[92:95]
	v_mfma_f32_16x16x32_bf16 v[88:91], v[162:165], v[188:191], v[88:91]
	v_mfma_f32_16x16x32_bf16 v[76:79], v[150:153], v[196:199], v[76:79]
	v_mfma_f32_16x16x32_bf16 v[72:75], v[162:165], v[196:199], v[72:75]
	v_mfma_f32_16x16x32_bf16 v[124:127], v[158:161], v[174:177], v[124:127]
	v_mfma_f32_16x16x32_bf16 v[120:123], v[166:169], v[174:177], v[120:123]
	v_mfma_f32_16x16x32_bf16 v[108:111], v[158:161], v[184:187], v[108:111]
	v_mfma_f32_16x16x32_bf16 v[104:107], v[166:169], v[184:187], v[104:107]
	v_mfma_f32_16x16x32_bf16 v[92:95], v[158:161], v[192:195], v[92:95]
	v_mfma_f32_16x16x32_bf16 v[88:91], v[166:169], v[192:195], v[88:91]
	v_mfma_f32_16x16x32_bf16 v[76:79], v[158:161], v[224:227], v[76:79]
	v_mfma_f32_16x16x32_bf16 v[72:75], v[166:169], v[224:227], v[72:75]
	s_setprio 0
	s_barrier
	s_add_i32 s72, 0, 0x14000
	s_add_i32 s70, s70, s57
	v_add_u32_e32 v148, s72, v154
	v_lshl_add_u64 v[204:205], s[26:27], 0, v[130:131]
	s_mov_b32 m0, s70
	ds_read_b128 v[228:231], v148
	ds_read_b128 v[232:235], v148 offset:1024
	ds_read_b128 v[236:239], v148 offset:2048
	ds_read_b128 v[240:243], v148 offset:3072
	global_load_lds_dwordx4 v[204:205], off
	v_lshl_add_u64 v[206:207], s[26:27], 0, v[134:135]
	s_add_i32 m0, s70, 0x2000
	s_nop 0
	global_load_lds_dwordx4 v[206:207], off
	s_barrier
	s_waitcnt lgkmcnt(0)
	s_setprio 1
	s_waitcnt lgkmcnt(0)
	v_mfma_f32_16x16x32_bf16 v[116:119], v[228:231], v[170:173], v[116:119]
	v_mfma_f32_16x16x32_bf16 v[112:115], v[236:239], v[170:173], v[112:115]
	v_mfma_f32_16x16x32_bf16 v[100:103], v[228:231], v[180:183], v[100:103]
	v_mfma_f32_16x16x32_bf16 v[96:99], v[236:239], v[180:183], v[96:99]
	v_mfma_f32_16x16x32_bf16 v[84:87], v[228:231], v[188:191], v[84:87]
	v_mfma_f32_16x16x32_bf16 v[80:83], v[236:239], v[188:191], v[80:83]
	v_mfma_f32_16x16x32_bf16 v[68:71], v[228:231], v[196:199], v[68:71]
	v_mfma_f32_16x16x32_bf16 v[64:67], v[236:239], v[196:199], v[64:67]
	v_mfma_f32_16x16x32_bf16 v[116:119], v[232:235], v[174:177], v[116:119]
	v_mfma_f32_16x16x32_bf16 v[112:115], v[240:243], v[174:177], v[112:115]
	v_mfma_f32_16x16x32_bf16 v[100:103], v[232:235], v[184:187], v[100:103]
	v_mfma_f32_16x16x32_bf16 v[96:99], v[240:243], v[184:187], v[96:99]
	v_mfma_f32_16x16x32_bf16 v[84:87], v[232:235], v[192:195], v[84:87]
	v_mfma_f32_16x16x32_bf16 v[80:83], v[240:243], v[192:195], v[80:83]
	v_mfma_f32_16x16x32_bf16 v[68:71], v[232:235], v[224:227], v[68:71]
	v_mfma_f32_16x16x32_bf16 v[64:67], v[240:243], v[224:227], v[64:67]
	s_setprio 0
	s_mov_b32 m0, s58
	v_lshl_add_u64 v[212:213], s[28:29], 0, v[128:129]
	s_barrier
	ds_read_b128 v[170:173], v156 offset:16384
	ds_read_b128 v[174:177], v156 offset:17408
	ds_read_b128 v[180:183], v156 offset:18432
	ds_read_b128 v[184:187], v156 offset:19456
	ds_read_b128 v[188:191], v156 offset:20480
	ds_read_b128 v[192:195], v156 offset:21504
	ds_read_b128 v[196:199], v156 offset:22528
	ds_read_b128 v[224:227], v156 offset:23552
	global_load_lds_dwordx4 v[212:213], off
	v_lshl_add_u64 v[214:215], s[28:29], 0, v[132:133]
	s_mov_b32 m0, s59
	s_nop 0
	global_load_lds_dwordx4 v[214:215], off
	s_barrier
	s_waitcnt lgkmcnt(0)
	s_setprio 1
	s_waitcnt lgkmcnt(0)
	v_mfma_f32_16x16x32_bf16 v[60:63], v[150:153], v[170:173], v[60:63]
	v_mfma_f32_16x16x32_bf16 v[56:59], v[162:165], v[170:173], v[56:59]
	v_mfma_f32_16x16x32_bf16 v[44:47], v[150:153], v[180:183], v[44:47]
	v_mfma_f32_16x16x32_bf16 v[40:43], v[162:165], v[180:183], v[40:43]
	v_mfma_f32_16x16x32_bf16 v[28:31], v[150:153], v[188:191], v[28:31]
	v_mfma_f32_16x16x32_bf16 v[24:27], v[162:165], v[188:191], v[24:27]
	v_mfma_f32_16x16x32_bf16 v[12:15], v[150:153], v[196:199], v[12:15]
	v_mfma_f32_16x16x32_bf16 v[8:11], v[162:165], v[196:199], v[8:11]
	v_mfma_f32_16x16x32_bf16 v[60:63], v[158:161], v[174:177], v[60:63]
	v_mfma_f32_16x16x32_bf16 v[56:59], v[166:169], v[174:177], v[56:59]
	v_mfma_f32_16x16x32_bf16 v[44:47], v[158:161], v[184:187], v[44:47]
	v_mfma_f32_16x16x32_bf16 v[40:43], v[166:169], v[184:187], v[40:43]
	v_mfma_f32_16x16x32_bf16 v[28:31], v[158:161], v[192:195], v[28:31]
	v_mfma_f32_16x16x32_bf16 v[24:27], v[166:169], v[192:195], v[24:27]
	v_mfma_f32_16x16x32_bf16 v[12:15], v[158:161], v[224:227], v[12:15]
	v_mfma_f32_16x16x32_bf16 v[8:11], v[166:169], v[224:227], v[8:11]
	s_setprio 0
	s_barrier
	s_add_u32 s70, s26, 0x80000
	s_addc_u32 s71, s27, 0
	s_add_i32 s72, s72, s57
	s_mov_b32 m0, s72
	s_nop 0
	global_load_lds_dwordx4 v130, s[70:71]
	s_add_i32 m0, s72, 0x2000
	s_nop 0
	global_load_lds_dwordx4 v134, s[70:71]
	s_waitcnt vmcnt(6)
	s_barrier
	s_setprio 1
	v_mfma_f32_16x16x32_bf16 v[52:55], v[228:231], v[170:173], v[52:55]
	v_mfma_f32_16x16x32_bf16 v[48:51], v[236:239], v[170:173], v[48:51]
	v_mfma_f32_16x16x32_bf16 v[36:39], v[228:231], v[180:183], v[36:39]
	v_mfma_f32_16x16x32_bf16 v[32:35], v[236:239], v[180:183], v[32:35]
	v_mfma_f32_16x16x32_bf16 v[20:23], v[228:231], v[188:191], v[20:23]
	v_mfma_f32_16x16x32_bf16 v[16:19], v[236:239], v[188:191], v[16:19]
	v_mfma_f32_16x16x32_bf16 v[4:7], v[228:231], v[196:199], v[4:7]
	v_mfma_f32_16x16x32_bf16 v[0:3], v[236:239], v[196:199], v[0:3]
	v_mfma_f32_16x16x32_bf16 v[52:55], v[232:235], v[174:177], v[52:55]
	v_mfma_f32_16x16x32_bf16 v[48:51], v[240:243], v[174:177], v[48:51]
	v_mfma_f32_16x16x32_bf16 v[36:39], v[232:235], v[184:187], v[36:39]
	v_mfma_f32_16x16x32_bf16 v[32:35], v[240:243], v[184:187], v[32:35]
	v_mfma_f32_16x16x32_bf16 v[20:23], v[232:235], v[192:195], v[20:23]
	v_mfma_f32_16x16x32_bf16 v[16:19], v[240:243], v[192:195], v[16:19]
	v_mfma_f32_16x16x32_bf16 v[4:7], v[232:235], v[224:227], v[4:7]
	v_mfma_f32_16x16x32_bf16 v[0:3], v[240:243], v[224:227], v[0:3]
	s_setprio 0
	s_add_i32 s70, 0, 0x18000
	v_add_u32_e32 v148, s70, v154
	s_barrier
	ds_read_b128 v[150:153], v148
	ds_read_b128 v[158:161], v148 offset:1024
	ds_read_b128 v[162:165], v148 offset:2048
	ds_read_b128 v[166:169], v148 offset:3072
	s_add_u32 s28, s28, 0x80000
	s_addc_u32 s29, s29, 0
	s_mov_b32 m0, s60
	ds_read_b128 v[170:173], v156 offset:32768
	ds_read_b128 v[174:177], v156 offset:33792
	ds_read_b128 v[180:183], v156 offset:34816
	ds_read_b128 v[184:187], v156 offset:35840
	ds_read_b128 v[188:191], v156 offset:36864
	ds_read_b128 v[192:195], v156 offset:37888
	ds_read_b128 v[196:199], v156 offset:38912
	ds_read_b128 v[224:227], v156 offset:39936
	global_load_lds_dwordx4 v128, s[28:29]
	s_mov_b32 m0, s61
	s_nop 0
	global_load_lds_dwordx4 v132, s[28:29]
	s_waitcnt lgkmcnt(8)
	s_barrier
	s_waitcnt lgkmcnt(0)
	s_setprio 1
	s_waitcnt lgkmcnt(0)
	v_mfma_f32_16x16x32_bf16 v[124:127], v[150:153], v[170:173], v[124:127]
	v_mfma_f32_16x16x32_bf16 v[120:123], v[162:165], v[170:173], v[120:123]
	v_mfma_f32_16x16x32_bf16 v[108:111], v[150:153], v[180:183], v[108:111]
	v_mfma_f32_16x16x32_bf16 v[104:107], v[162:165], v[180:183], v[104:107]
	v_mfma_f32_16x16x32_bf16 v[92:95], v[150:153], v[188:191], v[92:95]
	v_mfma_f32_16x16x32_bf16 v[88:91], v[162:165], v[188:191], v[88:91]
	v_mfma_f32_16x16x32_bf16 v[76:79], v[150:153], v[196:199], v[76:79]
	v_mfma_f32_16x16x32_bf16 v[72:75], v[162:165], v[196:199], v[72:75]
	v_mfma_f32_16x16x32_bf16 v[124:127], v[158:161], v[174:177], v[124:127]
	v_mfma_f32_16x16x32_bf16 v[120:123], v[166:169], v[174:177], v[120:123]
	v_mfma_f32_16x16x32_bf16 v[108:111], v[158:161], v[184:187], v[108:111]
	v_mfma_f32_16x16x32_bf16 v[104:107], v[166:169], v[184:187], v[104:107]
	v_mfma_f32_16x16x32_bf16 v[92:95], v[158:161], v[192:195], v[92:95]
	v_mfma_f32_16x16x32_bf16 v[88:91], v[166:169], v[192:195], v[88:91]
	v_mfma_f32_16x16x32_bf16 v[76:79], v[158:161], v[224:227], v[76:79]
	v_mfma_f32_16x16x32_bf16 v[72:75], v[166:169], v[224:227], v[72:75]
	s_setprio 0
	s_barrier
	s_add_i32 s28, 0, 0x1c000
	s_add_i32 s29, s70, s57
	v_add_u32_e32 v148, s28, v154
	v_lshl_add_u64 v[204:205], v[204:205], 0, s[54:55]
	s_mov_b32 m0, s29
	ds_read_b128 v[228:231], v148
	ds_read_b128 v[232:235], v148 offset:1024
	ds_read_b128 v[236:239], v148 offset:2048
	ds_read_b128 v[240:243], v148 offset:3072
	global_load_lds_dwordx4 v[204:205], off
	v_lshl_add_u64 v[204:205], v[206:207], 0, s[54:55]
	s_add_i32 m0, s29, 0x2000
	s_nop 0
	global_load_lds_dwordx4 v[204:205], off
	s_barrier
	s_waitcnt lgkmcnt(0)
	s_setprio 1
	s_waitcnt lgkmcnt(0)
	v_mfma_f32_16x16x32_bf16 v[116:119], v[228:231], v[170:173], v[116:119]
	v_mfma_f32_16x16x32_bf16 v[112:115], v[236:239], v[170:173], v[112:115]
	v_mfma_f32_16x16x32_bf16 v[100:103], v[228:231], v[180:183], v[100:103]
	v_mfma_f32_16x16x32_bf16 v[96:99], v[236:239], v[180:183], v[96:99]
	v_mfma_f32_16x16x32_bf16 v[84:87], v[228:231], v[188:191], v[84:87]
	v_mfma_f32_16x16x32_bf16 v[80:83], v[236:239], v[188:191], v[80:83]
	v_mfma_f32_16x16x32_bf16 v[68:71], v[228:231], v[196:199], v[68:71]
	v_mfma_f32_16x16x32_bf16 v[64:67], v[236:239], v[196:199], v[64:67]
	v_mfma_f32_16x16x32_bf16 v[116:119], v[232:235], v[174:177], v[116:119]
	v_mfma_f32_16x16x32_bf16 v[112:115], v[240:243], v[174:177], v[112:115]
	v_mfma_f32_16x16x32_bf16 v[100:103], v[232:235], v[184:187], v[100:103]
	v_mfma_f32_16x16x32_bf16 v[96:99], v[240:243], v[184:187], v[96:99]
	v_mfma_f32_16x16x32_bf16 v[84:87], v[232:235], v[192:195], v[84:87]
	v_mfma_f32_16x16x32_bf16 v[80:83], v[240:243], v[192:195], v[80:83]
	v_mfma_f32_16x16x32_bf16 v[68:71], v[232:235], v[224:227], v[68:71]
	v_mfma_f32_16x16x32_bf16 v[64:67], v[240:243], v[224:227], v[64:67]
	s_setprio 0
	s_mov_b32 m0, s62
	v_lshl_add_u64 v[204:205], v[212:213], 0, s[54:55]
	s_barrier
	ds_read_b128 v[170:173], v156 offset:49152
	ds_read_b128 v[174:177], v156 offset:50176
	ds_read_b128 v[180:183], v156 offset:51200
	ds_read_b128 v[184:187], v156 offset:52224
	ds_read_b128 v[188:191], v156 offset:53248
	ds_read_b128 v[192:195], v156 offset:54272
	ds_read_b128 v[196:199], v156 offset:55296
	ds_read_b128 v[224:227], v156 offset:56320
	global_load_lds_dwordx4 v[204:205], off
	v_lshl_add_u64 v[204:205], v[214:215], 0, s[54:55]
	s_mov_b32 m0, s63
	s_nop 0
	global_load_lds_dwordx4 v[204:205], off
	s_barrier
	s_waitcnt lgkmcnt(0)
	s_setprio 1
	s_waitcnt lgkmcnt(0)
	v_mfma_f32_16x16x32_bf16 v[60:63], v[150:153], v[170:173], v[60:63]
	v_mfma_f32_16x16x32_bf16 v[56:59], v[162:165], v[170:173], v[56:59]
	v_mfma_f32_16x16x32_bf16 v[44:47], v[150:153], v[180:183], v[44:47]
	v_mfma_f32_16x16x32_bf16 v[40:43], v[162:165], v[180:183], v[40:43]
	v_mfma_f32_16x16x32_bf16 v[28:31], v[150:153], v[188:191], v[28:31]
	v_mfma_f32_16x16x32_bf16 v[24:27], v[162:165], v[188:191], v[24:27]
	v_mfma_f32_16x16x32_bf16 v[12:15], v[150:153], v[196:199], v[12:15]
	v_mfma_f32_16x16x32_bf16 v[8:11], v[162:165], v[196:199], v[8:11]
	v_mfma_f32_16x16x32_bf16 v[60:63], v[158:161], v[174:177], v[60:63]
	v_mfma_f32_16x16x32_bf16 v[56:59], v[166:169], v[174:177], v[56:59]
	v_mfma_f32_16x16x32_bf16 v[44:47], v[158:161], v[184:187], v[44:47]
	v_mfma_f32_16x16x32_bf16 v[40:43], v[166:169], v[184:187], v[40:43]
	v_mfma_f32_16x16x32_bf16 v[28:31], v[158:161], v[192:195], v[28:31]
	v_mfma_f32_16x16x32_bf16 v[24:27], v[166:169], v[192:195], v[24:27]
	v_mfma_f32_16x16x32_bf16 v[12:15], v[158:161], v[224:227], v[12:15]
	v_mfma_f32_16x16x32_bf16 v[8:11], v[166:169], v[224:227], v[8:11]
	s_setprio 0
	s_barrier
	s_add_u32 s26, s26, 0x80080
	s_addc_u32 s27, s27, 0
	s_add_i32 s28, s28, s57
	s_mov_b32 m0, s28
	s_nop 0
	global_load_lds_dwordx4 v130, s[26:27]
	s_add_i32 m0, s28, 0x2000
	s_nop 0
	global_load_lds_dwordx4 v134, s[26:27]
	s_waitcnt vmcnt(6)
	s_barrier
	s_setprio 1
	v_mfma_f32_16x16x32_bf16 v[52:55], v[228:231], v[170:173], v[52:55]
	v_mfma_f32_16x16x32_bf16 v[48:51], v[236:239], v[170:173], v[48:51]
	v_mfma_f32_16x16x32_bf16 v[36:39], v[228:231], v[180:183], v[36:39]
	v_mfma_f32_16x16x32_bf16 v[32:35], v[236:239], v[180:183], v[32:35]
	v_mfma_f32_16x16x32_bf16 v[20:23], v[228:231], v[188:191], v[20:23]
	v_mfma_f32_16x16x32_bf16 v[16:19], v[236:239], v[188:191], v[16:19]
	v_mfma_f32_16x16x32_bf16 v[4:7], v[228:231], v[196:199], v[4:7]
	v_mfma_f32_16x16x32_bf16 v[0:3], v[236:239], v[196:199], v[0:3]
	v_mfma_f32_16x16x32_bf16 v[52:55], v[232:235], v[174:177], v[52:55]
	v_mfma_f32_16x16x32_bf16 v[48:51], v[240:243], v[174:177], v[48:51]
	v_mfma_f32_16x16x32_bf16 v[36:39], v[232:235], v[184:187], v[36:39]
	v_mfma_f32_16x16x32_bf16 v[32:35], v[240:243], v[184:187], v[32:35]
	v_mfma_f32_16x16x32_bf16 v[20:23], v[232:235], v[192:195], v[20:23]
	v_mfma_f32_16x16x32_bf16 v[16:19], v[240:243], v[192:195], v[16:19]
	v_mfma_f32_16x16x32_bf16 v[4:7], v[232:235], v[224:227], v[4:7]
	v_mfma_f32_16x16x32_bf16 v[0:3], v[240:243], v[224:227], v[0:3]
	s_setprio 0
	s_add_i32 s69, s69, 2
	s_add_u32 s5, s5, 0x100
	s_addc_u32 s17, s17, 0
	s_add_u32 s24, s24, 0x100
	s_addc_u32 s25, s25, 0
	s_cmp_gt_u32 s69, 29
	s_barrier
	s_cbranch_scc0 .LBB0_269
	s_lshl_b32 s5, s68, 8
	v_lshl_add_u32 v158, s4, 8, v137
	v_or_b32_e32 v148, s5, v136
	s_addk_i32 s5, 0xf000
	s_lshr_b32 s4, s5, 2
	v_and_b32_e32 v159, 0xffffff80, v158
	s_and_b32 s22, s4, 0x3ffffe00
	v_add_u32_e32 v160, v159, v155
	v_add_u32_e32 v150, s22, v160
	s_lshl_b32 s17, s68, 9
	v_ashrrev_i32_e32 v151, 31, v150
	v_lshlrev_b64 v[152:153], 13, v[150:151]
	v_add_u32_e32 v150, s17, v160
	v_ashrrev_i32_e32 v151, 31, v150
	v_cmp_ne_u32_e64 s[6:7], 0, v149
	s_movk_i32 s4, 0xfff
	v_lshlrev_b64 v[150:151], 10, v[150:151]
	s_and_b64 vcc, exec, s[6:7]
	v_cmp_lt_i32_e64 s[4:5], s4, v148
	v_cvt_pk_bf16_f32 v124, v124, v125
	v_cvt_pk_bf16_f32 v125, v126, v127
	v_cvt_pk_bf16_f32 v126, v120, v121
	v_cvt_pk_bf16_f32 v127, v122, v123
	s_cbranch_vccz .LBB0_290
	s_and_saveexec_b64 s[24:25], s[4:5]
	s_xor_b64 s[4:5], exec, s[24:25]
	v_and_b32_e32 v122, 0x778, v148
	v_lshl_add_u64 v[120:121], v[138:139], 0, v[152:153]
	v_lshlrev_b32_e32 v178, 1, v122
	v_lshl_add_u64 v[122:123], v[120:121], 0, v[178:179]
	s_andn2_saveexec_b64 s[4:5], s[4:5]
	v_lshl_add_u64 v[122:123], v[142:143], 0, v[150:151]
	s_or_b64 exec, exec, s[4:5]
	s_movk_i32 s4, 0x1a00
	v_mad_i64_i32 v[120:121], s[4:5], v158, s4, 0
	s_cbranch_execnz .LBB0_277

.LBB0_934:
	v_lshl_add_u64 v[8:9], s[8:9], 0, v[178:179]
	v_mov_b32_e32 v129, v179
	v_and_b32_e32 v7, 15, v3
	v_lshrrev_b32_e32 v16, 1, v3
	v_lshl_add_u64 v[10:11], s[8:9], 0, v[128:129]
	v_mov_b32_e32 v133, v179
	v_or_b32_e32 v138, s20, v7
	v_and_b32_e32 v139, 24, v16
	s_add_i32 m0, s22, 0x18000
	v_lshl_add_u64 v[8:9], v[8:9], 0, s[54:55]
	v_lshl_add_u64 v[12:13], s[6:7], 0, v[132:133]
	v_mov_b32_e32 v131, v179
	v_lshlrev_b32_e32 v16, 6, v138
	v_lshlrev_b32_e32 v17, 1, v139
	s_movk_i32 s10, 0x3c0
	s_waitcnt vmcnt(4)
	s_barrier
	global_load_lds_dwordx4 v[8:9], off
	v_lshl_add_u64 v[8:9], v[10:11], 0, s[54:55]
	s_add_i32 m0, s22, 0x1a000
	s_add_i32 s26, s22, 0x8000
	s_add_i32 s27, s22, 0xa000
	v_lshl_add_u64 v[14:15], s[6:7], 0, v[130:131]
	v_and_or_b32 v16, v16, s10, v17
	global_load_lds_dwordx4 v[8:9], off
	v_lshl_add_u64 v[8:9], v[12:13], 0, s[54:55]
	s_mov_b32 m0, s26
	s_add_u32 s10, s8, 0x100080
	global_load_lds_dwordx4 v[8:9], off
	v_lshl_add_u64 v[8:9], v[14:15], 0, s[54:55]
	s_mov_b32 m0, s27
	s_addc_u32 s11, s9, 0
	global_load_lds_dwordx4 v[8:9], off
	s_add_i32 m0, s22, 0x1c000
	global_load_lds_dwordx4 v178, s[10:11]
	s_add_i32 m0, s22, 0x1e000
	v_lshlrev_b32_e32 v3, 2, v3
	global_load_lds_dwordx4 v128, s[10:11]
	v_lshl_or_b32 v7, v7, 6, v17
	v_and_b32_e32 v3, 32, v3
	v_bitop3_b32 v140, v7, s19, v3 bitop3:0xde
	v_lshlrev_b32_e32 v3, 16, v0
	v_and_b32_e32 v3, 0xfffe0000, v3
	v_readlane_b32 s10, v253, 49
	v_lshl_add_u32 v1, v1, 13, v3
	v_and_b32_e32 v0, 1, v0
	s_add_u32 s10, s88, s10
	v_lshl_or_b32 v0, v0, 6, v1
	s_addc_u32 s11, s89, 0
	v_lshl_add_u32 v0, v2, 1, v0
	v_mov_b32_e32 v1, v179
	v_lshl_add_u64 v[134:135], s[10:11], 0, v[0:1]
	v_lshlrev_b32_e32 v0, 16, v4
	v_and_b32_e32 v0, 0xfffe0000, v0
	v_lshl_add_u32 v0, v5, 13, v0
	v_and_b32_e32 v1, 1, v4
	v_lshlrev_b32_e32 v18, 2, v138
	v_lshl_or_b32 v0, v1, 6, v0
	v_and_b32_e32 v18, 32, v18
	s_waitcnt vmcnt(6)
	v_lshl_add_u32 v0, v6, 1, v0
	v_mov_b32_e32 v1, v179
	v_bitop3_b32 v16, v16, s18, v18 bitop3:0xde
	v_lshl_add_u64 v[136:137], s[10:11], 0, v[0:1]
	v_mov_b32_e32 v0, 0
	s_mov_b32 s28, -2
	s_mov_b64 s[10:11], 0xb400080
	v_add_u32_e32 v141, 0, v16
	v_mov_b32_e32 v1, v0
	v_mov_b32_e32 v2, v0
	v_mov_b32_e32 v3, v0
	v_mov_b32_e32 v4, v0
	v_mov_b32_e32 v5, v0
	v_mov_b32_e32 v6, v0
	v_mov_b32_e32 v7, v0
	v_mov_b32_e32 v8, v0
	v_mov_b32_e32 v9, v0
	v_mov_b32_e32 v10, v0
	v_mov_b32_e32 v11, v0
	v_mov_b32_e32 v16, v0
	v_mov_b32_e32 v17, v0
	v_mov_b32_e32 v18, v0
	v_mov_b32_e32 v19, v0
	v_mov_b32_e32 v24, v0
	v_mov_b32_e32 v25, v0
	v_mov_b32_e32 v26, v0
	v_mov_b32_e32 v27, v0
	v_mov_b32_e32 v32, v0
	v_mov_b32_e32 v33, v0
	v_mov_b32_e32 v34, v0
	v_mov_b32_e32 v35, v0
	v_mov_b32_e32 v40, v0
	v_mov_b32_e32 v41, v0
	v_mov_b32_e32 v42, v0
	v_mov_b32_e32 v43, v0
	v_mov_b32_e32 v48, v0
	v_mov_b32_e32 v49, v0
	v_mov_b32_e32 v50, v0
	v_mov_b32_e32 v51, v0
	v_mov_b32_e32 v12, v0
	v_mov_b32_e32 v13, v0
	v_mov_b32_e32 v14, v0
	v_mov_b32_e32 v15, v0
	v_mov_b32_e32 v20, v0
	v_mov_b32_e32 v21, v0
	v_mov_b32_e32 v22, v0
	v_mov_b32_e32 v23, v0
	v_mov_b32_e32 v28, v0
	v_mov_b32_e32 v29, v0
	v_mov_b32_e32 v30, v0
	v_mov_b32_e32 v31, v0
	v_mov_b32_e32 v36, v0
	v_mov_b32_e32 v37, v0
	v_mov_b32_e32 v38, v0
	v_mov_b32_e32 v39, v0
	v_mov_b32_e32 v44, v0
	v_mov_b32_e32 v45, v0
	v_mov_b32_e32 v46, v0
	v_mov_b32_e32 v47, v0
	v_mov_b32_e32 v52, v0
	v_mov_b32_e32 v53, v0
	v_mov_b32_e32 v54, v0
	v_mov_b32_e32 v55, v0
	v_mov_b32_e32 v56, v0
	v_mov_b32_e32 v57, v0
	v_mov_b32_e32 v58, v0
	v_mov_b32_e32 v59, v0
	v_mov_b32_e32 v60, v0
	v_mov_b32_e32 v61, v0
	v_mov_b32_e32 v62, v0
	v_mov_b32_e32 v63, v0
	v_mov_b32_e32 v64, v0
	v_mov_b32_e32 v65, v0
	v_mov_b32_e32 v66, v0
	v_mov_b32_e32 v67, v0
	v_mov_b32_e32 v68, v0
	v_mov_b32_e32 v69, v0
	v_mov_b32_e32 v70, v0
	v_mov_b32_e32 v71, v0
	v_mov_b32_e32 v72, v0
	v_mov_b32_e32 v73, v0
	v_mov_b32_e32 v74, v0
	v_mov_b32_e32 v75, v0
	v_mov_b32_e32 v80, v0
	v_mov_b32_e32 v81, v0
	v_mov_b32_e32 v82, v0
	v_mov_b32_e32 v83, v0
	v_mov_b32_e32 v88, v0
	v_mov_b32_e32 v89, v0
	v_mov_b32_e32 v90, v0
	v_mov_b32_e32 v91, v0
	v_mov_b32_e32 v96, v0
	v_mov_b32_e32 v97, v0
	v_mov_b32_e32 v98, v0
	v_mov_b32_e32 v99, v0
	v_mov_b32_e32 v104, v0
	v_mov_b32_e32 v105, v0
	v_mov_b32_e32 v106, v0
	v_mov_b32_e32 v107, v0
	v_mov_b32_e32 v112, v0
	v_mov_b32_e32 v113, v0
	v_mov_b32_e32 v114, v0
	v_mov_b32_e32 v115, v0
	v_mov_b32_e32 v76, v0
	v_mov_b32_e32 v77, v0
	v_mov_b32_e32 v78, v0
	v_mov_b32_e32 v79, v0
	v_mov_b32_e32 v84, v0
	v_mov_b32_e32 v85, v0
	v_mov_b32_e32 v86, v0
	v_mov_b32_e32 v87, v0
	v_mov_b32_e32 v92, v0
	v_mov_b32_e32 v93, v0
	v_mov_b32_e32 v94, v0
	v_mov_b32_e32 v95, v0
	v_mov_b32_e32 v100, v0
	v_mov_b32_e32 v101, v0
	v_mov_b32_e32 v102, v0
	v_mov_b32_e32 v103, v0
	v_mov_b32_e32 v108, v0
	v_mov_b32_e32 v109, v0
	v_mov_b32_e32 v110, v0
	v_mov_b32_e32 v111, v0
	v_mov_b32_e32 v116, v0
	v_mov_b32_e32 v117, v0
	v_mov_b32_e32 v118, v0
	v_mov_b32_e32 v119, v0
	v_mov_b32_e32 v120, v0
	v_mov_b32_e32 v121, v0
	v_mov_b32_e32 v122, v0
	v_mov_b32_e32 v123, v0
	v_mov_b32_e32 v124, v0
	v_mov_b32_e32 v125, v0
	v_mov_b32_e32 v126, v0
	v_mov_b32_e32 v127, v0
	s_barrier
.LBB0_935:
	s_add_u32 s12, s10, 0xf4c00080
	s_addc_u32 s13, s11, -1
	s_cmp_lg_u32 s28, 60
	s_cselect_b32 s12, s12, 0
	s_cselect_b32 s13, s13, 0
	s_add_u32 s14, s6, s12
	s_addc_u32 s15, s7, s13
	s_add_i32 s29, 0, 0x10000
	v_add_u32_e32 v150, s29, v140
	ds_read_b128 v[142:145], v150
	ds_read_b128 v[146:149], v150 offset:1024
	ds_read_b128 v[154:157], v150 offset:2048
	ds_read_b128 v[158:161], v150 offset:3072
	s_add_u32 s12, s8, s12
	s_addc_u32 s13, s9, s13
	v_lshl_add_u64 v[150:151], v[136:137], 0, s[10:11]
	s_add_i32 m0, s22, 0xc000
	ds_read_b128 v[162:165], v141
	ds_read_b128 v[166:169], v141 offset:1024
	ds_read_b128 v[170:173], v141 offset:2048
	ds_read_b128 v[174:177], v141 offset:3072
	ds_read_b128 v[180:183], v141 offset:4096
	ds_read_b128 v[184:187], v141 offset:5120
	ds_read_b128 v[188:191], v141 offset:6144
	ds_read_b128 v[192:195], v141 offset:7168
	global_load_lds_dwordx4 v[150:151], off
	v_lshl_add_u64 v[150:151], v[134:135], 0, s[10:11]
	s_add_i32 m0, s22, 0xe000
	s_nop 0
	global_load_lds_dwordx4 v[150:151], off
	s_waitcnt lgkmcnt(8)
	s_barrier
	s_waitcnt lgkmcnt(0)
	s_setprio 1
	s_waitcnt lgkmcnt(0)
	v_mfma_f32_16x16x32_bf16 v[124:127], v[142:145], v[162:165], v[124:127]
	v_mfma_f32_16x16x32_bf16 v[120:123], v[154:157], v[162:165], v[120:123]
	v_mfma_f32_16x16x32_bf16 v[116:119], v[142:145], v[170:173], v[116:119]
	v_mfma_f32_16x16x32_bf16 v[108:111], v[154:157], v[170:173], v[108:111]
	v_mfma_f32_16x16x32_bf16 v[100:103], v[142:145], v[180:183], v[100:103]
	v_mfma_f32_16x16x32_bf16 v[92:95], v[154:157], v[180:183], v[92:95]
	v_mfma_f32_16x16x32_bf16 v[84:87], v[142:145], v[188:191], v[84:87]
	v_mfma_f32_16x16x32_bf16 v[76:79], v[154:157], v[188:191], v[76:79]
	v_mfma_f32_16x16x32_bf16 v[124:127], v[146:149], v[166:169], v[124:127]
	v_mfma_f32_16x16x32_bf16 v[120:123], v[158:161], v[166:169], v[120:123]
	v_mfma_f32_16x16x32_bf16 v[116:119], v[146:149], v[174:177], v[116:119]
	v_mfma_f32_16x16x32_bf16 v[108:111], v[158:161], v[174:177], v[108:111]
	v_mfma_f32_16x16x32_bf16 v[100:103], v[146:149], v[184:187], v[100:103]
	v_mfma_f32_16x16x32_bf16 v[92:95], v[158:161], v[184:187], v[92:95]
	v_mfma_f32_16x16x32_bf16 v[84:87], v[146:149], v[192:195], v[84:87]
	v_mfma_f32_16x16x32_bf16 v[76:79], v[158:161], v[192:195], v[76:79]
	s_setprio 0
	s_barrier
	s_add_i32 s35, 0, 0x14000
	v_add_u32_e32 v150, s35, v140
	s_add_i32 s29, s29, s16
	ds_read_b128 v[196:199], v150
	ds_read_b128 v[224:227], v150 offset:1024
	ds_read_b128 v[228:231], v150 offset:2048
	ds_read_b128 v[232:235], v150 offset:3072
	v_lshl_add_u64 v[150:151], s[12:13], 0, v[178:179]
	s_mov_b32 m0, s29
	v_lshl_add_u64 v[204:205], s[12:13], 0, v[128:129]
	global_load_lds_dwordx4 v[150:151], off
	s_add_i32 m0, s29, 0x2000
	s_nop 0
	global_load_lds_dwordx4 v[204:205], off
	s_barrier
	s_waitcnt lgkmcnt(0)
	s_setprio 1
	s_waitcnt lgkmcnt(0)
	v_mfma_f32_16x16x32_bf16 v[112:115], v[196:199], v[162:165], v[112:115]
	v_mfma_f32_16x16x32_bf16 v[104:107], v[228:231], v[162:165], v[104:107]
	v_mfma_f32_16x16x32_bf16 v[96:99], v[196:199], v[170:173], v[96:99]
	v_mfma_f32_16x16x32_bf16 v[88:91], v[228:231], v[170:173], v[88:91]
	v_mfma_f32_16x16x32_bf16 v[80:83], v[196:199], v[180:183], v[80:83]
	v_mfma_f32_16x16x32_bf16 v[72:75], v[228:231], v[180:183], v[72:75]
	v_mfma_f32_16x16x32_bf16 v[68:71], v[196:199], v[188:191], v[68:71]
	v_mfma_f32_16x16x32_bf16 v[64:67], v[228:231], v[188:191], v[64:67]
	v_mfma_f32_16x16x32_bf16 v[112:115], v[224:227], v[166:169], v[112:115]
	v_mfma_f32_16x16x32_bf16 v[104:107], v[232:235], v[166:169], v[104:107]
	v_mfma_f32_16x16x32_bf16 v[96:99], v[224:227], v[174:177], v[96:99]
	v_mfma_f32_16x16x32_bf16 v[88:91], v[232:235], v[174:177], v[88:91]
	v_mfma_f32_16x16x32_bf16 v[80:83], v[224:227], v[184:187], v[80:83]
	v_mfma_f32_16x16x32_bf16 v[72:75], v[232:235], v[184:187], v[72:75]
	v_mfma_f32_16x16x32_bf16 v[68:71], v[224:227], v[192:195], v[68:71]
	v_mfma_f32_16x16x32_bf16 v[64:67], v[232:235], v[192:195], v[64:67]
	s_setprio 0
	s_mov_b32 m0, s22
	v_lshl_add_u64 v[206:207], s[14:15], 0, v[132:133]
	s_barrier
	ds_read_b128 v[162:165], v141 offset:16384
	ds_read_b128 v[166:169], v141 offset:17408
	ds_read_b128 v[170:173], v141 offset:18432
	ds_read_b128 v[174:177], v141 offset:19456
	ds_read_b128 v[180:183], v141 offset:20480
	ds_read_b128 v[184:187], v141 offset:21504
	ds_read_b128 v[188:191], v141 offset:22528
	ds_read_b128 v[192:195], v141 offset:23552
	global_load_lds_dwordx4 v[206:207], off
	v_lshl_add_u64 v[212:213], s[14:15], 0, v[130:131]
	s_mov_b32 m0, s23
	s_nop 0
	global_load_lds_dwordx4 v[212:213], off
	s_barrier
	s_waitcnt lgkmcnt(0)
	s_setprio 1
	s_waitcnt lgkmcnt(0)
	v_mfma_f32_16x16x32_bf16 v[60:63], v[142:145], v[162:165], v[60:63]
	v_mfma_f32_16x16x32_bf16 v[56:59], v[154:157], v[162:165], v[56:59]
	v_mfma_f32_16x16x32_bf16 v[52:55], v[142:145], v[170:173], v[52:55]
	v_mfma_f32_16x16x32_bf16 v[44:47], v[154:157], v[170:173], v[44:47]
	v_mfma_f32_16x16x32_bf16 v[36:39], v[142:145], v[180:183], v[36:39]
	v_mfma_f32_16x16x32_bf16 v[28:31], v[154:157], v[180:183], v[28:31]
	v_mfma_f32_16x16x32_bf16 v[20:23], v[142:145], v[188:191], v[20:23]
	v_mfma_f32_16x16x32_bf16 v[12:15], v[154:157], v[188:191], v[12:15]
	v_mfma_f32_16x16x32_bf16 v[60:63], v[146:149], v[166:169], v[60:63]
	v_mfma_f32_16x16x32_bf16 v[56:59], v[158:161], v[166:169], v[56:59]
	v_mfma_f32_16x16x32_bf16 v[52:55], v[146:149], v[174:177], v[52:55]
	v_mfma_f32_16x16x32_bf16 v[44:47], v[158:161], v[174:177], v[44:47]
	v_mfma_f32_16x16x32_bf16 v[36:39], v[146:149], v[184:187], v[36:39]
	v_mfma_f32_16x16x32_bf16 v[28:31], v[158:161], v[184:187], v[28:31]
	v_mfma_f32_16x16x32_bf16 v[20:23], v[146:149], v[192:195], v[20:23]
	v_mfma_f32_16x16x32_bf16 v[12:15], v[158:161], v[192:195], v[12:15]
	s_setprio 0
	s_barrier
	s_add_u32 s30, s12, 0x100000
	s_addc_u32 s31, s13, 0
	s_add_i32 s29, s35, s16
	s_mov_b32 m0, s29
	s_nop 0
	global_load_lds_dwordx4 v178, s[30:31]
	s_add_i32 m0, s29, 0x2000
	s_nop 0
	global_load_lds_dwordx4 v128, s[30:31]
	s_waitcnt vmcnt(6)
	s_barrier
	s_setprio 1
	v_mfma_f32_16x16x32_bf16 v[48:51], v[196:199], v[162:165], v[48:51]
	v_mfma_f32_16x16x32_bf16 v[40:43], v[228:231], v[162:165], v[40:43]
	v_mfma_f32_16x16x32_bf16 v[32:35], v[196:199], v[170:173], v[32:35]
	v_mfma_f32_16x16x32_bf16 v[24:27], v[228:231], v[170:173], v[24:27]
	v_mfma_f32_16x16x32_bf16 v[16:19], v[196:199], v[180:183], v[16:19]
	v_mfma_f32_16x16x32_bf16 v[8:11], v[228:231], v[180:183], v[8:11]
	v_mfma_f32_16x16x32_bf16 v[4:7], v[196:199], v[188:191], v[4:7]
	v_mfma_f32_16x16x32_bf16 v[0:3], v[228:231], v[188:191], v[0:3]
	v_mfma_f32_16x16x32_bf16 v[48:51], v[224:227], v[166:169], v[48:51]
	v_mfma_f32_16x16x32_bf16 v[40:43], v[232:235], v[166:169], v[40:43]
	v_mfma_f32_16x16x32_bf16 v[32:35], v[224:227], v[174:177], v[32:35]
	v_mfma_f32_16x16x32_bf16 v[24:27], v[232:235], v[174:177], v[24:27]
	v_mfma_f32_16x16x32_bf16 v[16:19], v[224:227], v[184:187], v[16:19]
	v_mfma_f32_16x16x32_bf16 v[8:11], v[232:235], v[184:187], v[8:11]
	v_mfma_f32_16x16x32_bf16 v[4:7], v[224:227], v[192:195], v[4:7]
	v_mfma_f32_16x16x32_bf16 v[0:3], v[232:235], v[192:195], v[0:3]
	s_setprio 0
	s_add_i32 s29, 0, 0x18000
	v_add_u32_e32 v153, s29, v140
	s_barrier
	ds_read_b128 v[142:145], v153
	ds_read_b128 v[146:149], v153 offset:1024
	ds_read_b128 v[154:157], v153 offset:2048
	ds_read_b128 v[158:161], v153 offset:3072
	s_add_u32 s14, s14, 0x100000
	s_addc_u32 s15, s15, 0
	s_mov_b32 m0, s24
	ds_read_b128 v[162:165], v141 offset:32768
	ds_read_b128 v[166:169], v141 offset:33792
	ds_read_b128 v[170:173], v141 offset:34816
	ds_read_b128 v[174:177], v141 offset:35840
	ds_read_b128 v[180:183], v141 offset:36864
	ds_read_b128 v[184:187], v141 offset:37888
	ds_read_b128 v[188:191], v141 offset:38912
	ds_read_b128 v[192:195], v141 offset:39936
	global_load_lds_dwordx4 v132, s[14:15]
	s_mov_b32 m0, s25
	s_nop 0
	global_load_lds_dwordx4 v130, s[14:15]
	s_waitcnt lgkmcnt(8)
	s_barrier
	s_waitcnt lgkmcnt(0)
	s_setprio 1
	s_waitcnt lgkmcnt(0)
	v_mfma_f32_16x16x32_bf16 v[124:127], v[142:145], v[162:165], v[124:127]
	v_mfma_f32_16x16x32_bf16 v[120:123], v[154:157], v[162:165], v[120:123]
	v_mfma_f32_16x16x32_bf16 v[116:119], v[142:145], v[170:173], v[116:119]
	v_mfma_f32_16x16x32_bf16 v[108:111], v[154:157], v[170:173], v[108:111]
	v_mfma_f32_16x16x32_bf16 v[100:103], v[142:145], v[180:183], v[100:103]
	v_mfma_f32_16x16x32_bf16 v[92:95], v[154:157], v[180:183], v[92:95]
	v_mfma_f32_16x16x32_bf16 v[84:87], v[142:145], v[188:191], v[84:87]
	v_mfma_f32_16x16x32_bf16 v[76:79], v[154:157], v[188:191], v[76:79]
	v_mfma_f32_16x16x32_bf16 v[124:127], v[146:149], v[166:169], v[124:127]
	v_mfma_f32_16x16x32_bf16 v[120:123], v[158:161], v[166:169], v[120:123]
	v_mfma_f32_16x16x32_bf16 v[116:119], v[146:149], v[174:177], v[116:119]
	v_mfma_f32_16x16x32_bf16 v[108:111], v[158:161], v[174:177], v[108:111]
	v_mfma_f32_16x16x32_bf16 v[100:103], v[146:149], v[184:187], v[100:103]
	v_mfma_f32_16x16x32_bf16 v[92:95], v[158:161], v[184:187], v[92:95]
	v_mfma_f32_16x16x32_bf16 v[84:87], v[146:149], v[192:195], v[84:87]
	v_mfma_f32_16x16x32_bf16 v[76:79], v[158:161], v[192:195], v[76:79]
	s_setprio 0
	s_barrier
	s_add_i32 s14, 0, 0x1c000
	s_add_i32 s15, s29, s16
	v_add_u32_e32 v153, s14, v140
	v_lshl_add_u64 v[150:151], v[150:151], 0, s[54:55]
	s_mov_b32 m0, s15
	ds_read_b128 v[196:199], v153
	ds_read_b128 v[224:227], v153 offset:1024
	ds_read_b128 v[228:231], v153 offset:2048
	ds_read_b128 v[232:235], v153 offset:3072
	global_load_lds_dwordx4 v[150:151], off
	v_lshl_add_u64 v[150:151], v[204:205], 0, s[54:55]
	s_add_i32 m0, s15, 0x2000
	s_nop 0
	global_load_lds_dwordx4 v[150:151], off
	s_barrier
	s_waitcnt lgkmcnt(0)
	s_setprio 1
	s_waitcnt lgkmcnt(0)
	v_mfma_f32_16x16x32_bf16 v[112:115], v[196:199], v[162:165], v[112:115]
	v_mfma_f32_16x16x32_bf16 v[104:107], v[228:231], v[162:165], v[104:107]
	v_mfma_f32_16x16x32_bf16 v[96:99], v[196:199], v[170:173], v[96:99]
	v_mfma_f32_16x16x32_bf16 v[88:91], v[228:231], v[170:173], v[88:91]
	v_mfma_f32_16x16x32_bf16 v[80:83], v[196:199], v[180:183], v[80:83]
	v_mfma_f32_16x16x32_bf16 v[72:75], v[228:231], v[180:183], v[72:75]
	v_mfma_f32_16x16x32_bf16 v[68:71], v[196:199], v[188:191], v[68:71]
	v_mfma_f32_16x16x32_bf16 v[64:67], v[228:231], v[188:191], v[64:67]
	v_mfma_f32_16x16x32_bf16 v[112:115], v[224:227], v[166:169], v[112:115]
	v_mfma_f32_16x16x32_bf16 v[104:107], v[232:235], v[166:169], v[104:107]
	v_mfma_f32_16x16x32_bf16 v[96:99], v[224:227], v[174:177], v[96:99]
	v_mfma_f32_16x16x32_bf16 v[88:91], v[232:235], v[174:177], v[88:91]
	v_mfma_f32_16x16x32_bf16 v[80:83], v[224:227], v[184:187], v[80:83]
	v_mfma_f32_16x16x32_bf16 v[72:75], v[232:235], v[184:187], v[72:75]
	v_mfma_f32_16x16x32_bf16 v[68:71], v[224:227], v[192:195], v[68:71]
	v_mfma_f32_16x16x32_bf16 v[64:67], v[232:235], v[192:195], v[64:67]
	s_setprio 0
	s_mov_b32 m0, s26
	v_lshl_add_u64 v[150:151], v[206:207], 0, s[54:55]
	s_barrier
	ds_read_b128 v[162:165], v141 offset:49152
	ds_read_b128 v[166:169], v141 offset:50176
	ds_read_b128 v[170:173], v141 offset:51200
	ds_read_b128 v[174:177], v141 offset:52224
	ds_read_b128 v[180:183], v141 offset:53248
	ds_read_b128 v[184:187], v141 offset:54272
	ds_read_b128 v[188:191], v141 offset:55296
	ds_read_b128 v[192:195], v141 offset:56320
	global_load_lds_dwordx4 v[150:151], off
	v_lshl_add_u64 v[150:151], v[212:213], 0, s[54:55]
	s_mov_b32 m0, s27
	s_nop 0
	global_load_lds_dwordx4 v[150:151], off
	s_barrier
	s_waitcnt lgkmcnt(0)
	s_setprio 1
	s_waitcnt lgkmcnt(0)
	v_mfma_f32_16x16x32_bf16 v[60:63], v[142:145], v[162:165], v[60:63]
	v_mfma_f32_16x16x32_bf16 v[56:59], v[154:157], v[162:165], v[56:59]
	v_mfma_f32_16x16x32_bf16 v[52:55], v[142:145], v[170:173], v[52:55]
	v_mfma_f32_16x16x32_bf16 v[44:47], v[154:157], v[170:173], v[44:47]
	v_mfma_f32_16x16x32_bf16 v[36:39], v[142:145], v[180:183], v[36:39]
	v_mfma_f32_16x16x32_bf16 v[28:31], v[154:157], v[180:183], v[28:31]
	v_mfma_f32_16x16x32_bf16 v[20:23], v[142:145], v[188:191], v[20:23]
	v_mfma_f32_16x16x32_bf16 v[12:15], v[154:157], v[188:191], v[12:15]
	v_mfma_f32_16x16x32_bf16 v[60:63], v[146:149], v[166:169], v[60:63]
	v_mfma_f32_16x16x32_bf16 v[56:59], v[158:161], v[166:169], v[56:59]
	v_mfma_f32_16x16x32_bf16 v[52:55], v[146:149], v[174:177], v[52:55]
	v_mfma_f32_16x16x32_bf16 v[44:47], v[158:161], v[174:177], v[44:47]
	v_mfma_f32_16x16x32_bf16 v[36:39], v[146:149], v[184:187], v[36:39]
	v_mfma_f32_16x16x32_bf16 v[28:31], v[158:161], v[184:187], v[28:31]
	v_mfma_f32_16x16x32_bf16 v[20:23], v[146:149], v[192:195], v[20:23]
	v_mfma_f32_16x16x32_bf16 v[12:15], v[158:161], v[192:195], v[12:15]
	s_setprio 0
	s_barrier
	s_add_u32 s12, s12, 0x100080
	s_addc_u32 s13, s13, 0
	s_add_i32 s14, s14, s16
	s_mov_b32 m0, s14
	s_nop 0
	global_load_lds_dwordx4 v178, s[12:13]
	s_add_i32 m0, s14, 0x2000
	s_nop 0
	global_load_lds_dwordx4 v128, s[12:13]
	s_waitcnt vmcnt(6)
	s_barrier
	s_setprio 1
	v_mfma_f32_16x16x32_bf16 v[48:51], v[196:199], v[162:165], v[48:51]
	v_mfma_f32_16x16x32_bf16 v[40:43], v[228:231], v[162:165], v[40:43]
	v_mfma_f32_16x16x32_bf16 v[32:35], v[196:199], v[170:173], v[32:35]
	v_mfma_f32_16x16x32_bf16 v[24:27], v[228:231], v[170:173], v[24:27]
	v_mfma_f32_16x16x32_bf16 v[16:19], v[196:199], v[180:183], v[16:19]
	v_mfma_f32_16x16x32_bf16 v[8:11], v[228:231], v[180:183], v[8:11]
	v_mfma_f32_16x16x32_bf16 v[4:7], v[196:199], v[188:191], v[4:7]
	v_mfma_f32_16x16x32_bf16 v[0:3], v[228:231], v[188:191], v[0:3]
	v_mfma_f32_16x16x32_bf16 v[48:51], v[224:227], v[166:169], v[48:51]
	v_mfma_f32_16x16x32_bf16 v[40:43], v[232:235], v[166:169], v[40:43]
	v_mfma_f32_16x16x32_bf16 v[32:35], v[224:227], v[174:177], v[32:35]
	v_mfma_f32_16x16x32_bf16 v[24:27], v[232:235], v[174:177], v[24:27]
	v_mfma_f32_16x16x32_bf16 v[16:19], v[224:227], v[184:187], v[16:19]
	v_mfma_f32_16x16x32_bf16 v[8:11], v[232:235], v[184:187], v[8:11]
	v_mfma_f32_16x16x32_bf16 v[4:7], v[224:227], v[192:195], v[4:7]
	v_mfma_f32_16x16x32_bf16 v[0:3], v[232:235], v[192:195], v[0:3]
	s_setprio 0
	s_add_i32 s28, s28, 2
	s_add_u32 s10, s10, 0x100
	s_addc_u32 s11, s11, 0
	s_cmp_gt_u32 s28, 61
	s_barrier
	s_cbranch_scc0 .LBB0_935
	v_readlane_b32 s6, v253, 51
	s_or_b32 s6, s17, s6
	v_cvt_pk_bf16_f32 v124, v124, v125
	v_cvt_pk_bf16_f32 v125, v126, v127
	v_cvt_pk_bf16_f32 v126, v120, v121
	v_cvt_pk_bf16_f32 v127, v122, v123
	s_nop 0
	v_or_b32_e32 v130, s6, v139
	v_readlane_b32 s6, v253, 44
	v_lshlrev_b32_e32 v178, 1, v130
	s_nop 0
	v_add_u32_e32 v131, s6, v138
	v_add_u32_e32 v128, 0x1000, v131
	v_ashrrev_i32_e32 v129, 31, v128
	v_lshlrev_b64 v[128:129], 12, v[128:129]
	v_lshl_add_u64 v[128:129], s[4:5], 0, v[128:129]
	v_lshl_add_u64 v[128:129], v[128:129], 0, v[178:179]
	global_store_dwordx4 v[128:129], v[124:127], off
	v_cvt_pk_bf16_f32 v112, v112, v113
	v_cvt_pk_bf16_f32 v113, v114, v115
	v_cvt_pk_bf16_f32 v114, v104, v105
	v_add_u32_e32 v104, 0x1010, v131
	v_ashrrev_i32_e32 v105, 31, v104
	v_lshlrev_b64 v[104:105], 12, v[104:105]
	v_lshl_add_u64 v[104:105], s[4:5], 0, v[104:105]
	v_cvt_pk_bf16_f32 v115, v106, v107
	global_store_dwordx4 v[128:129], v[112:115], off offset:256
	v_readlane_b32 s6, v255, 8
	s_nop 0
	v_lshl_add_u64 v[112:113], v[104:105], 0, v[178:179]
	v_cvt_pk_bf16_f32 v104, v116, v117
	v_cvt_pk_bf16_f32 v105, v118, v119
	v_cvt_pk_bf16_f32 v106, v108, v109
	v_cvt_pk_bf16_f32 v107, v110, v111
	global_store_dwordx4 v[112:113], v[104:107], off
	v_cvt_pk_bf16_f32 v96, v96, v97
	v_cvt_pk_bf16_f32 v97, v98, v99
	v_cvt_pk_bf16_f32 v98, v88, v89
	v_add_u32_e32 v88, 0x1020, v131
	v_ashrrev_i32_e32 v89, 31, v88
	v_lshlrev_b64 v[88:89], 12, v[88:89]
	v_lshl_add_u64 v[88:89], s[4:5], 0, v[88:89]
	v_cvt_pk_bf16_f32 v99, v90, v91
	global_store_dwordx4 v[112:113], v[96:99], off offset:256
	s_nop 1
	v_lshl_add_u64 v[96:97], v[88:89], 0, v[178:179]
	v_cvt_pk_bf16_f32 v88, v100, v101
	v_cvt_pk_bf16_f32 v89, v102, v103
	v_cvt_pk_bf16_f32 v90, v92, v93
	v_cvt_pk_bf16_f32 v91, v94, v95
	global_store_dwordx4 v[96:97], v[88:91], off
	v_cvt_pk_bf16_f32 v80, v80, v81
	v_cvt_pk_bf16_f32 v81, v82, v83
	v_cvt_pk_bf16_f32 v82, v72, v73
	v_add_u32_e32 v72, 0x1030, v131
	v_ashrrev_i32_e32 v73, 31, v72
	v_lshlrev_b64 v[72:73], 12, v[72:73]
	v_lshl_add_u64 v[72:73], s[4:5], 0, v[72:73]
	v_cvt_pk_bf16_f32 v83, v74, v75
	global_store_dwordx4 v[96:97], v[80:83], off offset:256
	s_nop 1
	v_lshl_add_u64 v[80:81], v[72:73], 0, v[178:179]
	v_cvt_pk_bf16_f32 v72, v84, v85
	v_cvt_pk_bf16_f32 v73, v86, v87
	v_cvt_pk_bf16_f32 v74, v76, v77
	v_cvt_pk_bf16_f32 v75, v78, v79
	global_store_dwordx4 v[80:81], v[72:75], off
	v_cvt_pk_bf16_f32 v68, v68, v69
	v_cvt_pk_bf16_f32 v69, v70, v71
	v_cvt_pk_bf16_f32 v70, v64, v65
	v_add_u32_e32 v64, 0x1080, v131
	v_ashrrev_i32_e32 v65, 31, v64
	v_lshlrev_b64 v[64:65], 12, v[64:65]
	v_lshl_add_u64 v[64:65], s[4:5], 0, v[64:65]
	v_lshl_add_u64 v[64:65], v[64:65], 0, v[178:179]
	v_cvt_pk_bf16_f32 v71, v66, v67
	global_store_dwordx4 v[80:81], v[68:71], off offset:256
	v_cvt_pk_bf16_f32 v60, v60, v61
	v_cvt_pk_bf16_f32 v61, v62, v63
	v_cvt_pk_bf16_f32 v62, v56, v57
	v_cvt_pk_bf16_f32 v63, v58, v59
	global_store_dwordx4 v[64:65], v[60:63], off
	v_cvt_pk_bf16_f32 v48, v48, v49
	v_cvt_pk_bf16_f32 v49, v50, v51
	v_cvt_pk_bf16_f32 v50, v40, v41
	v_add_u32_e32 v40, 0x1090, v131
	v_ashrrev_i32_e32 v41, 31, v40
	v_lshlrev_b64 v[40:41], 12, v[40:41]
	v_lshl_add_u64 v[40:41], s[4:5], 0, v[40:41]
	v_cvt_pk_bf16_f32 v51, v42, v43
	global_store_dwordx4 v[64:65], v[48:51], off offset:256
	s_nop 1
	v_lshl_add_u64 v[48:49], v[40:41], 0, v[178:179]
	v_cvt_pk_bf16_f32 v40, v52, v53
	v_cvt_pk_bf16_f32 v41, v54, v55
	v_cvt_pk_bf16_f32 v42, v44, v45
	v_cvt_pk_bf16_f32 v43, v46, v47
	global_store_dwordx4 v[48:49], v[40:43], off
	v_cvt_pk_bf16_f32 v32, v32, v33
	v_cvt_pk_bf16_f32 v33, v34, v35
	v_cvt_pk_bf16_f32 v34, v24, v25
	v_add_u32_e32 v24, 0x10a0, v131
	v_ashrrev_i32_e32 v25, 31, v24
	v_lshlrev_b64 v[24:25], 12, v[24:25]
	v_lshl_add_u64 v[24:25], s[4:5], 0, v[24:25]
	v_cvt_pk_bf16_f32 v35, v26, v27
	global_store_dwordx4 v[48:49], v[32:35], off offset:256
	s_nop 1
	v_lshl_add_u64 v[32:33], v[24:25], 0, v[178:179]
	v_cvt_pk_bf16_f32 v24, v36, v37
	v_cvt_pk_bf16_f32 v25, v38, v39
	v_cvt_pk_bf16_f32 v26, v28, v29
	v_cvt_pk_bf16_f32 v27, v30, v31
	global_store_dwordx4 v[32:33], v[24:27], off
	v_cvt_pk_bf16_f32 v16, v16, v17
	v_cvt_pk_bf16_f32 v17, v18, v19
	v_cvt_pk_bf16_f32 v18, v8, v9
	v_add_u32_e32 v8, 0x10b0, v131
	v_ashrrev_i32_e32 v9, 31, v8
	v_lshlrev_b64 v[8:9], 12, v[8:9]
	v_lshl_add_u64 v[8:9], s[4:5], 0, v[8:9]
	v_cvt_pk_bf16_f32 v19, v10, v11
	global_store_dwordx4 v[32:33], v[16:19], off offset:256
	s_nop 1
	v_lshl_add_u64 v[16:17], v[8:9], 0, v[178:179]
	v_cvt_pk_bf16_f32 v8, v20, v21
	v_cvt_pk_bf16_f32 v9, v22, v23
	v_cvt_pk_bf16_f32 v10, v12, v13
	v_cvt_pk_bf16_f32 v11, v14, v15
	global_store_dwordx4 v[16:17], v[8:11], off
	v_cvt_pk_bf16_f32 v4, v4, v5
	v_cvt_pk_bf16_f32 v5, v6, v7
	v_cvt_pk_bf16_f32 v6, v0, v1
	v_cvt_pk_bf16_f32 v7, v2, v3
	global_store_dwordx4 v[16:17], v[4:7], off offset:256
	s_waitcnt vmcnt(0)
	s_cmp_lt_u32 s6, 4
	s_cbranch_scc0 .LBB0_938
	s_barrier

.LBB0_942:
	v_lshl_add_u64 v[8:9], s[8:9], 0, v[178:179]
	v_and_b32_e32 v7, 15, v3
	v_lshrrev_b32_e32 v12, 1, v3
	v_or_b32_e32 v138, s20, v7
	v_and_b32_e32 v139, 24, v12
	s_add_i32 m0, s22, 0x18000
	v_lshl_add_u64 v[8:9], v[8:9], 0, s[54:55]
	v_mov_b32_e32 v129, v179
	v_lshlrev_b32_e32 v12, 6, v138
	v_lshlrev_b32_e32 v13, 1, v139
	s_movk_i32 s10, 0x3c0
	v_lshlrev_b32_e32 v14, 2, v138
	s_waitcnt vmcnt(4)
	s_barrier
	global_load_lds_dwordx4 v[8:9], off
	s_add_i32 m0, s22, 0x1a000
	v_lshl_add_u64 v[10:11], s[8:9], 0, v[128:129]
	v_and_or_b32 v12, v12, s10, v13
	v_and_b32_e32 v14, 32, v14
	v_lshlrev_b32_e32 v3, 2, v3
	s_add_u32 s10, s88, 0xc300080
	v_mov_b32_e32 v133, v179
	v_bitop3_b32 v12, v12, s18, v14 bitop3:0xde
	v_lshl_or_b32 v7, v7, 6, v13
	v_and_b32_e32 v3, 32, v3
	v_lshl_add_u64 v[8:9], v[10:11], 0, s[54:55]
	s_addc_u32 s11, s89, 0
	s_add_i32 s18, s22, 0x8000
	v_mov_b32_e32 v131, v179
	v_bitop3_b32 v140, v7, s19, v3 bitop3:0xde
	global_load_lds_dwordx4 v[8:9], off
	s_mov_b32 m0, s18
	s_add_i32 s19, s22, 0xa000
	global_load_lds_dwordx4 v132, s[10:11]
	v_lshl_add_u64 v[8:9], s[10:11], 0, v[130:131]
	s_add_u32 s10, s8, 0x20080
	s_mov_b32 m0, s19
	s_addc_u32 s11, s9, 0
	global_load_lds_dwordx4 v[8:9], off
	s_add_i32 m0, s22, 0x1c000
	global_load_lds_dwordx4 v178, s[10:11]
	s_add_i32 m0, s22, 0x1e000
	v_lshlrev_b32_e32 v3, 13, v0
	global_load_lds_dwordx4 v128, s[10:11]
	v_and_b32_e32 v3, 0xffffc000, v3
	v_lshl_add_u32 v1, v1, 10, v3
	v_and_b32_e32 v0, 1, v0
	v_lshl_or_b32 v0, v0, 6, v1
	v_lshl_add_u32 v0, v2, 1, v0
	v_mov_b32_e32 v1, v179
	v_lshl_add_u64 v[134:135], s[88:89], 0, v[0:1]
	v_lshlrev_b32_e32 v0, 13, v4
	v_and_b32_e32 v0, 0xffffc000, v0
	v_lshl_add_u32 v0, v5, 10, v0
	v_and_b32_e32 v1, 1, v4
	v_lshl_or_b32 v0, v1, 6, v0
	s_waitcnt vmcnt(6)
	v_lshl_add_u32 v0, v6, 1, v0
	v_mov_b32_e32 v1, v179
	v_lshl_add_u64 v[136:137], s[88:89], 0, v[0:1]
	v_mov_b32_e32 v0, 0
	s_mov_b32 s20, -2
	s_mov_b64 s[10:11], 0xc320080
	v_add_u32_e32 v141, 0, v12
	v_mov_b32_e32 v1, v0
	v_mov_b32_e32 v2, v0
	v_mov_b32_e32 v3, v0
	v_mov_b32_e32 v4, v0
	v_mov_b32_e32 v5, v0
	v_mov_b32_e32 v6, v0
	v_mov_b32_e32 v7, v0
	v_mov_b32_e32 v8, v0
	v_mov_b32_e32 v9, v0
	v_mov_b32_e32 v10, v0
	v_mov_b32_e32 v11, v0
	v_mov_b32_e32 v16, v0
	v_mov_b32_e32 v17, v0
	v_mov_b32_e32 v18, v0
	v_mov_b32_e32 v19, v0
	v_mov_b32_e32 v24, v0
	v_mov_b32_e32 v25, v0
	v_mov_b32_e32 v26, v0
	v_mov_b32_e32 v27, v0
	v_mov_b32_e32 v32, v0
	v_mov_b32_e32 v33, v0
	v_mov_b32_e32 v34, v0
	v_mov_b32_e32 v35, v0
	v_mov_b32_e32 v40, v0
	v_mov_b32_e32 v41, v0
	v_mov_b32_e32 v42, v0
	v_mov_b32_e32 v43, v0
	v_mov_b32_e32 v48, v0
	v_mov_b32_e32 v49, v0
	v_mov_b32_e32 v50, v0
	v_mov_b32_e32 v51, v0
	v_mov_b32_e32 v12, v0
	v_mov_b32_e32 v13, v0
	v_mov_b32_e32 v14, v0
	v_mov_b32_e32 v15, v0
	v_mov_b32_e32 v20, v0
	v_mov_b32_e32 v21, v0
	v_mov_b32_e32 v22, v0
	v_mov_b32_e32 v23, v0
	v_mov_b32_e32 v28, v0
	v_mov_b32_e32 v29, v0
	v_mov_b32_e32 v30, v0
	v_mov_b32_e32 v31, v0
	v_mov_b32_e32 v36, v0
	v_mov_b32_e32 v37, v0
	v_mov_b32_e32 v38, v0
	v_mov_b32_e32 v39, v0
	v_mov_b32_e32 v44, v0
	v_mov_b32_e32 v45, v0
	v_mov_b32_e32 v46, v0
	v_mov_b32_e32 v47, v0
	v_mov_b32_e32 v52, v0
	v_mov_b32_e32 v53, v0
	v_mov_b32_e32 v54, v0
	v_mov_b32_e32 v55, v0
	v_mov_b32_e32 v56, v0
	v_mov_b32_e32 v57, v0
	v_mov_b32_e32 v58, v0
	v_mov_b32_e32 v59, v0
	v_mov_b32_e32 v60, v0
	v_mov_b32_e32 v61, v0
	v_mov_b32_e32 v62, v0
	v_mov_b32_e32 v63, v0
	v_mov_b32_e32 v64, v0
	v_mov_b32_e32 v65, v0
	v_mov_b32_e32 v66, v0
	v_mov_b32_e32 v67, v0
	v_mov_b32_e32 v68, v0
	v_mov_b32_e32 v69, v0
	v_mov_b32_e32 v70, v0
	v_mov_b32_e32 v71, v0
	v_mov_b32_e32 v72, v0
	v_mov_b32_e32 v73, v0
	v_mov_b32_e32 v74, v0
	v_mov_b32_e32 v75, v0
	v_mov_b32_e32 v80, v0
	v_mov_b32_e32 v81, v0
	v_mov_b32_e32 v82, v0
	v_mov_b32_e32 v83, v0
	v_mov_b32_e32 v88, v0
	v_mov_b32_e32 v89, v0
	v_mov_b32_e32 v90, v0
	v_mov_b32_e32 v91, v0
	v_mov_b32_e32 v96, v0
	v_mov_b32_e32 v97, v0
	v_mov_b32_e32 v98, v0
	v_mov_b32_e32 v99, v0
	v_mov_b32_e32 v104, v0
	v_mov_b32_e32 v105, v0
	v_mov_b32_e32 v106, v0
	v_mov_b32_e32 v107, v0
	v_mov_b32_e32 v112, v0
	v_mov_b32_e32 v113, v0
	v_mov_b32_e32 v114, v0
	v_mov_b32_e32 v115, v0
	v_mov_b32_e32 v76, v0
	v_mov_b32_e32 v77, v0
	v_mov_b32_e32 v78, v0
	v_mov_b32_e32 v79, v0
	v_mov_b32_e32 v84, v0
	v_mov_b32_e32 v85, v0
	v_mov_b32_e32 v86, v0
	v_mov_b32_e32 v87, v0
	v_mov_b32_e32 v92, v0
	v_mov_b32_e32 v93, v0
	v_mov_b32_e32 v94, v0
	v_mov_b32_e32 v95, v0
	v_mov_b32_e32 v100, v0
	v_mov_b32_e32 v101, v0
	v_mov_b32_e32 v102, v0
	v_mov_b32_e32 v103, v0
	v_mov_b32_e32 v108, v0
	v_mov_b32_e32 v109, v0
	v_mov_b32_e32 v110, v0
	v_mov_b32_e32 v111, v0
	v_mov_b32_e32 v116, v0
	v_mov_b32_e32 v117, v0
	v_mov_b32_e32 v118, v0
	v_mov_b32_e32 v119, v0
	v_mov_b32_e32 v120, v0
	v_mov_b32_e32 v121, v0
	v_mov_b32_e32 v122, v0
	v_mov_b32_e32 v123, v0
	v_mov_b32_e32 v124, v0
	v_mov_b32_e32 v125, v0
	v_mov_b32_e32 v126, v0
	v_mov_b32_e32 v127, v0
	s_barrier
.LBB0_943:
	s_add_u32 s12, s10, 0xf3ce0080
	s_addc_u32 s13, s11, -1
	s_cmp_lg_u32 s20, 4
	s_cselect_b32 s12, s12, 0
	s_cselect_b32 s13, s13, 0
	s_add_u32 s14, s6, s12
	s_addc_u32 s15, s7, s13
	s_add_i32 s21, 0, 0x10000
	v_add_u32_e32 v150, s21, v140
	ds_read_b128 v[142:145], v150
	ds_read_b128 v[146:149], v150 offset:1024
	ds_read_b128 v[154:157], v150 offset:2048
	ds_read_b128 v[158:161], v150 offset:3072
	s_add_u32 s12, s8, s12
	s_addc_u32 s13, s9, s13
	v_lshl_add_u64 v[150:151], v[136:137], 0, s[10:11]
	s_add_i32 m0, s22, 0xc000
	ds_read_b128 v[162:165], v141
	ds_read_b128 v[166:169], v141 offset:1024
	ds_read_b128 v[170:173], v141 offset:2048
	ds_read_b128 v[174:177], v141 offset:3072
	ds_read_b128 v[180:183], v141 offset:4096
	ds_read_b128 v[184:187], v141 offset:5120
	ds_read_b128 v[188:191], v141 offset:6144
	ds_read_b128 v[192:195], v141 offset:7168
	global_load_lds_dwordx4 v[150:151], off
	v_lshl_add_u64 v[150:151], v[134:135], 0, s[10:11]
	s_add_i32 m0, s22, 0xe000
	s_nop 0
	global_load_lds_dwordx4 v[150:151], off
	s_waitcnt lgkmcnt(8)
	s_barrier
	s_waitcnt lgkmcnt(0)
	s_setprio 1
	s_waitcnt lgkmcnt(0)
	v_mfma_f32_16x16x32_bf16 v[124:127], v[142:145], v[162:165], v[124:127]
	v_mfma_f32_16x16x32_bf16 v[120:123], v[154:157], v[162:165], v[120:123]
	v_mfma_f32_16x16x32_bf16 v[116:119], v[142:145], v[170:173], v[116:119]
	v_mfma_f32_16x16x32_bf16 v[108:111], v[154:157], v[170:173], v[108:111]
	v_mfma_f32_16x16x32_bf16 v[100:103], v[142:145], v[180:183], v[100:103]
	v_mfma_f32_16x16x32_bf16 v[92:95], v[154:157], v[180:183], v[92:95]
	v_mfma_f32_16x16x32_bf16 v[84:87], v[142:145], v[188:191], v[84:87]
	v_mfma_f32_16x16x32_bf16 v[76:79], v[154:157], v[188:191], v[76:79]
	v_mfma_f32_16x16x32_bf16 v[124:127], v[146:149], v[166:169], v[124:127]
	v_mfma_f32_16x16x32_bf16 v[120:123], v[158:161], v[166:169], v[120:123]
	v_mfma_f32_16x16x32_bf16 v[116:119], v[146:149], v[174:177], v[116:119]
	v_mfma_f32_16x16x32_bf16 v[108:111], v[158:161], v[174:177], v[108:111]
	v_mfma_f32_16x16x32_bf16 v[100:103], v[146:149], v[184:187], v[100:103]
	v_mfma_f32_16x16x32_bf16 v[92:95], v[158:161], v[184:187], v[92:95]
	v_mfma_f32_16x16x32_bf16 v[84:87], v[146:149], v[192:195], v[84:87]
	v_mfma_f32_16x16x32_bf16 v[76:79], v[158:161], v[192:195], v[76:79]
	s_setprio 0
	s_barrier
	s_add_i32 s28, 0, 0x14000
	v_add_u32_e32 v150, s28, v140
	s_add_i32 s21, s21, s16
	ds_read_b128 v[196:199], v150
	ds_read_b128 v[224:227], v150 offset:1024
	ds_read_b128 v[228:231], v150 offset:2048
	ds_read_b128 v[232:235], v150 offset:3072
	v_lshl_add_u64 v[150:151], s[12:13], 0, v[178:179]
	s_mov_b32 m0, s21
	v_lshl_add_u64 v[204:205], s[12:13], 0, v[128:129]
	global_load_lds_dwordx4 v[150:151], off
	s_add_i32 m0, s21, 0x2000
	s_nop 0
	global_load_lds_dwordx4 v[204:205], off
	s_barrier
	s_waitcnt lgkmcnt(0)
	s_setprio 1
	s_waitcnt lgkmcnt(0)
	v_mfma_f32_16x16x32_bf16 v[112:115], v[196:199], v[162:165], v[112:115]
	v_mfma_f32_16x16x32_bf16 v[104:107], v[228:231], v[162:165], v[104:107]
	v_mfma_f32_16x16x32_bf16 v[96:99], v[196:199], v[170:173], v[96:99]
	v_mfma_f32_16x16x32_bf16 v[88:91], v[228:231], v[170:173], v[88:91]
	v_mfma_f32_16x16x32_bf16 v[80:83], v[196:199], v[180:183], v[80:83]
	v_mfma_f32_16x16x32_bf16 v[72:75], v[228:231], v[180:183], v[72:75]
	v_mfma_f32_16x16x32_bf16 v[68:71], v[196:199], v[188:191], v[68:71]
	v_mfma_f32_16x16x32_bf16 v[64:67], v[228:231], v[188:191], v[64:67]
	v_mfma_f32_16x16x32_bf16 v[112:115], v[224:227], v[166:169], v[112:115]
	v_mfma_f32_16x16x32_bf16 v[104:107], v[232:235], v[166:169], v[104:107]
	v_mfma_f32_16x16x32_bf16 v[96:99], v[224:227], v[174:177], v[96:99]
	v_mfma_f32_16x16x32_bf16 v[88:91], v[232:235], v[174:177], v[88:91]
	v_mfma_f32_16x16x32_bf16 v[80:83], v[224:227], v[184:187], v[80:83]
	v_mfma_f32_16x16x32_bf16 v[72:75], v[232:235], v[184:187], v[72:75]
	v_mfma_f32_16x16x32_bf16 v[68:71], v[224:227], v[192:195], v[68:71]
	v_mfma_f32_16x16x32_bf16 v[64:67], v[232:235], v[192:195], v[64:67]
	s_setprio 0
	s_mov_b32 m0, s22
	v_lshl_add_u64 v[206:207], s[14:15], 0, v[132:133]
	s_barrier
	ds_read_b128 v[162:165], v141 offset:16384
	ds_read_b128 v[166:169], v141 offset:17408
	ds_read_b128 v[170:173], v141 offset:18432
	ds_read_b128 v[174:177], v141 offset:19456
	ds_read_b128 v[180:183], v141 offset:20480
	ds_read_b128 v[184:187], v141 offset:21504
	ds_read_b128 v[188:191], v141 offset:22528
	ds_read_b128 v[192:195], v141 offset:23552
	global_load_lds_dwordx4 v[206:207], off
	v_lshl_add_u64 v[212:213], s[14:15], 0, v[130:131]
	s_mov_b32 m0, s23
	s_nop 0
	global_load_lds_dwordx4 v[212:213], off
	s_barrier
	s_waitcnt lgkmcnt(0)
	s_setprio 1
	s_waitcnt lgkmcnt(0)
	v_mfma_f32_16x16x32_bf16 v[60:63], v[142:145], v[162:165], v[60:63]
	v_mfma_f32_16x16x32_bf16 v[56:59], v[154:157], v[162:165], v[56:59]
	v_mfma_f32_16x16x32_bf16 v[52:55], v[142:145], v[170:173], v[52:55]
	v_mfma_f32_16x16x32_bf16 v[44:47], v[154:157], v[170:173], v[44:47]
	v_mfma_f32_16x16x32_bf16 v[36:39], v[142:145], v[180:183], v[36:39]
	v_mfma_f32_16x16x32_bf16 v[28:31], v[154:157], v[180:183], v[28:31]
	v_mfma_f32_16x16x32_bf16 v[20:23], v[142:145], v[188:191], v[20:23]
	v_mfma_f32_16x16x32_bf16 v[12:15], v[154:157], v[188:191], v[12:15]
	v_mfma_f32_16x16x32_bf16 v[60:63], v[146:149], v[166:169], v[60:63]
	v_mfma_f32_16x16x32_bf16 v[56:59], v[158:161], v[166:169], v[56:59]
	v_mfma_f32_16x16x32_bf16 v[52:55], v[146:149], v[174:177], v[52:55]
	v_mfma_f32_16x16x32_bf16 v[44:47], v[158:161], v[174:177], v[44:47]
	v_mfma_f32_16x16x32_bf16 v[36:39], v[146:149], v[184:187], v[36:39]
	v_mfma_f32_16x16x32_bf16 v[28:31], v[158:161], v[184:187], v[28:31]
	v_mfma_f32_16x16x32_bf16 v[20:23], v[146:149], v[192:195], v[20:23]
	v_mfma_f32_16x16x32_bf16 v[12:15], v[158:161], v[192:195], v[12:15]
	s_setprio 0
	s_barrier
	s_add_u32 s26, s12, 0x20000
	s_addc_u32 s27, s13, 0
	s_add_i32 s21, s28, s16
	s_mov_b32 m0, s21
	s_nop 0
	global_load_lds_dwordx4 v178, s[26:27]
	s_add_i32 m0, s21, 0x2000
	s_nop 0
	global_load_lds_dwordx4 v128, s[26:27]
	s_waitcnt vmcnt(6)
	s_barrier
	s_setprio 1
	v_mfma_f32_16x16x32_bf16 v[48:51], v[196:199], v[162:165], v[48:51]
	v_mfma_f32_16x16x32_bf16 v[40:43], v[228:231], v[162:165], v[40:43]
	v_mfma_f32_16x16x32_bf16 v[32:35], v[196:199], v[170:173], v[32:35]
	v_mfma_f32_16x16x32_bf16 v[24:27], v[228:231], v[170:173], v[24:27]
	v_mfma_f32_16x16x32_bf16 v[16:19], v[196:199], v[180:183], v[16:19]
	v_mfma_f32_16x16x32_bf16 v[8:11], v[228:231], v[180:183], v[8:11]
	v_mfma_f32_16x16x32_bf16 v[4:7], v[196:199], v[188:191], v[4:7]
	v_mfma_f32_16x16x32_bf16 v[0:3], v[228:231], v[188:191], v[0:3]
	v_mfma_f32_16x16x32_bf16 v[48:51], v[224:227], v[166:169], v[48:51]
	v_mfma_f32_16x16x32_bf16 v[40:43], v[232:235], v[166:169], v[40:43]
	v_mfma_f32_16x16x32_bf16 v[32:35], v[224:227], v[174:177], v[32:35]
	v_mfma_f32_16x16x32_bf16 v[24:27], v[232:235], v[174:177], v[24:27]
	v_mfma_f32_16x16x32_bf16 v[16:19], v[224:227], v[184:187], v[16:19]
	v_mfma_f32_16x16x32_bf16 v[8:11], v[232:235], v[184:187], v[8:11]
	v_mfma_f32_16x16x32_bf16 v[4:7], v[224:227], v[192:195], v[4:7]
	v_mfma_f32_16x16x32_bf16 v[0:3], v[232:235], v[192:195], v[0:3]
	s_setprio 0
	s_add_i32 s21, 0, 0x18000
	v_add_u32_e32 v153, s21, v140
	s_barrier
	ds_read_b128 v[142:145], v153
	ds_read_b128 v[146:149], v153 offset:1024
	ds_read_b128 v[154:157], v153 offset:2048
	ds_read_b128 v[158:161], v153 offset:3072
	s_add_u32 s14, s14, 0x20000
	s_addc_u32 s15, s15, 0
	s_mov_b32 m0, s24
	ds_read_b128 v[162:165], v141 offset:32768
	ds_read_b128 v[166:169], v141 offset:33792
	ds_read_b128 v[170:173], v141 offset:34816
	ds_read_b128 v[174:177], v141 offset:35840
	ds_read_b128 v[180:183], v141 offset:36864
	ds_read_b128 v[184:187], v141 offset:37888
	ds_read_b128 v[188:191], v141 offset:38912
	ds_read_b128 v[192:195], v141 offset:39936
	global_load_lds_dwordx4 v132, s[14:15]
	s_mov_b32 m0, s25
	s_nop 0
	global_load_lds_dwordx4 v130, s[14:15]
	s_waitcnt lgkmcnt(8)
	s_barrier
	s_waitcnt lgkmcnt(0)
	s_setprio 1
	s_waitcnt lgkmcnt(0)
	v_mfma_f32_16x16x32_bf16 v[124:127], v[142:145], v[162:165], v[124:127]
	v_mfma_f32_16x16x32_bf16 v[120:123], v[154:157], v[162:165], v[120:123]
	v_mfma_f32_16x16x32_bf16 v[116:119], v[142:145], v[170:173], v[116:119]
	v_mfma_f32_16x16x32_bf16 v[108:111], v[154:157], v[170:173], v[108:111]
	v_mfma_f32_16x16x32_bf16 v[100:103], v[142:145], v[180:183], v[100:103]
	v_mfma_f32_16x16x32_bf16 v[92:95], v[154:157], v[180:183], v[92:95]
	v_mfma_f32_16x16x32_bf16 v[84:87], v[142:145], v[188:191], v[84:87]
	v_mfma_f32_16x16x32_bf16 v[76:79], v[154:157], v[188:191], v[76:79]
	v_mfma_f32_16x16x32_bf16 v[124:127], v[146:149], v[166:169], v[124:127]
	v_mfma_f32_16x16x32_bf16 v[120:123], v[158:161], v[166:169], v[120:123]
	v_mfma_f32_16x16x32_bf16 v[116:119], v[146:149], v[174:177], v[116:119]
	v_mfma_f32_16x16x32_bf16 v[108:111], v[158:161], v[174:177], v[108:111]
	v_mfma_f32_16x16x32_bf16 v[100:103], v[146:149], v[184:187], v[100:103]
	v_mfma_f32_16x16x32_bf16 v[92:95], v[158:161], v[184:187], v[92:95]
	v_mfma_f32_16x16x32_bf16 v[84:87], v[146:149], v[192:195], v[84:87]
	v_mfma_f32_16x16x32_bf16 v[76:79], v[158:161], v[192:195], v[76:79]
	s_setprio 0
	s_barrier
	s_add_i32 s14, 0, 0x1c000
	s_add_i32 s15, s21, s16
	v_add_u32_e32 v153, s14, v140
	v_lshl_add_u64 v[150:151], v[150:151], 0, s[54:55]
	s_mov_b32 m0, s15
	ds_read_b128 v[196:199], v153
	ds_read_b128 v[224:227], v153 offset:1024
	ds_read_b128 v[228:231], v153 offset:2048
	ds_read_b128 v[232:235], v153 offset:3072
	global_load_lds_dwordx4 v[150:151], off
	v_lshl_add_u64 v[150:151], v[204:205], 0, s[54:55]
	s_add_i32 m0, s15, 0x2000
	s_nop 0
	global_load_lds_dwordx4 v[150:151], off
	s_barrier
	s_waitcnt lgkmcnt(0)
	s_setprio 1
	s_waitcnt lgkmcnt(0)
	v_mfma_f32_16x16x32_bf16 v[112:115], v[196:199], v[162:165], v[112:115]
	v_mfma_f32_16x16x32_bf16 v[104:107], v[228:231], v[162:165], v[104:107]
	v_mfma_f32_16x16x32_bf16 v[96:99], v[196:199], v[170:173], v[96:99]
	v_mfma_f32_16x16x32_bf16 v[88:91], v[228:231], v[170:173], v[88:91]
	v_mfma_f32_16x16x32_bf16 v[80:83], v[196:199], v[180:183], v[80:83]
	v_mfma_f32_16x16x32_bf16 v[72:75], v[228:231], v[180:183], v[72:75]
	v_mfma_f32_16x16x32_bf16 v[68:71], v[196:199], v[188:191], v[68:71]
	v_mfma_f32_16x16x32_bf16 v[64:67], v[228:231], v[188:191], v[64:67]
	v_mfma_f32_16x16x32_bf16 v[112:115], v[224:227], v[166:169], v[112:115]
	v_mfma_f32_16x16x32_bf16 v[104:107], v[232:235], v[166:169], v[104:107]
	v_mfma_f32_16x16x32_bf16 v[96:99], v[224:227], v[174:177], v[96:99]
	v_mfma_f32_16x16x32_bf16 v[88:91], v[232:235], v[174:177], v[88:91]
	v_mfma_f32_16x16x32_bf16 v[80:83], v[224:227], v[184:187], v[80:83]
	v_mfma_f32_16x16x32_bf16 v[72:75], v[232:235], v[184:187], v[72:75]
	v_mfma_f32_16x16x32_bf16 v[68:71], v[224:227], v[192:195], v[68:71]
	v_mfma_f32_16x16x32_bf16 v[64:67], v[232:235], v[192:195], v[64:67]
	s_setprio 0
	s_mov_b32 m0, s18
	v_lshl_add_u64 v[150:151], v[206:207], 0, s[54:55]
	s_barrier
	ds_read_b128 v[162:165], v141 offset:49152
	ds_read_b128 v[166:169], v141 offset:50176
	ds_read_b128 v[170:173], v141 offset:51200
	ds_read_b128 v[174:177], v141 offset:52224
	ds_read_b128 v[180:183], v141 offset:53248
	ds_read_b128 v[184:187], v141 offset:54272
	ds_read_b128 v[188:191], v141 offset:55296
	ds_read_b128 v[192:195], v141 offset:56320
	global_load_lds_dwordx4 v[150:151], off
	v_lshl_add_u64 v[150:151], v[212:213], 0, s[54:55]
	s_mov_b32 m0, s19
	s_nop 0
	global_load_lds_dwordx4 v[150:151], off
	s_barrier
	s_waitcnt lgkmcnt(0)
	s_setprio 1
	s_waitcnt lgkmcnt(0)
	v_mfma_f32_16x16x32_bf16 v[60:63], v[142:145], v[162:165], v[60:63]
	v_mfma_f32_16x16x32_bf16 v[56:59], v[154:157], v[162:165], v[56:59]
	v_mfma_f32_16x16x32_bf16 v[52:55], v[142:145], v[170:173], v[52:55]
	v_mfma_f32_16x16x32_bf16 v[44:47], v[154:157], v[170:173], v[44:47]
	v_mfma_f32_16x16x32_bf16 v[36:39], v[142:145], v[180:183], v[36:39]
	v_mfma_f32_16x16x32_bf16 v[28:31], v[154:157], v[180:183], v[28:31]
	v_mfma_f32_16x16x32_bf16 v[20:23], v[142:145], v[188:191], v[20:23]
	v_mfma_f32_16x16x32_bf16 v[12:15], v[154:157], v[188:191], v[12:15]
	v_mfma_f32_16x16x32_bf16 v[60:63], v[146:149], v[166:169], v[60:63]
	v_mfma_f32_16x16x32_bf16 v[56:59], v[158:161], v[166:169], v[56:59]
	v_mfma_f32_16x16x32_bf16 v[52:55], v[146:149], v[174:177], v[52:55]
	v_mfma_f32_16x16x32_bf16 v[44:47], v[158:161], v[174:177], v[44:47]
	v_mfma_f32_16x16x32_bf16 v[36:39], v[146:149], v[184:187], v[36:39]
	v_mfma_f32_16x16x32_bf16 v[28:31], v[158:161], v[184:187], v[28:31]
	v_mfma_f32_16x16x32_bf16 v[20:23], v[146:149], v[192:195], v[20:23]
	v_mfma_f32_16x16x32_bf16 v[12:15], v[158:161], v[192:195], v[12:15]
	s_setprio 0
	s_barrier
	s_add_u32 s12, s12, 0x20080
	s_addc_u32 s13, s13, 0
	s_add_i32 s14, s14, s16
	s_mov_b32 m0, s14
	s_nop 0
	global_load_lds_dwordx4 v178, s[12:13]
	s_add_i32 m0, s14, 0x2000
	s_nop 0
	global_load_lds_dwordx4 v128, s[12:13]
	s_waitcnt vmcnt(6)
	s_barrier
	s_setprio 1
	v_mfma_f32_16x16x32_bf16 v[48:51], v[196:199], v[162:165], v[48:51]
	v_mfma_f32_16x16x32_bf16 v[40:43], v[228:231], v[162:165], v[40:43]
	v_mfma_f32_16x16x32_bf16 v[32:35], v[196:199], v[170:173], v[32:35]
	v_mfma_f32_16x16x32_bf16 v[24:27], v[228:231], v[170:173], v[24:27]
	v_mfma_f32_16x16x32_bf16 v[16:19], v[196:199], v[180:183], v[16:19]
	v_mfma_f32_16x16x32_bf16 v[8:11], v[228:231], v[180:183], v[8:11]
	v_mfma_f32_16x16x32_bf16 v[4:7], v[196:199], v[188:191], v[4:7]
	v_mfma_f32_16x16x32_bf16 v[0:3], v[228:231], v[188:191], v[0:3]
	v_mfma_f32_16x16x32_bf16 v[48:51], v[224:227], v[166:169], v[48:51]
	v_mfma_f32_16x16x32_bf16 v[40:43], v[232:235], v[166:169], v[40:43]
	v_mfma_f32_16x16x32_bf16 v[32:35], v[224:227], v[174:177], v[32:35]
	v_mfma_f32_16x16x32_bf16 v[24:27], v[232:235], v[174:177], v[24:27]
	v_mfma_f32_16x16x32_bf16 v[16:19], v[224:227], v[184:187], v[16:19]
	v_mfma_f32_16x16x32_bf16 v[8:11], v[232:235], v[184:187], v[8:11]
	v_mfma_f32_16x16x32_bf16 v[4:7], v[224:227], v[192:195], v[4:7]
	v_mfma_f32_16x16x32_bf16 v[0:3], v[232:235], v[192:195], v[0:3]
	s_setprio 0
	s_add_i32 s20, s20, 2
	s_add_u32 s10, s10, 0x100
	s_addc_u32 s11, s11, 0
	s_cmp_gt_u32 s20, 5
	s_barrier
	s_cbranch_scc0 .LBB0_943
	v_readlane_b32 s6, v254, 23
	s_or_b32 s6, s17, s6
	v_cvt_pk_bf16_f32 v124, v124, v125
	v_cvt_pk_bf16_f32 v125, v126, v127
	v_cvt_pk_bf16_f32 v126, v120, v121
	v_cvt_pk_bf16_f32 v127, v122, v123
	s_nop 0
	v_or_b32_e32 v132, s6, v139
	v_readlane_b32 s6, v254, 25
	v_lshlrev_b32_e32 v178, 1, v132
	s_nop 0
	v_add_u32_e32 v128, s6, v138
	v_ashrrev_i32_e32 v129, 31, v128
	v_lshlrev_b64 v[130:131], 12, v[128:129]
	v_lshl_add_u64 v[130:131], s[4:5], 0, v[130:131]
	v_lshl_add_u64 v[130:131], v[130:131], 0, v[178:179]
	global_store_dwordx4 v[130:131], v[124:127], off
	v_cvt_pk_bf16_f32 v112, v112, v113
	v_cvt_pk_bf16_f32 v113, v114, v115
	v_cvt_pk_bf16_f32 v114, v104, v105
	v_or_b32_e32 v104, 16, v128
	v_ashrrev_i32_e32 v105, 31, v104
	v_lshlrev_b64 v[104:105], 12, v[104:105]
	v_lshl_add_u64 v[104:105], s[4:5], 0, v[104:105]
	v_cvt_pk_bf16_f32 v115, v106, v107
	global_store_dwordx4 v[130:131], v[112:115], off offset:256
	s_nop 1
	v_lshl_add_u64 v[112:113], v[104:105], 0, v[178:179]
	v_cvt_pk_bf16_f32 v104, v116, v117
	v_cvt_pk_bf16_f32 v105, v118, v119
	v_cvt_pk_bf16_f32 v106, v108, v109
	v_cvt_pk_bf16_f32 v107, v110, v111
	global_store_dwordx4 v[112:113], v[104:107], off
	v_cvt_pk_bf16_f32 v96, v96, v97
	v_cvt_pk_bf16_f32 v97, v98, v99
	v_cvt_pk_bf16_f32 v98, v88, v89
	v_or_b32_e32 v88, 32, v128
	v_ashrrev_i32_e32 v89, 31, v88
	v_lshlrev_b64 v[88:89], 12, v[88:89]
	v_lshl_add_u64 v[88:89], s[4:5], 0, v[88:89]
	v_cvt_pk_bf16_f32 v99, v90, v91
	global_store_dwordx4 v[112:113], v[96:99], off offset:256
	s_nop 1
	v_lshl_add_u64 v[96:97], v[88:89], 0, v[178:179]
	v_cvt_pk_bf16_f32 v88, v100, v101
	v_cvt_pk_bf16_f32 v89, v102, v103
	v_cvt_pk_bf16_f32 v90, v92, v93
	v_cvt_pk_bf16_f32 v91, v94, v95
	global_store_dwordx4 v[96:97], v[88:91], off
	v_cvt_pk_bf16_f32 v80, v80, v81
	v_cvt_pk_bf16_f32 v81, v82, v83
	v_cvt_pk_bf16_f32 v82, v72, v73
	v_or_b32_e32 v72, 48, v128
	v_ashrrev_i32_e32 v73, 31, v72
	v_lshlrev_b64 v[72:73], 12, v[72:73]
	v_lshl_add_u64 v[72:73], s[4:5], 0, v[72:73]
	v_cvt_pk_bf16_f32 v83, v74, v75
	global_store_dwordx4 v[96:97], v[80:83], off offset:256
	s_nop 1
	v_lshl_add_u64 v[80:81], v[72:73], 0, v[178:179]
	v_cvt_pk_bf16_f32 v72, v84, v85
	v_cvt_pk_bf16_f32 v73, v86, v87
	v_cvt_pk_bf16_f32 v74, v76, v77
	v_cvt_pk_bf16_f32 v75, v78, v79
	global_store_dwordx4 v[80:81], v[72:75], off
	v_cvt_pk_bf16_f32 v68, v68, v69
	v_cvt_pk_bf16_f32 v69, v70, v71
	v_cvt_pk_bf16_f32 v70, v64, v65
	v_add_u32_e32 v64, 0x80, v128
	v_ashrrev_i32_e32 v65, 31, v64
	v_lshlrev_b64 v[64:65], 12, v[64:65]
	v_lshl_add_u64 v[64:65], s[4:5], 0, v[64:65]
	v_lshl_add_u64 v[64:65], v[64:65], 0, v[178:179]
	v_cvt_pk_bf16_f32 v71, v66, v67
	global_store_dwordx4 v[80:81], v[68:71], off offset:256
	v_cvt_pk_bf16_f32 v60, v60, v61
	v_cvt_pk_bf16_f32 v61, v62, v63
	v_cvt_pk_bf16_f32 v62, v56, v57
	v_cvt_pk_bf16_f32 v63, v58, v59
	global_store_dwordx4 v[64:65], v[60:63], off
	v_cvt_pk_bf16_f32 v48, v48, v49
	v_cvt_pk_bf16_f32 v49, v50, v51
	v_cvt_pk_bf16_f32 v50, v40, v41
	v_add_u32_e32 v40, 0x90, v128
	v_ashrrev_i32_e32 v41, 31, v40
	v_lshlrev_b64 v[40:41], 12, v[40:41]
	v_lshl_add_u64 v[40:41], s[4:5], 0, v[40:41]
	v_cvt_pk_bf16_f32 v51, v42, v43
	global_store_dwordx4 v[64:65], v[48:51], off offset:256
	s_nop 1
	v_lshl_add_u64 v[48:49], v[40:41], 0, v[178:179]
	v_cvt_pk_bf16_f32 v40, v52, v53
	v_cvt_pk_bf16_f32 v41, v54, v55
	v_cvt_pk_bf16_f32 v42, v44, v45
	v_cvt_pk_bf16_f32 v43, v46, v47
	global_store_dwordx4 v[48:49], v[40:43], off
	v_cvt_pk_bf16_f32 v32, v32, v33
	v_cvt_pk_bf16_f32 v33, v34, v35
	v_cvt_pk_bf16_f32 v34, v24, v25
	v_add_u32_e32 v24, 0xa0, v128
	v_ashrrev_i32_e32 v25, 31, v24
	v_lshlrev_b64 v[24:25], 12, v[24:25]
	v_lshl_add_u64 v[24:25], s[4:5], 0, v[24:25]
	v_cvt_pk_bf16_f32 v35, v26, v27
	global_store_dwordx4 v[48:49], v[32:35], off offset:256
	s_nop 1
	v_lshl_add_u64 v[32:33], v[24:25], 0, v[178:179]
	v_cvt_pk_bf16_f32 v24, v36, v37
	v_cvt_pk_bf16_f32 v25, v38, v39
	v_cvt_pk_bf16_f32 v26, v28, v29
	v_cvt_pk_bf16_f32 v27, v30, v31
	global_store_dwordx4 v[32:33], v[24:27], off
	v_cvt_pk_bf16_f32 v16, v16, v17
	v_cvt_pk_bf16_f32 v17, v18, v19
	v_cvt_pk_bf16_f32 v18, v8, v9
	v_add_u32_e32 v8, 0xb0, v128
	v_ashrrev_i32_e32 v9, 31, v8
	v_lshlrev_b64 v[8:9], 12, v[8:9]
	v_lshl_add_u64 v[8:9], s[4:5], 0, v[8:9]
	v_cvt_pk_bf16_f32 v19, v10, v11
	global_store_dwordx4 v[32:33], v[16:19], off offset:256
	v_readlane_b32 s4, v255, 8
	s_nop 0
	v_lshl_add_u64 v[16:17], v[8:9], 0, v[178:179]
	v_cvt_pk_bf16_f32 v8, v20, v21
	v_cvt_pk_bf16_f32 v9, v22, v23
	v_cvt_pk_bf16_f32 v10, v12, v13
	v_cvt_pk_bf16_f32 v11, v14, v15
	global_store_dwordx4 v[16:17], v[8:11], off
	v_cvt_pk_bf16_f32 v4, v4, v5
	v_cvt_pk_bf16_f32 v5, v6, v7
	v_cvt_pk_bf16_f32 v6, v0, v1
	v_cvt_pk_bf16_f32 v7, v2, v3
	global_store_dwordx4 v[16:17], v[4:7], off offset:256
	s_waitcnt vmcnt(0)
	s_cmp_lt_u32 s4, 4
	s_cbranch_scc0 .LBB0_946
	s_barrier

.LBB0_1073:
	v_readlane_b32 s6, v255, 20
	v_readlane_b32 s7, v255, 21
	s_lshl_b64 s[6:7], s[6:7], 2
	s_add_u32 s5, s88, s6
	s_addc_u32 s6, s89, s7
	v_bfe_u32 v18, v16, 4, 2
	s_add_u32 s35, s5, 0xc344000
	v_and_b32_e32 v17, 15, v16
	v_lshlrev_b32_e32 v19, 4, v18
	v_lshlrev_b32_e32 v16, 2, v16
	s_addc_u32 s39, s6, 0
	v_lshl_or_b32 v156, s4, 6, v17
	v_lshl_or_b32 v17, v17, 6, v19
	s_lshl_b32 s4, s4, 13
	v_and_b32_e32 v16, 32, v16
	v_bitop3_b32 v19, v17, s4, v16 bitop3:0xde
	s_lshl_b32 s4, s86, 5
	s_and_b32 s6, s4, 0x60
	s_add_i32 m0, s29, 0x18000
	v_lshl_add_u64 v[6:7], v[6:7], 0, s[54:55]
	s_lshl_b32 s4, s6, 7
	s_waitcnt vmcnt(4)
	s_barrier
	global_load_lds_dwordx4 v[6:7], off
	v_lshl_add_u64 v[4:5], v[4:5], 0, s[54:55]
	s_add_i32 m0, s29, 0x1a000
	s_add_i32 s56, s29, 0x8000
	s_add_i32 s57, s29, 0xa000
	v_bitop3_b32 v157, v17, s4, v16 bitop3:0xde
	global_load_lds_dwordx4 v[4:5], off
	v_lshl_add_u64 v[2:3], v[2:3], 0, s[54:55]
	s_mov_b32 m0, s56
	s_add_u32 s4, s18, 0x80080
	global_load_lds_dwordx4 v[2:3], off
	v_lshl_add_u64 v[0:1], v[0:1], 0, s[54:55]
	s_mov_b32 m0, s57
	s_addc_u32 s5, s19, 0
	global_load_lds_dwordx4 v[0:1], off
	s_add_i32 m0, s29, 0x1c000
	global_load_lds_dwordx4 v178, s[4:5]
	v_lshl_add_u64 v[0:1], s[4:5], 0, v[144:145]
	s_add_i32 m0, s29, 0x1e000
	s_mov_b64 s[4:5], 0x80080
	global_load_lds_dwordx4 v[0:1], off
	v_lshlrev_b32_e32 v0, 14, v8
	v_and_b32_e32 v0, 0x7fff8000, v0
	v_lshl_add_u32 v0, v9, 11, v0
	v_or_b32_e32 v0, v0, v10
	v_add_lshl_u32 v0, v0, v11, 1
	v_mov_b32_e32 v1, v179
	v_lshl_add_u64 v[146:147], v[0:1], 0, s[4:5]
	v_lshlrev_b32_e32 v0, 14, v12
	v_and_b32_e32 v0, 0x7fff8000, v0
	v_lshl_add_u32 v0, v13, 11, v0
	s_waitcnt vmcnt(6)
	v_or_b32_e32 v0, v0, v14
	v_add_lshl_u32 v0, v0, v15, 1
	v_lshl_or_b32 v158, v18, 2, s6
	v_lshl_add_u64 v[148:149], v[0:1], 0, s[4:5]
	s_mov_b32 s58, 0
	v_add_u32_e32 v159, 0, v19
	s_barrier

.LBB0_1077:
	s_add_u32 s18, s16, 0x100
	s_addc_u32 s19, s17, 0
	s_add_i32 s66, 0, 0x10000
	v_add_u32_e32 v140, s66, v157
	ds_read_b128 v[128:131], v140
	ds_read_b128 v[132:135], v140 offset:1024
	ds_read_b128 v[136:139], v140 offset:2048
	ds_read_b128 v[140:143], v140 offset:3072
	s_cmp_eq_u32 s63, 28
	s_cselect_b32 s23, s13, s19
	s_cselect_b32 s22, s12, s18
	s_cselect_b32 s21, s15, s62
	s_cselect_b32 s20, s14, s5
	v_lshl_add_u64 v[154:155], s[16:17], 0, v[148:149]
	s_add_i32 m0, s29, 0xc000
	ds_read_b128 v[150:153], v159
	ds_read_b128 v[160:163], v159 offset:1024
	ds_read_b128 v[164:167], v159 offset:2048
	ds_read_b128 v[168:171], v159 offset:3072
	ds_read_b128 v[172:175], v159 offset:4096
	ds_read_b128 v[180:183], v159 offset:5120
	ds_read_b128 v[184:187], v159 offset:6144
	ds_read_b128 v[188:191], v159 offset:7168
	global_load_lds_dwordx4 v[154:155], off
	v_lshl_add_u64 v[154:155], s[16:17], 0, v[146:147]
	s_add_i32 m0, s29, 0xe000
	s_nop 0
	global_load_lds_dwordx4 v[154:155], off
	s_waitcnt lgkmcnt(8)
	s_barrier
	s_waitcnt lgkmcnt(0)
	s_setprio 1
	s_waitcnt lgkmcnt(0)
	v_mfma_f32_16x16x32_bf16 v[124:127], v[128:131], v[150:153], v[124:127]
	v_mfma_f32_16x16x32_bf16 v[120:123], v[136:139], v[150:153], v[120:123]
	v_mfma_f32_16x16x32_bf16 v[108:111], v[128:131], v[164:167], v[108:111]
	v_mfma_f32_16x16x32_bf16 v[104:107], v[136:139], v[164:167], v[104:107]
	v_mfma_f32_16x16x32_bf16 v[92:95], v[128:131], v[172:175], v[92:95]
	v_mfma_f32_16x16x32_bf16 v[88:91], v[136:139], v[172:175], v[88:91]
	v_mfma_f32_16x16x32_bf16 v[76:79], v[128:131], v[184:187], v[76:79]
	v_mfma_f32_16x16x32_bf16 v[72:75], v[136:139], v[184:187], v[72:75]
	v_mfma_f32_16x16x32_bf16 v[124:127], v[132:135], v[160:163], v[124:127]
	v_mfma_f32_16x16x32_bf16 v[120:123], v[140:143], v[160:163], v[120:123]
	v_mfma_f32_16x16x32_bf16 v[108:111], v[132:135], v[168:171], v[108:111]
	v_mfma_f32_16x16x32_bf16 v[104:107], v[140:143], v[168:171], v[104:107]
	v_mfma_f32_16x16x32_bf16 v[92:95], v[132:135], v[180:183], v[92:95]
	v_mfma_f32_16x16x32_bf16 v[88:91], v[140:143], v[180:183], v[88:91]
	v_mfma_f32_16x16x32_bf16 v[76:79], v[132:135], v[188:191], v[76:79]
	v_mfma_f32_16x16x32_bf16 v[72:75], v[140:143], v[188:191], v[72:75]
	s_setprio 0
	s_barrier
	s_add_i32 s67, 0, 0x14000
	v_add_u32_e32 v154, s67, v157
	s_add_i32 s16, s66, s28
	ds_read_b128 v[192:195], v154
	ds_read_b128 v[196:199], v154 offset:1024
	ds_read_b128 v[204:207], v154 offset:2048
	ds_read_b128 v[212:215], v154 offset:3072
	v_lshl_add_u64 v[154:155], s[20:21], 0, v[178:179]
	s_mov_b32 m0, s16
	v_lshl_add_u64 v[176:177], s[20:21], 0, v[144:145]
	global_load_lds_dwordx4 v[154:155], off
	s_add_i32 m0, s16, 0x2000
	s_nop 0
	global_load_lds_dwordx4 v[176:177], off
	s_barrier
	s_waitcnt lgkmcnt(0)
	s_setprio 1
	s_waitcnt lgkmcnt(0)
	v_mfma_f32_16x16x32_bf16 v[116:119], v[192:195], v[150:153], v[116:119]
	v_mfma_f32_16x16x32_bf16 v[112:115], v[204:207], v[150:153], v[112:115]
	v_mfma_f32_16x16x32_bf16 v[100:103], v[192:195], v[164:167], v[100:103]
	v_mfma_f32_16x16x32_bf16 v[96:99], v[204:207], v[164:167], v[96:99]
	v_mfma_f32_16x16x32_bf16 v[84:87], v[192:195], v[172:175], v[84:87]
	v_mfma_f32_16x16x32_bf16 v[80:83], v[204:207], v[172:175], v[80:83]
	v_mfma_f32_16x16x32_bf16 v[68:71], v[192:195], v[184:187], v[68:71]
	v_mfma_f32_16x16x32_bf16 v[64:67], v[204:207], v[184:187], v[64:67]
	v_mfma_f32_16x16x32_bf16 v[116:119], v[196:199], v[160:163], v[116:119]
	v_mfma_f32_16x16x32_bf16 v[112:115], v[212:215], v[160:163], v[112:115]
	v_mfma_f32_16x16x32_bf16 v[100:103], v[196:199], v[168:171], v[100:103]
	v_mfma_f32_16x16x32_bf16 v[96:99], v[212:215], v[168:171], v[96:99]
	v_mfma_f32_16x16x32_bf16 v[84:87], v[196:199], v[180:183], v[84:87]
	v_mfma_f32_16x16x32_bf16 v[80:83], v[212:215], v[180:183], v[80:83]
	v_mfma_f32_16x16x32_bf16 v[68:71], v[196:199], v[188:191], v[68:71]
	v_mfma_f32_16x16x32_bf16 v[64:67], v[212:215], v[188:191], v[64:67]
	s_setprio 0
	s_mov_b32 m0, s29
	v_lshl_add_u64 v[224:225], s[22:23], 0, v[178:179]
	s_barrier
	ds_read_b128 v[150:153], v159 offset:16384
	ds_read_b128 v[160:163], v159 offset:17408
	ds_read_b128 v[164:167], v159 offset:18432
	ds_read_b128 v[168:171], v159 offset:19456
	ds_read_b128 v[172:175], v159 offset:20480
	ds_read_b128 v[180:183], v159 offset:21504
	ds_read_b128 v[184:187], v159 offset:22528
	ds_read_b128 v[188:191], v159 offset:23552
	global_load_lds_dwordx4 v[224:225], off
	v_lshl_add_u64 v[226:227], s[22:23], 0, v[144:145]
	s_mov_b32 m0, s30
	s_nop 0
	global_load_lds_dwordx4 v[226:227], off
	s_barrier
	s_waitcnt lgkmcnt(0)
	s_setprio 1
	s_waitcnt lgkmcnt(0)
	v_mfma_f32_16x16x32_bf16 v[60:63], v[128:131], v[150:153], v[60:63]
	v_mfma_f32_16x16x32_bf16 v[56:59], v[136:139], v[150:153], v[56:59]
	v_mfma_f32_16x16x32_bf16 v[44:47], v[128:131], v[164:167], v[44:47]
	v_mfma_f32_16x16x32_bf16 v[40:43], v[136:139], v[164:167], v[40:43]
	v_mfma_f32_16x16x32_bf16 v[28:31], v[128:131], v[172:175], v[28:31]
	v_mfma_f32_16x16x32_bf16 v[24:27], v[136:139], v[172:175], v[24:27]
	v_mfma_f32_16x16x32_bf16 v[12:15], v[128:131], v[184:187], v[12:15]
	v_mfma_f32_16x16x32_bf16 v[8:11], v[136:139], v[184:187], v[8:11]
	v_mfma_f32_16x16x32_bf16 v[60:63], v[132:135], v[160:163], v[60:63]
	v_mfma_f32_16x16x32_bf16 v[56:59], v[140:143], v[160:163], v[56:59]
	v_mfma_f32_16x16x32_bf16 v[44:47], v[132:135], v[168:171], v[44:47]
	v_mfma_f32_16x16x32_bf16 v[40:43], v[140:143], v[168:171], v[40:43]
	v_mfma_f32_16x16x32_bf16 v[28:31], v[132:135], v[180:183], v[28:31]
	v_mfma_f32_16x16x32_bf16 v[24:27], v[140:143], v[180:183], v[24:27]
	v_mfma_f32_16x16x32_bf16 v[12:15], v[132:135], v[188:191], v[12:15]
	v_mfma_f32_16x16x32_bf16 v[8:11], v[140:143], v[188:191], v[8:11]
	s_setprio 0
	s_barrier
	s_add_u32 s16, s20, 0x80000
	s_addc_u32 s17, s21, 0
	s_add_i32 s66, s67, s28
	s_mov_b32 m0, s66
	s_nop 0
	global_load_lds_dwordx4 v178, s[16:17]
	s_add_i32 m0, s66, 0x2000
	s_nop 0
	global_load_lds_dwordx4 v144, s[16:17]
	s_waitcnt vmcnt(6)
	s_barrier
	s_setprio 1
	v_mfma_f32_16x16x32_bf16 v[52:55], v[192:195], v[150:153], v[52:55]
	v_mfma_f32_16x16x32_bf16 v[48:51], v[204:207], v[150:153], v[48:51]
	v_mfma_f32_16x16x32_bf16 v[36:39], v[192:195], v[164:167], v[36:39]
	v_mfma_f32_16x16x32_bf16 v[32:35], v[204:207], v[164:167], v[32:35]
	v_mfma_f32_16x16x32_bf16 v[20:23], v[192:195], v[172:175], v[20:23]
	v_mfma_f32_16x16x32_bf16 v[16:19], v[204:207], v[172:175], v[16:19]
	v_mfma_f32_16x16x32_bf16 v[4:7], v[192:195], v[184:187], v[4:7]
	v_mfma_f32_16x16x32_bf16 v[0:3], v[204:207], v[184:187], v[0:3]
	v_mfma_f32_16x16x32_bf16 v[52:55], v[196:199], v[160:163], v[52:55]
	v_mfma_f32_16x16x32_bf16 v[48:51], v[212:215], v[160:163], v[48:51]
	v_mfma_f32_16x16x32_bf16 v[36:39], v[196:199], v[168:171], v[36:39]
	v_mfma_f32_16x16x32_bf16 v[32:35], v[212:215], v[168:171], v[32:35]
	v_mfma_f32_16x16x32_bf16 v[20:23], v[196:199], v[180:183], v[20:23]
	v_mfma_f32_16x16x32_bf16 v[16:19], v[212:215], v[180:183], v[16:19]
	v_mfma_f32_16x16x32_bf16 v[4:7], v[196:199], v[188:191], v[4:7]
	v_mfma_f32_16x16x32_bf16 v[0:3], v[212:215], v[188:191], v[0:3]
	s_setprio 0
	s_add_i32 s66, 0, 0x18000
	v_add_u32_e32 v140, s66, v157
	s_barrier
	ds_read_b128 v[128:131], v140
	ds_read_b128 v[132:135], v140 offset:1024
	ds_read_b128 v[136:139], v140 offset:2048
	ds_read_b128 v[140:143], v140 offset:3072
	s_add_u32 s16, s22, 0x80000
	s_addc_u32 s17, s23, 0
	s_mov_b32 m0, s31
	ds_read_b128 v[150:153], v159 offset:32768
	ds_read_b128 v[160:163], v159 offset:33792
	ds_read_b128 v[164:167], v159 offset:34816
	ds_read_b128 v[168:171], v159 offset:35840
	ds_read_b128 v[172:175], v159 offset:36864
	ds_read_b128 v[180:183], v159 offset:37888
	ds_read_b128 v[184:187], v159 offset:38912
	ds_read_b128 v[188:191], v159 offset:39936
	global_load_lds_dwordx4 v178, s[16:17]
	s_mov_b32 m0, s34
	s_nop 0
	global_load_lds_dwordx4 v144, s[16:17]
	s_waitcnt lgkmcnt(8)
	s_barrier
	s_waitcnt lgkmcnt(0)
	s_setprio 1
	s_waitcnt lgkmcnt(0)
	v_mfma_f32_16x16x32_bf16 v[124:127], v[128:131], v[150:153], v[124:127]
	v_mfma_f32_16x16x32_bf16 v[120:123], v[136:139], v[150:153], v[120:123]
	v_mfma_f32_16x16x32_bf16 v[108:111], v[128:131], v[164:167], v[108:111]
	v_mfma_f32_16x16x32_bf16 v[104:107], v[136:139], v[164:167], v[104:107]
	v_mfma_f32_16x16x32_bf16 v[92:95], v[128:131], v[172:175], v[92:95]
	v_mfma_f32_16x16x32_bf16 v[88:91], v[136:139], v[172:175], v[88:91]
	v_mfma_f32_16x16x32_bf16 v[76:79], v[128:131], v[184:187], v[76:79]
	v_mfma_f32_16x16x32_bf16 v[72:75], v[136:139], v[184:187], v[72:75]
	v_mfma_f32_16x16x32_bf16 v[124:127], v[132:135], v[160:163], v[124:127]
	v_mfma_f32_16x16x32_bf16 v[120:123], v[140:143], v[160:163], v[120:123]
	v_mfma_f32_16x16x32_bf16 v[108:111], v[132:135], v[168:171], v[108:111]
	v_mfma_f32_16x16x32_bf16 v[104:107], v[140:143], v[168:171], v[104:107]
	v_mfma_f32_16x16x32_bf16 v[92:95], v[132:135], v[180:183], v[92:95]
	v_mfma_f32_16x16x32_bf16 v[88:91], v[140:143], v[180:183], v[88:91]
	v_mfma_f32_16x16x32_bf16 v[76:79], v[132:135], v[188:191], v[76:79]
	v_mfma_f32_16x16x32_bf16 v[72:75], v[140:143], v[188:191], v[72:75]
	s_setprio 0
	s_barrier
	s_add_i32 s22, 0, 0x1c000
	s_add_i32 s16, s66, s28
	v_add_u32_e32 v212, s22, v157
	v_lshl_add_u64 v[154:155], v[154:155], 0, s[54:55]
	s_mov_b32 m0, s16
	ds_read_b128 v[192:195], v212
	ds_read_b128 v[196:199], v212 offset:1024
	ds_read_b128 v[204:207], v212 offset:2048
	ds_read_b128 v[212:215], v212 offset:3072
	global_load_lds_dwordx4 v[154:155], off
	v_lshl_add_u64 v[154:155], v[176:177], 0, s[54:55]
	s_add_i32 m0, s16, 0x2000
	s_nop 0
	global_load_lds_dwordx4 v[154:155], off
	s_barrier
	s_waitcnt lgkmcnt(0)
	s_setprio 1
	s_waitcnt lgkmcnt(0)
	v_mfma_f32_16x16x32_bf16 v[116:119], v[192:195], v[150:153], v[116:119]
	v_mfma_f32_16x16x32_bf16 v[112:115], v[204:207], v[150:153], v[112:115]
	v_mfma_f32_16x16x32_bf16 v[100:103], v[192:195], v[164:167], v[100:103]
	v_mfma_f32_16x16x32_bf16 v[96:99], v[204:207], v[164:167], v[96:99]
	v_mfma_f32_16x16x32_bf16 v[84:87], v[192:195], v[172:175], v[84:87]
	v_mfma_f32_16x16x32_bf16 v[80:83], v[204:207], v[172:175], v[80:83]
	v_mfma_f32_16x16x32_bf16 v[68:71], v[192:195], v[184:187], v[68:71]
	v_mfma_f32_16x16x32_bf16 v[64:67], v[204:207], v[184:187], v[64:67]
	v_mfma_f32_16x16x32_bf16 v[116:119], v[196:199], v[160:163], v[116:119]
	v_mfma_f32_16x16x32_bf16 v[112:115], v[212:215], v[160:163], v[112:115]
	v_mfma_f32_16x16x32_bf16 v[100:103], v[196:199], v[168:171], v[100:103]
	v_mfma_f32_16x16x32_bf16 v[96:99], v[212:215], v[168:171], v[96:99]
	v_mfma_f32_16x16x32_bf16 v[84:87], v[196:199], v[180:183], v[84:87]
	v_mfma_f32_16x16x32_bf16 v[80:83], v[212:215], v[180:183], v[80:83]
	v_mfma_f32_16x16x32_bf16 v[68:71], v[196:199], v[188:191], v[68:71]
	v_mfma_f32_16x16x32_bf16 v[64:67], v[212:215], v[188:191], v[64:67]
	s_setprio 0
	s_mov_b32 m0, s56
	v_lshl_add_u64 v[154:155], v[224:225], 0, s[54:55]
	s_barrier
	ds_read_b128 v[150:153], v159 offset:49152
	ds_read_b128 v[160:163], v159 offset:50176
	ds_read_b128 v[164:167], v159 offset:51200
	ds_read_b128 v[168:171], v159 offset:52224
	ds_read_b128 v[172:175], v159 offset:53248
	ds_read_b128 v[180:183], v159 offset:54272
	ds_read_b128 v[184:187], v159 offset:55296
	ds_read_b128 v[188:191], v159 offset:56320
	global_load_lds_dwordx4 v[154:155], off
	v_lshl_add_u64 v[154:155], v[226:227], 0, s[54:55]
	s_mov_b32 m0, s57
	s_nop 0
	global_load_lds_dwordx4 v[154:155], off
	s_barrier
	s_waitcnt lgkmcnt(0)
	s_setprio 1
	s_waitcnt lgkmcnt(0)
	v_mfma_f32_16x16x32_bf16 v[60:63], v[128:131], v[150:153], v[60:63]
	v_mfma_f32_16x16x32_bf16 v[56:59], v[136:139], v[150:153], v[56:59]
	v_mfma_f32_16x16x32_bf16 v[44:47], v[128:131], v[164:167], v[44:47]
	v_mfma_f32_16x16x32_bf16 v[40:43], v[136:139], v[164:167], v[40:43]
	v_mfma_f32_16x16x32_bf16 v[28:31], v[128:131], v[172:175], v[28:31]
	v_mfma_f32_16x16x32_bf16 v[24:27], v[136:139], v[172:175], v[24:27]
	v_mfma_f32_16x16x32_bf16 v[12:15], v[128:131], v[184:187], v[12:15]
	v_mfma_f32_16x16x32_bf16 v[8:11], v[136:139], v[184:187], v[8:11]
	v_mfma_f32_16x16x32_bf16 v[60:63], v[132:135], v[160:163], v[60:63]
	v_mfma_f32_16x16x32_bf16 v[56:59], v[140:143], v[160:163], v[56:59]
	v_mfma_f32_16x16x32_bf16 v[44:47], v[132:135], v[168:171], v[44:47]
	v_mfma_f32_16x16x32_bf16 v[40:43], v[140:143], v[168:171], v[40:43]
	v_mfma_f32_16x16x32_bf16 v[28:31], v[132:135], v[180:183], v[28:31]
	v_mfma_f32_16x16x32_bf16 v[24:27], v[140:143], v[180:183], v[24:27]
	v_mfma_f32_16x16x32_bf16 v[12:15], v[132:135], v[188:191], v[12:15]
	v_mfma_f32_16x16x32_bf16 v[8:11], v[140:143], v[188:191], v[8:11]
	s_setprio 0
	s_barrier
	s_add_u32 s16, s20, 0x80080
	s_addc_u32 s17, s21, 0
	s_add_i32 s20, s22, s28
	s_mov_b32 m0, s20
	s_nop 0
	global_load_lds_dwordx4 v178, s[16:17]
	s_add_i32 m0, s20, 0x2000
	s_nop 0
	global_load_lds_dwordx4 v144, s[16:17]
	s_waitcnt vmcnt(6)
	s_barrier
	s_setprio 1
	v_mfma_f32_16x16x32_bf16 v[52:55], v[192:195], v[150:153], v[52:55]
	v_mfma_f32_16x16x32_bf16 v[48:51], v[204:207], v[150:153], v[48:51]
	v_mfma_f32_16x16x32_bf16 v[36:39], v[192:195], v[164:167], v[36:39]
	v_mfma_f32_16x16x32_bf16 v[32:35], v[204:207], v[164:167], v[32:35]
	v_mfma_f32_16x16x32_bf16 v[20:23], v[192:195], v[172:175], v[20:23]
	v_mfma_f32_16x16x32_bf16 v[16:19], v[204:207], v[172:175], v[16:19]
	v_mfma_f32_16x16x32_bf16 v[4:7], v[192:195], v[184:187], v[4:7]
	v_mfma_f32_16x16x32_bf16 v[0:3], v[204:207], v[184:187], v[0:3]
	v_mfma_f32_16x16x32_bf16 v[52:55], v[196:199], v[160:163], v[52:55]
	v_mfma_f32_16x16x32_bf16 v[48:51], v[212:215], v[160:163], v[48:51]
	v_mfma_f32_16x16x32_bf16 v[36:39], v[196:199], v[168:171], v[36:39]
	v_mfma_f32_16x16x32_bf16 v[32:35], v[212:215], v[168:171], v[32:35]
	v_mfma_f32_16x16x32_bf16 v[20:23], v[196:199], v[180:183], v[20:23]
	v_mfma_f32_16x16x32_bf16 v[16:19], v[212:215], v[180:183], v[16:19]
	v_mfma_f32_16x16x32_bf16 v[4:7], v[196:199], v[188:191], v[4:7]
	v_mfma_f32_16x16x32_bf16 v[0:3], v[212:215], v[188:191], v[0:3]
	s_setprio 0
	s_add_i32 s63, s63, 2
	s_add_u32 s5, s5, 0x100
	s_addc_u32 s62, s62, 0
	s_cmp_gt_u32 s63, 29
	s_mov_b64 s[16:17], s[18:19]
	s_barrier
	s_cbranch_scc0 .LBB0_1077
	s_lshl_b32 s5, s60, 8
	s_add_i32 s12, s5, 0xfffff000
	s_ashr_i32 s12, s12, 11
	s_add_i32 s12, s12, 1
	s_cmp_lt_i32 s60, 16
	s_cselect_b32 s12, 0, s12
	v_add_u32_e32 v154, s5, v156
	v_lshl_or_b32 v152, s61, 8, v158
	s_mul_hi_i32 s15, s12, 0xc000
	s_mul_i32 s14, s12, 0xc000
	v_readlane_b32 s12, v254, 59
	v_readlane_b32 s13, v254, 63
	v_ashrrev_i32_e32 v155, 31, v154
	s_cselect_b32 s13, s12, s13
	v_readlane_b32 s12, v254, 61
	v_readlane_b32 s16, v255, 1
	v_ashrrev_i32_e32 v153, 31, v152
	v_lshlrev_b64 v[150:151], 11, v[154:155]
	s_cselect_b32 s12, s12, s16
	s_add_u32 s14, s35, s14
	v_lshl_add_u64 v[150:151], v[150:151], 0, v[152:153]
	s_addc_u32 s15, s39, s15
	v_lshlrev_b64 v[150:151], 2, v[150:151]
	v_lshl_add_u64 v[128:129], v[152:153], 2, s[14:15]
	v_lshl_add_u64 v[166:167], s[12:13], 0, v[150:151]
	global_load_dwordx4 v[140:143], v[128:129], off
	global_load_dwordx4 v[136:139], v[128:129], off offset:64
	global_load_dwordx4 v[132:135], v[128:129], off offset:512
	s_nop 0
	global_load_dwordx4 v[128:131], v[128:129], off offset:576
	v_readlane_b32 s68, v252, 37
	global_load_dwordx4 v[160:163], v[166:167], off
	v_readlane_b32 s82, v252, 51
	v_readlane_b32 s83, v252, 52
	s_mov_b64 s[14:15], 0x100000
	s_and_b64 vcc, exec, s[10:11]
	v_lshl_add_u64 v[164:165], s[82:83], 0, v[150:151]
	s_mov_b32 s61, s59
	s_mov_b32 s60, s4
	s_mov_b64 s[18:19], s[6:7]
	s_mov_b64 s[16:17], s[8:9]
	v_readlane_b32 s69, v252, 38
	v_readlane_b32 s70, v252, 39
	v_readlane_b32 s71, v252, 40
	v_readlane_b32 s72, v252, 41
	v_readlane_b32 s73, v252, 42
	v_readlane_b32 s74, v252, 43
	v_readlane_b32 s75, v252, 44
	v_readlane_b32 s76, v252, 45
	v_readlane_b32 s77, v252, 46
	v_readlane_b32 s78, v252, 47
	v_readlane_b32 s79, v252, 48
	v_readlane_b32 s80, v252, 49
	v_readlane_b32 s81, v252, 50
	s_waitcnt vmcnt(0)
	v_pk_fma_f32 v[126:127], v[126:127], v[142:143], v[162:163]
	v_pk_fma_f32 v[124:125], v[124:125], v[140:141], v[160:161]
	global_store_dwordx4 v[164:165], v[124:127], off
	global_load_dwordx4 v[124:127], v[166:167], off offset:64
	s_waitcnt vmcnt(0)
	v_pk_fma_f32 v[122:123], v[122:123], v[138:139], v[126:127]
	v_pk_fma_f32 v[120:121], v[120:121], v[136:137], v[124:125]
	global_store_dwordx4 v[164:165], v[120:123], off offset:64
	global_load_dwordx4 v[120:123], v[166:167], off offset:512
	s_waitcnt vmcnt(0)
	v_pk_fma_f32 v[118:119], v[118:119], v[134:135], v[122:123]
	v_pk_fma_f32 v[116:117], v[116:117], v[132:133], v[120:121]
	global_store_dwordx4 v[164:165], v[116:119], off offset:512
	global_load_dwordx4 v[116:119], v[166:167], off offset:576
	s_waitcnt vmcnt(0)
	v_pk_fma_f32 v[114:115], v[114:115], v[130:131], v[118:119]
	v_pk_fma_f32 v[112:113], v[112:113], v[128:129], v[116:117]
	global_store_dwordx4 v[164:165], v[112:115], off offset:576
	s_nop 1
	v_or_b32_e32 v112, 16, v154
	v_ashrrev_i32_e32 v113, 31, v112
	v_lshlrev_b64 v[112:113], 11, v[112:113]
	v_lshl_add_u64 v[112:113], v[112:113], 0, v[152:153]
	v_lshlrev_b64 v[112:113], 2, v[112:113]
	v_lshl_add_u64 v[118:119], s[12:13], 0, v[112:113]
	v_lshl_add_u64 v[116:117], s[82:83], 0, v[112:113]
	global_load_dwordx4 v[112:115], v[118:119], off
	s_waitcnt vmcnt(0)
	v_pk_fma_f32 v[110:111], v[110:111], v[142:143], v[114:115]
	v_pk_fma_f32 v[108:109], v[108:109], v[140:141], v[112:113]
	global_store_dwordx4 v[116:117], v[108:111], off
	global_load_dwordx4 v[108:111], v[118:119], off offset:64
	s_waitcnt vmcnt(0)
	v_pk_fma_f32 v[106:107], v[106:107], v[138:139], v[110:111]
	v_pk_fma_f32 v[104:105], v[104:105], v[136:137], v[108:109]
	global_store_dwordx4 v[116:117], v[104:107], off offset:64
	global_load_dwordx4 v[104:107], v[118:119], off offset:512
	s_waitcnt vmcnt(0)
	v_pk_fma_f32 v[102:103], v[102:103], v[134:135], v[106:107]
	v_pk_fma_f32 v[100:101], v[100:101], v[132:133], v[104:105]
	global_store_dwordx4 v[116:117], v[100:103], off offset:512
	global_load_dwordx4 v[100:103], v[118:119], off offset:576
	s_waitcnt vmcnt(0)
	v_pk_fma_f32 v[98:99], v[98:99], v[130:131], v[102:103]
	v_pk_fma_f32 v[96:97], v[96:97], v[128:129], v[100:101]
	global_store_dwordx4 v[116:117], v[96:99], off offset:576
	s_nop 1
	v_or_b32_e32 v96, 32, v154
	v_ashrrev_i32_e32 v97, 31, v96
	v_lshlrev_b64 v[96:97], 11, v[96:97]
	v_lshl_add_u64 v[96:97], v[96:97], 0, v[152:153]
	v_lshlrev_b64 v[96:97], 2, v[96:97]
	v_lshl_add_u64 v[102:103], s[12:13], 0, v[96:97]
	v_lshl_add_u64 v[100:101], s[82:83], 0, v[96:97]
	global_load_dwordx4 v[96:99], v[102:103], off
	s_waitcnt vmcnt(0)
	v_pk_fma_f32 v[94:95], v[94:95], v[142:143], v[98:99]
	v_pk_fma_f32 v[92:93], v[92:93], v[140:141], v[96:97]
	global_store_dwordx4 v[100:101], v[92:95], off
	global_load_dwordx4 v[92:95], v[102:103], off offset:64
	s_waitcnt vmcnt(0)
	v_pk_fma_f32 v[90:91], v[90:91], v[138:139], v[94:95]
	v_pk_fma_f32 v[88:89], v[88:89], v[136:137], v[92:93]
	global_store_dwordx4 v[100:101], v[88:91], off offset:64
	global_load_dwordx4 v[88:91], v[102:103], off offset:512
	s_waitcnt vmcnt(0)
	v_pk_fma_f32 v[86:87], v[86:87], v[134:135], v[90:91]
	v_pk_fma_f32 v[84:85], v[84:85], v[132:133], v[88:89]
	global_store_dwordx4 v[100:101], v[84:87], off offset:512
	global_load_dwordx4 v[84:87], v[102:103], off offset:576
	s_waitcnt vmcnt(0)
	v_pk_fma_f32 v[82:83], v[82:83], v[130:131], v[86:87]
	v_pk_fma_f32 v[80:81], v[80:81], v[128:129], v[84:85]
	global_store_dwordx4 v[100:101], v[80:83], off offset:576
	s_nop 1
	v_or_b32_e32 v80, 48, v154
	v_ashrrev_i32_e32 v81, 31, v80
	v_lshlrev_b64 v[80:81], 11, v[80:81]
	v_lshl_add_u64 v[80:81], v[80:81], 0, v[152:153]
	v_lshlrev_b64 v[80:81], 2, v[80:81]
	v_lshl_add_u64 v[86:87], s[12:13], 0, v[80:81]
	v_lshl_add_u64 v[84:85], s[82:83], 0, v[80:81]
	global_load_dwordx4 v[80:83], v[86:87], off
	s_waitcnt vmcnt(0)
	v_pk_fma_f32 v[78:79], v[78:79], v[142:143], v[82:83]
	v_pk_fma_f32 v[76:77], v[76:77], v[140:141], v[80:81]
	global_store_dwordx4 v[84:85], v[76:79], off
	global_load_dwordx4 v[76:79], v[86:87], off offset:64
	s_waitcnt vmcnt(0)
	v_pk_fma_f32 v[74:75], v[74:75], v[138:139], v[78:79]
	v_pk_fma_f32 v[72:73], v[72:73], v[136:137], v[76:77]
	global_store_dwordx4 v[84:85], v[72:75], off offset:64
	global_load_dwordx4 v[72:75], v[86:87], off offset:512
	s_waitcnt vmcnt(0)
	v_pk_fma_f32 v[70:71], v[70:71], v[134:135], v[74:75]
	v_pk_fma_f32 v[68:69], v[68:69], v[132:133], v[72:73]
	global_store_dwordx4 v[84:85], v[68:71], off offset:512
	global_load_dwordx4 v[68:71], v[86:87], off offset:576
	s_waitcnt vmcnt(0)
	v_pk_fma_f32 v[66:67], v[66:67], v[130:131], v[70:71]
	v_pk_fma_f32 v[64:65], v[64:65], v[128:129], v[68:69]
	global_store_dwordx4 v[84:85], v[64:67], off offset:576
	s_nop 1
	v_lshl_add_u64 v[64:65], v[150:151], 0, s[14:15]
	v_lshl_add_u64 v[70:71], s[12:13], 0, v[64:65]
	v_lshl_add_u64 v[68:69], s[82:83], 0, v[64:65]
	global_load_dwordx4 v[64:67], v[70:71], off
	s_mov_b64 s[14:15], 0x120000
	s_waitcnt vmcnt(0)
	v_pk_fma_f32 v[62:63], v[62:63], v[142:143], v[66:67]
	v_pk_fma_f32 v[60:61], v[60:61], v[140:141], v[64:65]
	global_store_dwordx4 v[68:69], v[60:63], off
	global_load_dwordx4 v[60:63], v[70:71], off offset:64
	s_waitcnt vmcnt(0)
	v_pk_fma_f32 v[58:59], v[58:59], v[138:139], v[62:63]
	v_pk_fma_f32 v[56:57], v[56:57], v[136:137], v[60:61]
	global_store_dwordx4 v[68:69], v[56:59], off offset:64
	global_load_dwordx4 v[56:59], v[70:71], off offset:512
	s_waitcnt vmcnt(0)
	v_pk_fma_f32 v[54:55], v[54:55], v[134:135], v[58:59]
	v_pk_fma_f32 v[52:53], v[52:53], v[132:133], v[56:57]
	global_store_dwordx4 v[68:69], v[52:55], off offset:512
	global_load_dwordx4 v[52:55], v[70:71], off offset:576
	s_waitcnt vmcnt(0)
	v_pk_fma_f32 v[50:51], v[50:51], v[130:131], v[54:55]
	v_pk_fma_f32 v[48:49], v[48:49], v[128:129], v[52:53]
	global_store_dwordx4 v[68:69], v[48:51], off offset:576
	s_nop 1
	v_lshl_add_u64 v[48:49], v[150:151], 0, s[14:15]
	v_lshl_add_u64 v[54:55], s[12:13], 0, v[48:49]
	v_lshl_add_u64 v[52:53], s[82:83], 0, v[48:49]
	global_load_dwordx4 v[48:51], v[54:55], off
	s_mov_b64 s[14:15], 0x140000
	s_waitcnt vmcnt(0)
	v_pk_fma_f32 v[46:47], v[46:47], v[142:143], v[50:51]
	v_pk_fma_f32 v[44:45], v[44:45], v[140:141], v[48:49]
	global_store_dwordx4 v[52:53], v[44:47], off
	global_load_dwordx4 v[44:47], v[54:55], off offset:64
	s_waitcnt vmcnt(0)
	v_pk_fma_f32 v[42:43], v[42:43], v[138:139], v[46:47]
	v_pk_fma_f32 v[40:41], v[40:41], v[136:137], v[44:45]
	global_store_dwordx4 v[52:53], v[40:43], off offset:64
	global_load_dwordx4 v[40:43], v[54:55], off offset:512
	s_waitcnt vmcnt(0)
	v_pk_fma_f32 v[38:39], v[38:39], v[134:135], v[42:43]
	v_pk_fma_f32 v[36:37], v[36:37], v[132:133], v[40:41]
	global_store_dwordx4 v[52:53], v[36:39], off offset:512
	global_load_dwordx4 v[36:39], v[54:55], off offset:576
	s_waitcnt vmcnt(0)
	v_pk_fma_f32 v[34:35], v[34:35], v[130:131], v[38:39]
	v_pk_fma_f32 v[32:33], v[32:33], v[128:129], v[36:37]
	global_store_dwordx4 v[52:53], v[32:35], off offset:576
	s_nop 1
	v_lshl_add_u64 v[32:33], v[150:151], 0, s[14:15]
	v_lshl_add_u64 v[38:39], s[12:13], 0, v[32:33]
	v_lshl_add_u64 v[36:37], s[82:83], 0, v[32:33]
	global_load_dwordx4 v[32:35], v[38:39], off
	s_mov_b64 s[14:15], 0x160000
	s_waitcnt vmcnt(0)
	v_pk_fma_f32 v[30:31], v[30:31], v[142:143], v[34:35]
	v_pk_fma_f32 v[28:29], v[28:29], v[140:141], v[32:33]
	global_store_dwordx4 v[36:37], v[28:31], off
	global_load_dwordx4 v[28:31], v[38:39], off offset:64
	s_waitcnt vmcnt(0)
	v_pk_fma_f32 v[26:27], v[26:27], v[138:139], v[30:31]
	v_pk_fma_f32 v[24:25], v[24:25], v[136:137], v[28:29]
	global_store_dwordx4 v[36:37], v[24:27], off offset:64
	global_load_dwordx4 v[24:27], v[38:39], off offset:512
	s_waitcnt vmcnt(0)
	v_pk_fma_f32 v[22:23], v[22:23], v[134:135], v[26:27]
	v_pk_fma_f32 v[20:21], v[20:21], v[132:133], v[24:25]
	global_store_dwordx4 v[36:37], v[20:23], off offset:512
	global_load_dwordx4 v[20:23], v[38:39], off offset:576
	s_waitcnt vmcnt(0)
	v_pk_fma_f32 v[18:19], v[18:19], v[130:131], v[22:23]
	v_pk_fma_f32 v[16:17], v[16:17], v[128:129], v[20:21]
	global_store_dwordx4 v[36:37], v[16:19], off offset:576
	s_nop 1
	v_lshl_add_u64 v[16:17], v[150:151], 0, s[14:15]
	v_lshl_add_u64 v[22:23], s[12:13], 0, v[16:17]
	v_lshl_add_u64 v[20:21], s[82:83], 0, v[16:17]
	global_load_dwordx4 v[16:19], v[22:23], off
	s_waitcnt vmcnt(0)
	v_pk_fma_f32 v[14:15], v[14:15], v[142:143], v[18:19]
	v_pk_fma_f32 v[12:13], v[12:13], v[140:141], v[16:17]
	global_store_dwordx4 v[20:21], v[12:15], off
	global_load_dwordx4 v[12:15], v[22:23], off offset:64
	s_waitcnt vmcnt(0)
	v_pk_fma_f32 v[10:11], v[10:11], v[138:139], v[14:15]
	v_pk_fma_f32 v[8:9], v[8:9], v[136:137], v[12:13]
	global_store_dwordx4 v[20:21], v[8:11], off offset:64
	global_load_dwordx4 v[8:11], v[22:23], off offset:512
	s_waitcnt vmcnt(0)
	v_pk_fma_f32 v[6:7], v[6:7], v[134:135], v[10:11]
	v_pk_fma_f32 v[4:5], v[4:5], v[132:133], v[8:9]
	global_store_dwordx4 v[20:21], v[4:7], off offset:512
	global_load_dwordx4 v[4:7], v[22:23], off offset:576
	s_waitcnt vmcnt(0)
	v_pk_fma_f32 v[2:3], v[2:3], v[130:131], v[6:7]
	v_pk_fma_f32 v[0:1], v[0:1], v[128:129], v[4:5]
	global_store_dwordx4 v[20:21], v[0:3], off offset:576
	s_cbranch_vccz .LBB0_1074
	s_waitcnt vmcnt(0)
	s_mov_b32 s4, s86
	s_cmp_gt_u32 s4, 3
	s_mov_b32 s34, 0x10000
	s_movk_i32 s57, 0x404
	s_cbranch_scc1 .LBB0_1081
	s_barrier

.LBB0_1193:
	s_add_u32 s12, s88, 0x1ebdb700
	s_addc_u32 s13, s89, 0
	s_add_u32 s17, s88, 0x114db700
	v_bfe_u32 v224, v12, 4, 2
	s_addc_u32 s18, s89, 0
	v_readlane_b32 s16, v255, 8
	v_and_b32_e32 v223, 15, v12
	s_lshl_b32 s14, s5, 6
	v_lshlrev_b32_e32 v15, 4, v224
	v_lshlrev_b32_e32 v12, 2, v12
	s_and_b32 s7, s16, 3
	v_writelane_b32 v255, s14, 9
	v_lshl_or_b32 v15, v223, 6, v15
	s_lshl_b32 s14, s5, 13
	v_and_b32_e32 v12, 32, v12
	s_add_i32 m0, s84, 0x18000
	v_lshl_add_u64 v[6:7], v[6:7], 0, s[54:55]
	v_bitop3_b32 v16, v15, s14, v12 bitop3:0xde
	s_lshl_b32 s22, s7, 5
	s_lshl_b32 s14, s7, 12
	s_waitcnt vmcnt(4)
	s_barrier
	global_load_lds_dwordx4 v[6:7], off
	v_lshl_add_u64 v[4:5], v[4:5], 0, s[54:55]
	s_add_i32 m0, s84, 0x1a000
	s_add_i32 s59, s84, 0x8000
	s_add_i32 s20, s84, 0xa000
	v_bitop3_b32 v225, v15, s14, v12 bitop3:0xde
	global_load_lds_dwordx4 v[4:5], off
	v_lshl_add_u64 v[2:3], v[2:3], 0, s[54:55]
	s_mov_b32 m0, s59
	s_add_u32 s14, s66, 0x80080
	global_load_lds_dwordx4 v[2:3], off
	v_lshl_add_u64 v[0:1], v[0:1], 0, s[54:55]
	s_mov_b32 m0, s20
	s_addc_u32 s15, s67, 0
	global_load_lds_dwordx4 v[0:1], off
	s_add_i32 m0, s84, 0x1c000
	global_load_lds_dwordx4 v182, s[14:15]
	s_add_i32 m0, s84, 0x1e000
	s_lshl_b32 s5, s5, 11
	global_load_lds_dwordx4 v186, s[14:15]
	s_lshl_b32 s34, s7, 9
	s_xor_b64 s[14:15], s[10:11], -1
	s_cmp_gt_u32 s16, 3
	s_cselect_b64 s[26:27], -1, 0
	v_writelane_b32 v255, s26, 12
	s_cmp_lt_u32 s16, 4
	v_cndmask_b32_e64 v1, 0, 1, s[14:15]
	v_writelane_b32 v255, s27, 13
	s_cselect_b64 s[26:27], -1, 0
	v_cndmask_b32_e64 v0, 0, 1, s[26:27]
	v_writelane_b32 v255, s26, 14
	s_and_b64 s[14:15], s[26:27], exec
	s_cselect_b32 s14, 0, 2
	s_movk_i32 s15, 0x1800
	v_readfirstlane_b32 s19, v0
	s_cselect_b32 s15, s15, 0x1000
	s_or_b32 s14, s14, s19
	v_readfirstlane_b32 s19, v1
	s_or_b32 s6, s6, s19
	s_lshl_b32 s14, s14, 11
	s_lshl_b32 s6, s6, 11
	s_lshl_b32 s7, s7, 7
	v_writelane_b32 v255, s27, 15
	s_add_u32 s16, s17, s7
	v_writelane_b32 v255, s17, 4
	s_addc_u32 s17, s18, 0
	s_add_i32 s7, 0, 0x20000
	v_writelane_b32 v255, s18, 22
	s_add_i32 s19, s7, s5
	s_add_i32 s5, s5, 0
	v_writelane_b32 v255, s16, 23
	s_add_i32 s5, s5, s34
	s_add_i32 s5, s5, 0x21000
	v_writelane_b32 v255, s17, 24
	s_add_i32 s16, s19, s34
	v_writelane_b32 v255, s16, 16
	s_add_u32 s16, s60, 0xac00
	s_addc_u32 s17, s61, 0
	v_writelane_b32 v255, s5, 7
	s_add_u32 s64, s60, 0x15800
	v_writelane_b32 v255, s16, 18
	s_addc_u32 s65, s61, 0
	v_lshlrev_b32_e32 v0, 15, v11
	v_writelane_b32 v255, s17, 19
	s_add_u32 s16, s60, 0x5600
	s_addc_u32 s17, s61, 0
	v_writelane_b32 v254, s16, 59
	v_and_b32_e32 v0, 0xffff0000, v0
	v_lshl_add_u32 v0, v13, 12, v0
	v_writelane_b32 v254, s17, 60
	s_add_u32 s16, s60, 0x10200
	s_addc_u32 s17, s61, 0
	s_add_u32 s26, s60, 0x1ae00
	v_writelane_b32 v254, s16, 61
	s_addc_u32 s27, s61, 0
	s_add_u32 s30, s80, 0x5600
	v_writelane_b32 v254, s17, 62
	s_addc_u32 s31, s81, 0
	v_readlane_b32 s68, v254, 40
	v_readlane_b32 s69, v254, 41
	v_readlane_b32 s70, v254, 42
	v_readlane_b32 s71, v254, 43
	v_readlane_b32 s72, v254, 44
	v_readlane_b32 s73, v254, 45
	v_readlane_b32 s74, v254, 46
	v_readlane_b32 s75, v254, 47
	v_readlane_b32 s76, v254, 48
	v_readlane_b32 s77, v254, 49
	v_readlane_b32 s78, v254, 50
	v_readlane_b32 s79, v254, 51
	v_readlane_b32 s80, v254, 52
	v_readlane_b32 s81, v254, 53
	v_readlane_b32 s82, v254, 54
	v_readlane_b32 s83, v254, 55
	s_lshl_b32 s68, s22, 2
	v_writelane_b32 v254, s68, 40
	v_and_b32_e32 v1, 1, v11
	v_lshl_or_b32 v0, v1, 6, v0
	v_writelane_b32 v254, s69, 41
	v_writelane_b32 v254, s70, 42
	v_writelane_b32 v254, s71, 43
	v_writelane_b32 v254, s72, 44
	v_writelane_b32 v254, s73, 45
	v_writelane_b32 v254, s74, 46
	v_writelane_b32 v254, s75, 47
	v_writelane_b32 v254, s76, 48
	v_writelane_b32 v254, s77, 49
	v_writelane_b32 v254, s78, 50
	v_writelane_b32 v254, s79, 51
	v_writelane_b32 v254, s80, 52
	v_lshl_add_u32 v188, v14, 1, v0
	v_lshlrev_b32_e32 v0, 15, v8
	v_writelane_b32 v254, s81, 53
	v_and_b32_e32 v0, 0xffff0000, v0
	v_writelane_b32 v254, s82, 54
	s_waitcnt vmcnt(6)
	v_lshl_add_u32 v0, v9, 12, v0
	v_and_b32_e32 v1, 1, v8
	v_writelane_b32 v254, s83, 55
	s_add_i32 s19, s7, s4
	s_add_i32 s57, s7, s14
	s_add_i32 s14, s7, s6
	s_add_i32 s15, s7, s15
	v_lshl_or_b32 v0, v1, 6, v0
	v_readlane_b32 s80, v254, 63
	s_add_i32 s19, s19, s34
	s_add_i32 s57, s57, s34
	s_add_i32 s14, s14, s34
	s_add_i32 s15, s15, s34
	v_mov_b32_e32 v189, v179
	v_lshl_add_u32 v190, v10, 1, v0
	v_mov_b32_e32 v191, v179
	v_add_u32_e32 v226, 0, v16
	s_mov_b32 s21, s22
	v_readlane_b32 s81, v255, 0
	s_barrier
	s_branch .LBB0_1195

.LBB0_1198:
	s_add_u32 s70, s8, 0xfff80080
	s_addc_u32 s71, s9, -1
	s_add_i32 s77, 0, 0x10000
	v_add_u32_e32 v140, s77, v225
	ds_read_b128 v[128:131], v140
	ds_read_b128 v[132:135], v140 offset:1024
	ds_read_b128 v[136:139], v140 offset:2048
	ds_read_b128 v[140:143], v140 offset:3072
	s_cmp_eq_u32 s76, 28
	s_cselect_b32 s73, s5, s71
	s_cselect_b32 s72, s4, s70
	s_cselect_b32 s71, s7, s75
	s_cselect_b32 s70, s6, s35
	s_add_i32 m0, s84, 0xc000
	ds_read_b128 v[144:147], v226
	ds_read_b128 v[148:151], v226 offset:1024
	ds_read_b128 v[152:155], v226 offset:2048
	ds_read_b128 v[156:159], v226 offset:3072
	ds_read_b128 v[160:163], v226 offset:4096
	ds_read_b128 v[164:167], v226 offset:5120
	ds_read_b128 v[168:171], v226 offset:6144
	ds_read_b128 v[172:175], v226 offset:7168
	global_load_lds_dwordx4 v190, s[8:9]
	s_add_i32 m0, s84, 0xe000
	s_nop 0
	global_load_lds_dwordx4 v188, s[8:9]
	s_waitcnt lgkmcnt(8)
	s_barrier
	s_waitcnt lgkmcnt(0)
	s_setprio 1
	s_waitcnt lgkmcnt(0)
	v_mfma_f32_16x16x32_bf16 v[124:127], v[128:131], v[144:147], v[124:127]
	v_mfma_f32_16x16x32_bf16 v[60:63], v[136:139], v[144:147], v[60:63]
	v_mfma_f32_16x16x32_bf16 v[116:119], v[128:131], v[152:155], v[116:119]
	v_mfma_f32_16x16x32_bf16 v[52:55], v[136:139], v[152:155], v[52:55]
	v_mfma_f32_16x16x32_bf16 v[108:111], v[128:131], v[160:163], v[108:111]
	v_mfma_f32_16x16x32_bf16 v[44:47], v[136:139], v[160:163], v[44:47]
	v_mfma_f32_16x16x32_bf16 v[100:103], v[128:131], v[168:171], v[100:103]
	v_mfma_f32_16x16x32_bf16 v[36:39], v[136:139], v[168:171], v[36:39]
	v_mfma_f32_16x16x32_bf16 v[124:127], v[132:135], v[148:151], v[124:127]
	v_mfma_f32_16x16x32_bf16 v[60:63], v[140:143], v[148:151], v[60:63]
	v_mfma_f32_16x16x32_bf16 v[116:119], v[132:135], v[156:159], v[116:119]
	v_mfma_f32_16x16x32_bf16 v[52:55], v[140:143], v[156:159], v[52:55]
	v_mfma_f32_16x16x32_bf16 v[108:111], v[132:135], v[164:167], v[108:111]
	v_mfma_f32_16x16x32_bf16 v[44:47], v[140:143], v[164:167], v[44:47]
	v_mfma_f32_16x16x32_bf16 v[100:103], v[132:135], v[172:175], v[100:103]
	v_mfma_f32_16x16x32_bf16 v[36:39], v[140:143], v[172:175], v[36:39]
	s_setprio 0
	s_barrier
	s_add_i32 vcc_lo, 0, 0x14000
	v_add_u32_e32 v176, vcc_lo, v225
	s_add_i32 s77, s77, s24
	ds_read_b128 v[192:195], v176
	ds_read_b128 v[196:199], v176 offset:1024
	ds_read_b128 v[204:207], v176 offset:2048
	ds_read_b128 v[212:215], v176 offset:3072
	v_lshl_add_u64 v[176:177], s[70:71], 0, v[182:183]
	s_mov_b32 m0, s77
	v_lshl_add_u64 v[228:229], s[70:71], 0, v[186:187]
	global_load_lds_dwordx4 v[176:177], off
	s_add_i32 m0, s77, 0x2000
	s_nop 0
	global_load_lds_dwordx4 v[228:229], off
	s_barrier
	s_waitcnt lgkmcnt(0)
	s_setprio 1
	s_waitcnt lgkmcnt(0)
	v_mfma_f32_16x16x32_bf16 v[120:123], v[192:195], v[144:147], v[120:123]
	v_mfma_f32_16x16x32_bf16 v[56:59], v[204:207], v[144:147], v[56:59]
	v_mfma_f32_16x16x32_bf16 v[112:115], v[192:195], v[152:155], v[112:115]
	v_mfma_f32_16x16x32_bf16 v[48:51], v[204:207], v[152:155], v[48:51]
	v_mfma_f32_16x16x32_bf16 v[104:107], v[192:195], v[160:163], v[104:107]
	v_mfma_f32_16x16x32_bf16 v[40:43], v[204:207], v[160:163], v[40:43]
	v_mfma_f32_16x16x32_bf16 v[96:99], v[192:195], v[168:171], v[96:99]
	v_mfma_f32_16x16x32_bf16 v[32:35], v[204:207], v[168:171], v[32:35]
	v_mfma_f32_16x16x32_bf16 v[120:123], v[196:199], v[148:151], v[120:123]
	v_mfma_f32_16x16x32_bf16 v[56:59], v[212:215], v[148:151], v[56:59]
	v_mfma_f32_16x16x32_bf16 v[112:115], v[196:199], v[156:159], v[112:115]
	v_mfma_f32_16x16x32_bf16 v[48:51], v[212:215], v[156:159], v[48:51]
	v_mfma_f32_16x16x32_bf16 v[104:107], v[196:199], v[164:167], v[104:107]
	v_mfma_f32_16x16x32_bf16 v[40:43], v[212:215], v[164:167], v[40:43]
	v_mfma_f32_16x16x32_bf16 v[96:99], v[196:199], v[172:175], v[96:99]
	v_mfma_f32_16x16x32_bf16 v[32:35], v[212:215], v[172:175], v[32:35]
	s_setprio 0
	s_mov_b32 m0, s84
	v_lshl_add_u64 v[230:231], s[72:73], 0, v[180:181]
	s_barrier
	ds_read_b128 v[144:147], v226 offset:16384
	ds_read_b128 v[148:151], v226 offset:17408
	ds_read_b128 v[152:155], v226 offset:18432
	ds_read_b128 v[156:159], v226 offset:19456
	ds_read_b128 v[160:163], v226 offset:20480
	ds_read_b128 v[164:167], v226 offset:21504
	ds_read_b128 v[168:171], v226 offset:22528
	ds_read_b128 v[172:175], v226 offset:23552
	global_load_lds_dwordx4 v[230:231], off
	v_lshl_add_u64 v[232:233], s[72:73], 0, v[184:185]
	s_mov_b32 m0, s85
	s_nop 0
	global_load_lds_dwordx4 v[232:233], off
	s_barrier
	s_waitcnt lgkmcnt(0)
	s_setprio 1
	s_waitcnt lgkmcnt(0)
	v_mfma_f32_16x16x32_bf16 v[92:95], v[128:131], v[144:147], v[92:95]
	v_mfma_f32_16x16x32_bf16 v[28:31], v[136:139], v[144:147], v[28:31]
	v_mfma_f32_16x16x32_bf16 v[84:87], v[128:131], v[152:155], v[84:87]
	v_mfma_f32_16x16x32_bf16 v[20:23], v[136:139], v[152:155], v[20:23]
	v_mfma_f32_16x16x32_bf16 v[76:79], v[128:131], v[160:163], v[76:79]
	v_mfma_f32_16x16x32_bf16 v[12:15], v[136:139], v[160:163], v[12:15]
	v_mfma_f32_16x16x32_bf16 v[68:71], v[128:131], v[168:171], v[68:71]
	v_mfma_f32_16x16x32_bf16 v[4:7], v[136:139], v[168:171], v[4:7]
	v_mfma_f32_16x16x32_bf16 v[92:95], v[132:135], v[148:151], v[92:95]
	v_mfma_f32_16x16x32_bf16 v[28:31], v[140:143], v[148:151], v[28:31]
	v_mfma_f32_16x16x32_bf16 v[84:87], v[132:135], v[156:159], v[84:87]
	v_mfma_f32_16x16x32_bf16 v[20:23], v[140:143], v[156:159], v[20:23]
	v_mfma_f32_16x16x32_bf16 v[76:79], v[132:135], v[164:167], v[76:79]
	v_mfma_f32_16x16x32_bf16 v[12:15], v[140:143], v[164:167], v[12:15]
	v_mfma_f32_16x16x32_bf16 v[68:71], v[132:135], v[172:175], v[68:71]
	v_mfma_f32_16x16x32_bf16 v[4:7], v[140:143], v[172:175], v[4:7]
	s_setprio 0
	s_barrier
	s_add_u32 s78, s70, 0x80000
	s_addc_u32 s79, s71, 0
	s_add_i32 s77, vcc_lo, s24
	s_mov_b32 m0, s77
	s_nop 0
	global_load_lds_dwordx4 v182, s[78:79]
	s_add_i32 m0, s77, 0x2000
	s_nop 0
	global_load_lds_dwordx4 v186, s[78:79]
	s_waitcnt vmcnt(6)
	s_barrier
	s_setprio 1
	v_mfma_f32_16x16x32_bf16 v[88:91], v[192:195], v[144:147], v[88:91]
	v_mfma_f32_16x16x32_bf16 v[24:27], v[204:207], v[144:147], v[24:27]
	v_mfma_f32_16x16x32_bf16 v[80:83], v[192:195], v[152:155], v[80:83]
	v_mfma_f32_16x16x32_bf16 v[16:19], v[204:207], v[152:155], v[16:19]
	v_mfma_f32_16x16x32_bf16 v[72:75], v[192:195], v[160:163], v[72:75]
	v_mfma_f32_16x16x32_bf16 v[8:11], v[204:207], v[160:163], v[8:11]
	v_mfma_f32_16x16x32_bf16 v[64:67], v[192:195], v[168:171], v[64:67]
	v_mfma_f32_16x16x32_bf16 v[0:3], v[204:207], v[168:171], v[0:3]
	v_mfma_f32_16x16x32_bf16 v[88:91], v[196:199], v[148:151], v[88:91]
	v_mfma_f32_16x16x32_bf16 v[24:27], v[212:215], v[148:151], v[24:27]
	v_mfma_f32_16x16x32_bf16 v[80:83], v[196:199], v[156:159], v[80:83]
	v_mfma_f32_16x16x32_bf16 v[16:19], v[212:215], v[156:159], v[16:19]
	v_mfma_f32_16x16x32_bf16 v[72:75], v[196:199], v[164:167], v[72:75]
	v_mfma_f32_16x16x32_bf16 v[8:11], v[212:215], v[164:167], v[8:11]
	v_mfma_f32_16x16x32_bf16 v[64:67], v[196:199], v[172:175], v[64:67]
	v_mfma_f32_16x16x32_bf16 v[0:3], v[212:215], v[172:175], v[0:3]
	s_setprio 0
	s_add_i32 s77, 0, 0x18000
	v_add_u32_e32 v140, s77, v225
	s_barrier
	ds_read_b128 v[128:131], v140
	ds_read_b128 v[132:135], v140 offset:1024
	ds_read_b128 v[136:139], v140 offset:2048
	ds_read_b128 v[140:143], v140 offset:3072
	s_add_u32 s72, s72, 0x80000
	s_addc_u32 s73, s73, 0
	s_mov_b32 m0, s86
	ds_read_b128 v[144:147], v226 offset:32768
	ds_read_b128 v[148:151], v226 offset:33792
	ds_read_b128 v[152:155], v226 offset:34816
	ds_read_b128 v[156:159], v226 offset:35840
	ds_read_b128 v[160:163], v226 offset:36864
	ds_read_b128 v[164:167], v226 offset:37888
	ds_read_b128 v[168:171], v226 offset:38912
	ds_read_b128 v[172:175], v226 offset:39936
	global_load_lds_dwordx4 v180, s[72:73]
	s_mov_b32 m0, s87
	s_nop 0
	global_load_lds_dwordx4 v184, s[72:73]
	s_waitcnt lgkmcnt(8)
	s_barrier
	s_waitcnt lgkmcnt(0)
	s_setprio 1
	s_waitcnt lgkmcnt(0)
	v_mfma_f32_16x16x32_bf16 v[124:127], v[128:131], v[144:147], v[124:127]
	v_mfma_f32_16x16x32_bf16 v[60:63], v[136:139], v[144:147], v[60:63]
	v_mfma_f32_16x16x32_bf16 v[116:119], v[128:131], v[152:155], v[116:119]
	v_mfma_f32_16x16x32_bf16 v[52:55], v[136:139], v[152:155], v[52:55]
	v_mfma_f32_16x16x32_bf16 v[108:111], v[128:131], v[160:163], v[108:111]
	v_mfma_f32_16x16x32_bf16 v[44:47], v[136:139], v[160:163], v[44:47]
	v_mfma_f32_16x16x32_bf16 v[100:103], v[128:131], v[168:171], v[100:103]
	v_mfma_f32_16x16x32_bf16 v[36:39], v[136:139], v[168:171], v[36:39]
	v_mfma_f32_16x16x32_bf16 v[124:127], v[132:135], v[148:151], v[124:127]
	v_mfma_f32_16x16x32_bf16 v[60:63], v[140:143], v[148:151], v[60:63]
	v_mfma_f32_16x16x32_bf16 v[116:119], v[132:135], v[156:159], v[116:119]
	v_mfma_f32_16x16x32_bf16 v[52:55], v[140:143], v[156:159], v[52:55]
	v_mfma_f32_16x16x32_bf16 v[108:111], v[132:135], v[164:167], v[108:111]
	v_mfma_f32_16x16x32_bf16 v[44:47], v[140:143], v[164:167], v[44:47]
	v_mfma_f32_16x16x32_bf16 v[100:103], v[132:135], v[172:175], v[100:103]
	v_mfma_f32_16x16x32_bf16 v[36:39], v[140:143], v[172:175], v[36:39]
	s_setprio 0
	s_barrier
	s_add_i32 s72, 0, 0x1c000
	s_add_i32 s73, s77, s24
	v_add_u32_e32 v178, s72, v225
	v_lshl_add_u64 v[176:177], v[176:177], 0, s[54:55]
	s_mov_b32 m0, s73
	ds_read_b128 v[192:195], v178
	ds_read_b128 v[196:199], v178 offset:1024
	ds_read_b128 v[204:207], v178 offset:2048
	ds_read_b128 v[212:215], v178 offset:3072
	global_load_lds_dwordx4 v[176:177], off
	v_lshl_add_u64 v[176:177], v[228:229], 0, s[54:55]
	s_add_i32 m0, s73, 0x2000
	s_nop 0
	global_load_lds_dwordx4 v[176:177], off
	s_barrier
	s_waitcnt lgkmcnt(0)
	s_setprio 1
	s_waitcnt lgkmcnt(0)
	v_mfma_f32_16x16x32_bf16 v[120:123], v[192:195], v[144:147], v[120:123]
	v_mfma_f32_16x16x32_bf16 v[56:59], v[204:207], v[144:147], v[56:59]
	v_mfma_f32_16x16x32_bf16 v[112:115], v[192:195], v[152:155], v[112:115]
	v_mfma_f32_16x16x32_bf16 v[48:51], v[204:207], v[152:155], v[48:51]
	v_mfma_f32_16x16x32_bf16 v[104:107], v[192:195], v[160:163], v[104:107]
	v_mfma_f32_16x16x32_bf16 v[40:43], v[204:207], v[160:163], v[40:43]
	v_mfma_f32_16x16x32_bf16 v[96:99], v[192:195], v[168:171], v[96:99]
	v_mfma_f32_16x16x32_bf16 v[32:35], v[204:207], v[168:171], v[32:35]
	v_mfma_f32_16x16x32_bf16 v[120:123], v[196:199], v[148:151], v[120:123]
	v_mfma_f32_16x16x32_bf16 v[56:59], v[212:215], v[148:151], v[56:59]
	v_mfma_f32_16x16x32_bf16 v[112:115], v[196:199], v[156:159], v[112:115]
	v_mfma_f32_16x16x32_bf16 v[48:51], v[212:215], v[156:159], v[48:51]
	v_mfma_f32_16x16x32_bf16 v[104:107], v[196:199], v[164:167], v[104:107]
	v_mfma_f32_16x16x32_bf16 v[40:43], v[212:215], v[164:167], v[40:43]
	v_mfma_f32_16x16x32_bf16 v[96:99], v[196:199], v[172:175], v[96:99]
	v_mfma_f32_16x16x32_bf16 v[32:35], v[212:215], v[172:175], v[32:35]
	s_setprio 0
	s_mov_b32 m0, s59
	v_lshl_add_u64 v[176:177], v[230:231], 0, s[54:55]
	s_barrier
	ds_read_b128 v[144:147], v226 offset:49152
	ds_read_b128 v[148:151], v226 offset:50176
	ds_read_b128 v[152:155], v226 offset:51200
	ds_read_b128 v[156:159], v226 offset:52224
	ds_read_b128 v[160:163], v226 offset:53248
	ds_read_b128 v[164:167], v226 offset:54272
	ds_read_b128 v[168:171], v226 offset:55296
	ds_read_b128 v[172:175], v226 offset:56320
	global_load_lds_dwordx4 v[176:177], off
	v_lshl_add_u64 v[176:177], v[232:233], 0, s[54:55]
	s_mov_b32 m0, s20
	s_nop 0
	global_load_lds_dwordx4 v[176:177], off
	s_barrier
	s_waitcnt lgkmcnt(0)
	s_setprio 1
	s_waitcnt lgkmcnt(0)
	v_mfma_f32_16x16x32_bf16 v[92:95], v[128:131], v[144:147], v[92:95]
	v_mfma_f32_16x16x32_bf16 v[28:31], v[136:139], v[144:147], v[28:31]
	v_mfma_f32_16x16x32_bf16 v[84:87], v[128:131], v[152:155], v[84:87]
	v_mfma_f32_16x16x32_bf16 v[20:23], v[136:139], v[152:155], v[20:23]
	v_mfma_f32_16x16x32_bf16 v[76:79], v[128:131], v[160:163], v[76:79]
	v_mfma_f32_16x16x32_bf16 v[12:15], v[136:139], v[160:163], v[12:15]
	v_mfma_f32_16x16x32_bf16 v[68:71], v[128:131], v[168:171], v[68:71]
	v_mfma_f32_16x16x32_bf16 v[4:7], v[136:139], v[168:171], v[4:7]
	v_mfma_f32_16x16x32_bf16 v[92:95], v[132:135], v[148:151], v[92:95]
	v_mfma_f32_16x16x32_bf16 v[28:31], v[140:143], v[148:151], v[28:31]
	v_mfma_f32_16x16x32_bf16 v[84:87], v[132:135], v[156:159], v[84:87]
	v_mfma_f32_16x16x32_bf16 v[20:23], v[140:143], v[156:159], v[20:23]
	v_mfma_f32_16x16x32_bf16 v[76:79], v[132:135], v[164:167], v[76:79]
	v_mfma_f32_16x16x32_bf16 v[12:15], v[140:143], v[164:167], v[12:15]
	v_mfma_f32_16x16x32_bf16 v[68:71], v[132:135], v[172:175], v[68:71]
	v_mfma_f32_16x16x32_bf16 v[4:7], v[140:143], v[172:175], v[4:7]
	s_setprio 0
	s_barrier
	s_add_u32 s70, s70, 0x80080
	s_addc_u32 s71, s71, 0
	s_add_i32 s72, s72, s24
	s_mov_b32 m0, s72
	s_nop 0
	global_load_lds_dwordx4 v182, s[70:71]
	s_add_i32 m0, s72, 0x2000
	s_nop 0
	global_load_lds_dwordx4 v186, s[70:71]
	s_waitcnt vmcnt(6)
	s_barrier
	s_setprio 1
	v_mfma_f32_16x16x32_bf16 v[88:91], v[192:195], v[144:147], v[88:91]
	v_mfma_f32_16x16x32_bf16 v[24:27], v[204:207], v[144:147], v[24:27]
	v_mfma_f32_16x16x32_bf16 v[80:83], v[192:195], v[152:155], v[80:83]
	v_mfma_f32_16x16x32_bf16 v[16:19], v[204:207], v[152:155], v[16:19]
	v_mfma_f32_16x16x32_bf16 v[72:75], v[192:195], v[160:163], v[72:75]
	v_mfma_f32_16x16x32_bf16 v[8:11], v[204:207], v[160:163], v[8:11]
	v_mfma_f32_16x16x32_bf16 v[64:67], v[192:195], v[168:171], v[64:67]
	v_mfma_f32_16x16x32_bf16 v[0:3], v[204:207], v[168:171], v[0:3]
	v_mfma_f32_16x16x32_bf16 v[88:91], v[196:199], v[148:151], v[88:91]
	v_mfma_f32_16x16x32_bf16 v[24:27], v[212:215], v[148:151], v[24:27]
	v_mfma_f32_16x16x32_bf16 v[80:83], v[196:199], v[156:159], v[80:83]
	v_mfma_f32_16x16x32_bf16 v[16:19], v[212:215], v[156:159], v[16:19]
	v_mfma_f32_16x16x32_bf16 v[72:75], v[196:199], v[164:167], v[72:75]
	v_mfma_f32_16x16x32_bf16 v[8:11], v[212:215], v[164:167], v[8:11]
	v_mfma_f32_16x16x32_bf16 v[64:67], v[196:199], v[172:175], v[64:67]
	v_mfma_f32_16x16x32_bf16 v[0:3], v[212:215], v[172:175], v[0:3]
	s_setprio 0
	s_add_i32 s76, s76, 2
	s_add_u32 s35, s35, 0x100
	s_addc_u32 s75, s75, 0
	s_add_u32 s8, s8, 0x100
	s_addc_u32 s9, s9, 0
	s_cmp_gt_u32 s76, 29
	s_barrier
	s_cbranch_scc0 .LBB0_1198
	v_mov_b32_e32 v140, v224
	v_mov_b32_e32 v194, v223
	v_readlane_b32 s4, v255, 16
	v_lshlrev_b32_e32 v227, 6, v140
	v_cmp_lt_i32_e32 vcc, 14, v194
	v_add_u32_e32 v141, s4, v227
	s_mov_b64 s[4:5], 0
	s_and_saveexec_b64 s[6:7], vcc
	s_xor_b64 s[6:7], exec, s[6:7]
	s_cbranch_execz .LBB0_1203
	v_cmp_eq_u32_e32 vcc, 15, v194
	s_and_saveexec_b64 s[8:9], vcc
	s_mov_b64 s[4:5], exec
	ds_write_b128 v141, v[100:103] offset:256
	s_or_b64 exec, exec, s[8:9]
	s_and_b64 s[4:5], s[4:5], exec

.LBB0_1359:
	v_readlane_b32 s6, v255, 20
	v_readlane_b32 s7, v255, 21
	s_lshl_b64 s[6:7], s[6:7], 2
	s_add_u32 s5, s88, s6
	s_addc_u32 s6, s89, s7
	v_bfe_u32 v18, v16, 4, 2
	s_add_u32 s35, s5, 0xc34a000
	v_and_b32_e32 v17, 15, v16
	v_lshlrev_b32_e32 v19, 4, v18
	v_lshlrev_b32_e32 v16, 2, v16
	s_addc_u32 s39, s6, 0
	v_lshl_or_b32 v152, s4, 6, v17
	v_lshl_or_b32 v17, v17, 6, v19
	s_lshl_b32 s4, s4, 13
	v_and_b32_e32 v16, 32, v16
	v_bitop3_b32 v19, v17, s4, v16 bitop3:0xde
	s_lshl_b32 s4, s86, 5
	s_and_b32 s6, s4, 0x60
	s_add_i32 m0, s29, 0x18000
	v_lshl_add_u64 v[6:7], v[6:7], 0, s[54:55]
	s_lshl_b32 s4, s6, 7
	s_waitcnt vmcnt(4)
	s_barrier
	global_load_lds_dwordx4 v[6:7], off
	v_lshl_add_u64 v[4:5], v[4:5], 0, s[54:55]
	s_add_i32 m0, s29, 0x1a000
	s_add_i32 s56, s29, 0x8000
	s_add_i32 s57, s29, 0xa000
	v_bitop3_b32 v153, v17, s4, v16 bitop3:0xde
	global_load_lds_dwordx4 v[4:5], off
	v_lshl_add_u64 v[2:3], v[2:3], 0, s[54:55]
	s_mov_b32 m0, s56
	s_add_u32 s4, s16, 0x158080
	global_load_lds_dwordx4 v[2:3], off
	v_lshl_add_u64 v[0:1], v[0:1], 0, s[54:55]
	s_mov_b32 m0, s57
	s_addc_u32 s5, s17, 0
	global_load_lds_dwordx4 v[0:1], off
	s_add_i32 m0, s29, 0x1c000
	global_load_lds_dwordx4 v178, s[4:5]
	s_add_i32 m0, s29, 0x1e000
	v_lshl_or_b32 v154, v18, 2, s6
	global_load_lds_dwordx4 v144, s[4:5]
	s_movk_i32 s6, 0x1580
	v_lshrrev_b32_e32 v1, 1, v8
	v_mul_lo_u32 v0, v9, s6
	s_mov_b32 s7, 0x15800
	v_mad_u64_u32 v[0:1], s[4:5], v1, s7, v[0:1]
	v_or_b32_e32 v0, v0, v10
	v_add_lshl_u32 v0, v0, v11, 1
	v_mov_b32_e32 v1, v179
	s_mov_b64 s[8:9], 0x158080
	v_lshl_add_u64 v[146:147], v[0:1], 0, s[8:9]
	v_lshrrev_b32_e32 v1, 1, v12
	v_mul_lo_u32 v0, v13, s6
	v_mad_u64_u32 v[0:1], s[4:5], v1, s7, v[0:1]
	s_waitcnt vmcnt(6)
	v_or_b32_e32 v0, v0, v14
	v_add_lshl_u32 v0, v0, v15, 1
	v_mov_b32_e32 v1, v179
	v_lshl_add_u64 v[148:149], v[0:1], 0, s[8:9]
	s_mov_b32 s58, 0
	v_add_u32_e32 v155, 0, v19
	s_barrier

.LBB0_1363:
	s_add_u32 s16, s14, 0x100
	s_addc_u32 s17, s15, 0
	s_add_i32 s68, 0, 0x10000
	v_add_u32_e32 v76, s68, v153
	ds_read_b128 v[48:51], v76
	ds_read_b128 v[68:71], v76 offset:1024
	ds_read_b128 v[72:75], v76 offset:2048
	ds_read_b128 v[76:79], v76 offset:3072
	s_cmpk_eq_i32 s67, 0x52
	s_cselect_b32 s21, s11, s17
	s_cselect_b32 s20, s10, s16
	s_cselect_b32 s19, s13, s66
	s_cselect_b32 s18, s12, s63
	v_lshl_add_u64 v[150:151], s[14:15], 0, v[148:149]
	s_add_i32 m0, s29, 0xc000
	ds_read_b128 v[156:159], v155
	ds_read_b128 v[160:163], v155 offset:1024
	ds_read_b128 v[164:167], v155 offset:2048
	ds_read_b128 v[168:171], v155 offset:3072
	ds_read_b128 v[172:175], v155 offset:4096
	ds_read_b128 v[180:183], v155 offset:5120
	ds_read_b128 v[184:187], v155 offset:6144
	ds_read_b128 v[188:191], v155 offset:7168
	global_load_lds_dwordx4 v[150:151], off
	v_lshl_add_u64 v[150:151], s[14:15], 0, v[146:147]
	s_add_i32 m0, s29, 0xe000
	s_nop 0
	global_load_lds_dwordx4 v[150:151], off
	s_waitcnt lgkmcnt(8)
	s_barrier
	s_waitcnt lgkmcnt(0)
	s_setprio 1
	s_waitcnt lgkmcnt(0)
	v_mfma_f32_16x16x32_bf16 v[140:143], v[48:51], v[156:159], v[140:143]
	v_mfma_f32_16x16x32_bf16 v[136:139], v[72:75], v[156:159], v[136:139]
	v_mfma_f32_16x16x32_bf16 v[124:127], v[48:51], v[164:167], v[124:127]
	v_mfma_f32_16x16x32_bf16 v[120:123], v[72:75], v[164:167], v[120:123]
	v_mfma_f32_16x16x32_bf16 v[116:119], v[48:51], v[172:175], v[116:119]
	v_mfma_f32_16x16x32_bf16 v[112:115], v[72:75], v[172:175], v[112:115]
	v_mfma_f32_16x16x32_bf16 v[100:103], v[48:51], v[184:187], v[100:103]
	v_mfma_f32_16x16x32_bf16 v[96:99], v[72:75], v[184:187], v[96:99]
	v_mfma_f32_16x16x32_bf16 v[140:143], v[68:71], v[160:163], v[140:143]
	v_mfma_f32_16x16x32_bf16 v[136:139], v[76:79], v[160:163], v[136:139]
	v_mfma_f32_16x16x32_bf16 v[124:127], v[68:71], v[168:171], v[124:127]
	v_mfma_f32_16x16x32_bf16 v[120:123], v[76:79], v[168:171], v[120:123]
	v_mfma_f32_16x16x32_bf16 v[116:119], v[68:71], v[180:183], v[116:119]
	v_mfma_f32_16x16x32_bf16 v[112:115], v[76:79], v[180:183], v[112:115]
	v_mfma_f32_16x16x32_bf16 v[100:103], v[68:71], v[188:191], v[100:103]
	v_mfma_f32_16x16x32_bf16 v[96:99], v[76:79], v[188:191], v[96:99]
	s_setprio 0
	s_barrier
	s_add_i32 s69, 0, 0x14000
	v_add_u32_e32 v150, s69, v153
	s_add_i32 s14, s68, s28
	ds_read_b128 v[192:195], v150
	ds_read_b128 v[196:199], v150 offset:1024
	ds_read_b128 v[204:207], v150 offset:2048
	ds_read_b128 v[212:215], v150 offset:3072
	v_lshl_add_u64 v[150:151], s[18:19], 0, v[178:179]
	s_mov_b32 m0, s14
	v_lshl_add_u64 v[176:177], s[18:19], 0, v[144:145]
	global_load_lds_dwordx4 v[150:151], off
	s_add_i32 m0, s14, 0x2000
	s_nop 0
	global_load_lds_dwordx4 v[176:177], off
	s_barrier
	s_waitcnt lgkmcnt(0)
	s_setprio 1
	s_waitcnt lgkmcnt(0)
	v_mfma_f32_16x16x32_bf16 v[132:135], v[192:195], v[156:159], v[132:135]
	v_mfma_f32_16x16x32_bf16 v[128:131], v[204:207], v[156:159], v[128:131]
	v_mfma_f32_16x16x32_bf16 v[108:111], v[192:195], v[164:167], v[108:111]
	v_mfma_f32_16x16x32_bf16 v[104:107], v[204:207], v[164:167], v[104:107]
	v_mfma_f32_16x16x32_bf16 v[92:95], v[192:195], v[172:175], v[92:95]
	v_mfma_f32_16x16x32_bf16 v[88:91], v[204:207], v[172:175], v[88:91]
	v_mfma_f32_16x16x32_bf16 v[84:87], v[192:195], v[184:187], v[84:87]
	v_mfma_f32_16x16x32_bf16 v[80:83], v[204:207], v[184:187], v[80:83]
	v_mfma_f32_16x16x32_bf16 v[132:135], v[196:199], v[160:163], v[132:135]
	v_mfma_f32_16x16x32_bf16 v[128:131], v[212:215], v[160:163], v[128:131]
	v_mfma_f32_16x16x32_bf16 v[108:111], v[196:199], v[168:171], v[108:111]
	v_mfma_f32_16x16x32_bf16 v[104:107], v[212:215], v[168:171], v[104:107]
	v_mfma_f32_16x16x32_bf16 v[92:95], v[196:199], v[180:183], v[92:95]
	v_mfma_f32_16x16x32_bf16 v[88:91], v[212:215], v[180:183], v[88:91]
	v_mfma_f32_16x16x32_bf16 v[84:87], v[196:199], v[188:191], v[84:87]
	v_mfma_f32_16x16x32_bf16 v[80:83], v[212:215], v[188:191], v[80:83]
	s_setprio 0
	s_mov_b32 m0, s29
	v_lshl_add_u64 v[224:225], s[20:21], 0, v[178:179]
	s_barrier
	ds_read_b128 v[156:159], v155 offset:16384
	ds_read_b128 v[160:163], v155 offset:17408
	ds_read_b128 v[164:167], v155 offset:18432
	ds_read_b128 v[168:171], v155 offset:19456
	ds_read_b128 v[172:175], v155 offset:20480
	ds_read_b128 v[180:183], v155 offset:21504
	ds_read_b128 v[184:187], v155 offset:22528
	ds_read_b128 v[188:191], v155 offset:23552
	global_load_lds_dwordx4 v[224:225], off
	v_lshl_add_u64 v[226:227], s[20:21], 0, v[144:145]
	s_mov_b32 m0, s30
	s_nop 0
	global_load_lds_dwordx4 v[226:227], off
	s_barrier
	s_waitcnt lgkmcnt(0)
	s_setprio 1
	s_waitcnt lgkmcnt(0)
	v_mfma_f32_16x16x32_bf16 v[64:67], v[48:51], v[156:159], v[64:67]
	v_mfma_f32_16x16x32_bf16 v[60:63], v[72:75], v[156:159], v[60:63]
	v_mfma_f32_16x16x32_bf16 v[44:47], v[48:51], v[164:167], v[44:47]
	v_mfma_f32_16x16x32_bf16 v[40:43], v[72:75], v[164:167], v[40:43]
	v_mfma_f32_16x16x32_bf16 v[28:31], v[48:51], v[172:175], v[28:31]
	v_mfma_f32_16x16x32_bf16 v[24:27], v[72:75], v[172:175], v[24:27]
	v_mfma_f32_16x16x32_bf16 v[12:15], v[48:51], v[184:187], v[12:15]
	v_mfma_f32_16x16x32_bf16 v[8:11], v[72:75], v[184:187], v[8:11]
	v_mfma_f32_16x16x32_bf16 v[64:67], v[68:71], v[160:163], v[64:67]
	v_mfma_f32_16x16x32_bf16 v[60:63], v[76:79], v[160:163], v[60:63]
	v_mfma_f32_16x16x32_bf16 v[44:47], v[68:71], v[168:171], v[44:47]
	v_mfma_f32_16x16x32_bf16 v[40:43], v[76:79], v[168:171], v[40:43]
	v_mfma_f32_16x16x32_bf16 v[28:31], v[68:71], v[180:183], v[28:31]
	v_mfma_f32_16x16x32_bf16 v[24:27], v[76:79], v[180:183], v[24:27]
	v_mfma_f32_16x16x32_bf16 v[12:15], v[68:71], v[188:191], v[12:15]
	v_mfma_f32_16x16x32_bf16 v[8:11], v[76:79], v[188:191], v[8:11]
	s_setprio 0
	s_barrier
	s_add_u32 s14, s18, 0x158000
	s_addc_u32 s15, s19, 0
	s_add_i32 s68, s69, s28
	s_mov_b32 m0, s68
	s_nop 0
	global_load_lds_dwordx4 v178, s[14:15]
	s_add_i32 m0, s68, 0x2000
	s_nop 0
	global_load_lds_dwordx4 v144, s[14:15]
	s_waitcnt vmcnt(6)
	s_barrier
	s_setprio 1
	v_mfma_f32_16x16x32_bf16 v[52:55], v[204:207], v[156:159], v[52:55]
	v_mfma_f32_16x16x32_bf16 v[36:39], v[192:195], v[164:167], v[36:39]
	v_mfma_f32_16x16x32_bf16 v[32:35], v[204:207], v[164:167], v[32:35]
	v_mfma_f32_16x16x32_bf16 v[20:23], v[192:195], v[172:175], v[20:23]
	v_mfma_f32_16x16x32_bf16 v[16:19], v[204:207], v[172:175], v[16:19]
	v_mfma_f32_16x16x32_bf16 v[4:7], v[192:195], v[184:187], v[4:7]
	v_mfma_f32_16x16x32_bf16 v[0:3], v[204:207], v[184:187], v[0:3]
	v_mfma_f32_16x16x32_bf16 v[48:51], v[192:195], v[156:159], v[56:59]
	v_mfma_f32_16x16x32_bf16 v[52:55], v[212:215], v[160:163], v[52:55]
	v_mfma_f32_16x16x32_bf16 v[36:39], v[196:199], v[168:171], v[36:39]
	v_mfma_f32_16x16x32_bf16 v[32:35], v[212:215], v[168:171], v[32:35]
	v_mfma_f32_16x16x32_bf16 v[20:23], v[196:199], v[180:183], v[20:23]
	v_mfma_f32_16x16x32_bf16 v[16:19], v[212:215], v[180:183], v[16:19]
	v_mfma_f32_16x16x32_bf16 v[4:7], v[196:199], v[188:191], v[4:7]
	v_mfma_f32_16x16x32_bf16 v[0:3], v[212:215], v[188:191], v[0:3]
	v_mfma_f32_16x16x32_bf16 v[48:51], v[196:199], v[160:163], v[48:51]
	s_setprio 0
	s_add_i32 s68, 0, 0x18000
	v_add_u32_e32 v76, s68, v153
	s_barrier
	ds_read_b128 v[56:59], v76
	ds_read_b128 v[68:71], v76 offset:1024
	ds_read_b128 v[72:75], v76 offset:2048
	ds_read_b128 v[76:79], v76 offset:3072
	s_add_u32 s14, s20, 0x158000
	s_addc_u32 s15, s21, 0
	s_mov_b32 m0, s31
	ds_read_b128 v[156:159], v155 offset:32768
	ds_read_b128 v[160:163], v155 offset:33792
	ds_read_b128 v[164:167], v155 offset:34816
	ds_read_b128 v[168:171], v155 offset:35840
	ds_read_b128 v[172:175], v155 offset:36864
	ds_read_b128 v[180:183], v155 offset:37888
	ds_read_b128 v[184:187], v155 offset:38912
	ds_read_b128 v[188:191], v155 offset:39936
	global_load_lds_dwordx4 v178, s[14:15]
	s_mov_b32 m0, s34
	s_nop 0
	global_load_lds_dwordx4 v144, s[14:15]
	s_waitcnt lgkmcnt(8)
	s_barrier
	s_waitcnt lgkmcnt(0)
	s_setprio 1
	s_waitcnt lgkmcnt(0)
	v_mfma_f32_16x16x32_bf16 v[140:143], v[56:59], v[156:159], v[140:143]
	v_mfma_f32_16x16x32_bf16 v[136:139], v[72:75], v[156:159], v[136:139]
	v_mfma_f32_16x16x32_bf16 v[124:127], v[56:59], v[164:167], v[124:127]
	v_mfma_f32_16x16x32_bf16 v[120:123], v[72:75], v[164:167], v[120:123]
	v_mfma_f32_16x16x32_bf16 v[116:119], v[56:59], v[172:175], v[116:119]
	v_mfma_f32_16x16x32_bf16 v[112:115], v[72:75], v[172:175], v[112:115]
	v_mfma_f32_16x16x32_bf16 v[100:103], v[56:59], v[184:187], v[100:103]
	v_mfma_f32_16x16x32_bf16 v[96:99], v[72:75], v[184:187], v[96:99]
	v_mfma_f32_16x16x32_bf16 v[140:143], v[68:71], v[160:163], v[140:143]
	v_mfma_f32_16x16x32_bf16 v[136:139], v[76:79], v[160:163], v[136:139]
	v_mfma_f32_16x16x32_bf16 v[124:127], v[68:71], v[168:171], v[124:127]
	v_mfma_f32_16x16x32_bf16 v[120:123], v[76:79], v[168:171], v[120:123]
	v_mfma_f32_16x16x32_bf16 v[116:119], v[68:71], v[180:183], v[116:119]
	v_mfma_f32_16x16x32_bf16 v[112:115], v[76:79], v[180:183], v[112:115]
	v_mfma_f32_16x16x32_bf16 v[100:103], v[68:71], v[188:191], v[100:103]
	v_mfma_f32_16x16x32_bf16 v[96:99], v[76:79], v[188:191], v[96:99]
	s_setprio 0
	s_barrier
	s_add_i32 s20, 0, 0x1c000
	s_add_i32 s14, s68, s28
	v_add_u32_e32 v212, s20, v153
	v_lshl_add_u64 v[150:151], v[150:151], 0, s[54:55]
	s_mov_b32 m0, s14
	ds_read_b128 v[192:195], v212
	ds_read_b128 v[196:199], v212 offset:1024
	ds_read_b128 v[204:207], v212 offset:2048
	ds_read_b128 v[212:215], v212 offset:3072
	global_load_lds_dwordx4 v[150:151], off
	v_lshl_add_u64 v[150:151], v[176:177], 0, s[54:55]
	s_add_i32 m0, s14, 0x2000
	s_nop 0
	global_load_lds_dwordx4 v[150:151], off
	s_barrier
	s_waitcnt lgkmcnt(0)
	s_setprio 1
	s_waitcnt lgkmcnt(0)
	v_mfma_f32_16x16x32_bf16 v[132:135], v[192:195], v[156:159], v[132:135]
	v_mfma_f32_16x16x32_bf16 v[128:131], v[204:207], v[156:159], v[128:131]
	v_mfma_f32_16x16x32_bf16 v[108:111], v[192:195], v[164:167], v[108:111]
	v_mfma_f32_16x16x32_bf16 v[104:107], v[204:207], v[164:167], v[104:107]
	v_mfma_f32_16x16x32_bf16 v[92:95], v[192:195], v[172:175], v[92:95]
	v_mfma_f32_16x16x32_bf16 v[88:91], v[204:207], v[172:175], v[88:91]
	v_mfma_f32_16x16x32_bf16 v[84:87], v[192:195], v[184:187], v[84:87]
	v_mfma_f32_16x16x32_bf16 v[80:83], v[204:207], v[184:187], v[80:83]
	v_mfma_f32_16x16x32_bf16 v[132:135], v[196:199], v[160:163], v[132:135]
	v_mfma_f32_16x16x32_bf16 v[128:131], v[212:215], v[160:163], v[128:131]
	v_mfma_f32_16x16x32_bf16 v[108:111], v[196:199], v[168:171], v[108:111]
	v_mfma_f32_16x16x32_bf16 v[104:107], v[212:215], v[168:171], v[104:107]
	v_mfma_f32_16x16x32_bf16 v[92:95], v[196:199], v[180:183], v[92:95]
	v_mfma_f32_16x16x32_bf16 v[88:91], v[212:215], v[180:183], v[88:91]
	v_mfma_f32_16x16x32_bf16 v[84:87], v[196:199], v[188:191], v[84:87]
	v_mfma_f32_16x16x32_bf16 v[80:83], v[212:215], v[188:191], v[80:83]
	s_setprio 0
	s_mov_b32 m0, s56
	v_lshl_add_u64 v[150:151], v[224:225], 0, s[54:55]
	s_barrier
	ds_read_b128 v[156:159], v155 offset:49152
	ds_read_b128 v[160:163], v155 offset:50176
	ds_read_b128 v[164:167], v155 offset:51200
	ds_read_b128 v[168:171], v155 offset:52224
	ds_read_b128 v[172:175], v155 offset:53248
	ds_read_b128 v[180:183], v155 offset:54272
	ds_read_b128 v[184:187], v155 offset:55296
	ds_read_b128 v[188:191], v155 offset:56320
	global_load_lds_dwordx4 v[150:151], off
	v_lshl_add_u64 v[150:151], v[226:227], 0, s[54:55]
	s_mov_b32 m0, s57
	s_nop 0
	global_load_lds_dwordx4 v[150:151], off
	s_barrier
	s_waitcnt lgkmcnt(0)
	s_setprio 1
	s_waitcnt lgkmcnt(0)
	v_mfma_f32_16x16x32_bf16 v[64:67], v[56:59], v[156:159], v[64:67]
	v_mfma_f32_16x16x32_bf16 v[60:63], v[72:75], v[156:159], v[60:63]
	v_mfma_f32_16x16x32_bf16 v[44:47], v[56:59], v[164:167], v[44:47]
	v_mfma_f32_16x16x32_bf16 v[40:43], v[72:75], v[164:167], v[40:43]
	v_mfma_f32_16x16x32_bf16 v[28:31], v[56:59], v[172:175], v[28:31]
	v_mfma_f32_16x16x32_bf16 v[24:27], v[72:75], v[172:175], v[24:27]
	v_mfma_f32_16x16x32_bf16 v[12:15], v[56:59], v[184:187], v[12:15]
	v_mfma_f32_16x16x32_bf16 v[8:11], v[72:75], v[184:187], v[8:11]
	v_mfma_f32_16x16x32_bf16 v[64:67], v[68:71], v[160:163], v[64:67]
	v_mfma_f32_16x16x32_bf16 v[60:63], v[76:79], v[160:163], v[60:63]
	v_mfma_f32_16x16x32_bf16 v[44:47], v[68:71], v[168:171], v[44:47]
	v_mfma_f32_16x16x32_bf16 v[40:43], v[76:79], v[168:171], v[40:43]
	v_mfma_f32_16x16x32_bf16 v[28:31], v[68:71], v[180:183], v[28:31]
	v_mfma_f32_16x16x32_bf16 v[24:27], v[76:79], v[180:183], v[24:27]
	v_mfma_f32_16x16x32_bf16 v[12:15], v[68:71], v[188:191], v[12:15]
	v_mfma_f32_16x16x32_bf16 v[8:11], v[76:79], v[188:191], v[8:11]
	s_setprio 0
	s_barrier
	s_add_u32 s14, s18, 0x158080
	s_addc_u32 s15, s19, 0
	s_add_i32 s18, s20, s28
	s_mov_b32 m0, s18
	s_nop 0
	global_load_lds_dwordx4 v178, s[14:15]
	s_add_i32 m0, s18, 0x2000
	s_nop 0
	global_load_lds_dwordx4 v144, s[14:15]
	s_waitcnt vmcnt(6)
	s_barrier
	s_setprio 1
	v_mfma_f32_16x16x32_bf16 v[48:51], v[192:195], v[156:159], v[48:51]
	v_mfma_f32_16x16x32_bf16 v[56:59], v[196:199], v[160:163], v[48:51]
	v_mfma_f32_16x16x32_bf16 v[48:51], v[204:207], v[156:159], v[52:55]
	v_mfma_f32_16x16x32_bf16 v[36:39], v[192:195], v[164:167], v[36:39]
	v_mfma_f32_16x16x32_bf16 v[32:35], v[204:207], v[164:167], v[32:35]
	v_mfma_f32_16x16x32_bf16 v[20:23], v[192:195], v[172:175], v[20:23]
	v_mfma_f32_16x16x32_bf16 v[16:19], v[204:207], v[172:175], v[16:19]
	v_mfma_f32_16x16x32_bf16 v[4:7], v[192:195], v[184:187], v[4:7]
	v_mfma_f32_16x16x32_bf16 v[0:3], v[204:207], v[184:187], v[0:3]
	v_mfma_f32_16x16x32_bf16 v[52:55], v[212:215], v[160:163], v[48:51]
	v_mfma_f32_16x16x32_bf16 v[36:39], v[196:199], v[168:171], v[36:39]
	v_mfma_f32_16x16x32_bf16 v[32:35], v[212:215], v[168:171], v[32:35]
	v_mfma_f32_16x16x32_bf16 v[20:23], v[196:199], v[180:183], v[20:23]
	v_mfma_f32_16x16x32_bf16 v[16:19], v[212:215], v[180:183], v[16:19]
	v_mfma_f32_16x16x32_bf16 v[4:7], v[196:199], v[188:191], v[4:7]
	v_mfma_f32_16x16x32_bf16 v[0:3], v[212:215], v[188:191], v[0:3]
	s_setprio 0
	s_add_i32 s67, s67, 2
	s_add_u32 s63, s63, 0x100
	s_addc_u32 s66, s66, 0
	s_cmpk_gt_u32 s67, 0x53
	s_mov_b64 s[14:15], s[16:17]
	s_barrier
	s_cbranch_scc0 .LBB0_1363
	s_lshl_b32 s12, s61, 8
	s_add_i32 s10, s12, 0xfffff000
	s_ashr_i32 s10, s10, 11
	s_add_i32 s10, s10, 1
	s_cmp_gt_i32 s61, 15
	s_cselect_b32 s10, s10, 0
	v_add_u32_e32 v162, s12, v152
	v_lshl_or_b32 v48, s62, 8, v154
	s_mul_hi_i32 s11, s10, 0xc000
	s_mul_i32 s10, s10, 0xc000
	v_ashrrev_i32_e32 v163, 31, v162
	v_readlane_b32 s68, v252, 37
	s_add_u32 s10, s35, s10
	v_ashrrev_i32_e32 v49, 31, v48
	v_lshlrev_b64 v[150:151], 13, v[162:163]
	v_readlane_b32 s82, v252, 51
	v_readlane_b32 s83, v252, 52
	s_addc_u32 s11, s39, s11
	v_lshlrev_b64 v[160:161], 2, v[48:49]
	v_lshl_add_u64 v[150:151], s[82:83], 0, v[150:151]
	v_lshl_add_u64 v[48:49], s[10:11], 0, v[160:161]
	v_lshl_add_u64 v[150:151], v[150:151], 0, v[160:161]
	global_load_dwordx4 v[76:79], v[48:49], off
	global_load_dwordx4 v[72:75], v[48:49], off offset:64
	global_load_dwordx4 v[68:71], v[48:49], off offset:512
	s_nop 0
	global_load_dwordx4 v[48:51], v[48:49], off offset:576
	s_mov_b64 s[10:11], 0x100000
	global_load_dwordx4 v[156:159], v[150:151], off
	s_mov_b32 s62, s59
	s_mov_b32 s61, s60
	s_mov_b64 s[16:17], s[6:7]
	s_mov_b64 s[14:15], s[8:9]
	v_readlane_b32 s69, v252, 38
	v_readlane_b32 s70, v252, 39
	v_readlane_b32 s71, v252, 40
	v_readlane_b32 s72, v252, 41
	v_readlane_b32 s73, v252, 42
	v_readlane_b32 s74, v252, 43
	v_readlane_b32 s75, v252, 44
	v_readlane_b32 s76, v252, 45
	v_readlane_b32 s77, v252, 46
	v_readlane_b32 s78, v252, 47
	v_readlane_b32 s79, v252, 48
	v_readlane_b32 s80, v252, 49
	v_readlane_b32 s81, v252, 50
	s_waitcnt vmcnt(0)
	v_pk_fma_f32 v[142:143], v[142:143], v[78:79], v[158:159]
	v_pk_fma_f32 v[140:141], v[140:141], v[76:77], v[156:157]
	global_store_dwordx4 v[150:151], v[140:143], off
	global_load_dwordx4 v[140:143], v[150:151], off offset:64
	s_waitcnt vmcnt(0)
	v_pk_fma_f32 v[138:139], v[138:139], v[74:75], v[142:143]
	v_pk_fma_f32 v[136:137], v[136:137], v[72:73], v[140:141]
	global_store_dwordx4 v[150:151], v[136:139], off offset:64
	global_load_dwordx4 v[136:139], v[150:151], off offset:512
	s_waitcnt vmcnt(0)
	v_pk_fma_f32 v[134:135], v[134:135], v[70:71], v[138:139]
	v_pk_fma_f32 v[132:133], v[132:133], v[68:69], v[136:137]
	global_store_dwordx4 v[150:151], v[132:135], off offset:512
	global_load_dwordx4 v[132:135], v[150:151], off offset:576
	s_waitcnt vmcnt(0)
	v_pk_fma_f32 v[130:131], v[130:131], v[50:51], v[134:135]
	v_pk_fma_f32 v[128:129], v[128:129], v[48:49], v[132:133]
	global_store_dwordx4 v[150:151], v[128:131], off offset:576
	s_nop 1
	v_or_b32_e32 v128, 16, v162
	v_ashrrev_i32_e32 v129, 31, v128
	v_lshlrev_b64 v[128:129], 13, v[128:129]
	v_lshl_add_u64 v[128:129], s[82:83], 0, v[128:129]
	v_lshl_add_u64 v[132:133], v[128:129], 0, v[160:161]
	global_load_dwordx4 v[128:131], v[132:133], off
	s_waitcnt vmcnt(0)
	v_pk_fma_f32 v[126:127], v[126:127], v[78:79], v[130:131]
	v_pk_fma_f32 v[124:125], v[124:125], v[76:77], v[128:129]
	global_store_dwordx4 v[132:133], v[124:127], off
	global_load_dwordx4 v[124:127], v[132:133], off offset:64
	s_waitcnt vmcnt(0)
	v_pk_fma_f32 v[122:123], v[122:123], v[74:75], v[126:127]
	v_pk_fma_f32 v[120:121], v[120:121], v[72:73], v[124:125]
	global_store_dwordx4 v[132:133], v[120:123], off offset:64
	global_load_dwordx4 v[120:123], v[132:133], off offset:512
	s_waitcnt vmcnt(0)
	v_pk_fma_f32 v[110:111], v[110:111], v[70:71], v[122:123]
	v_pk_fma_f32 v[108:109], v[108:109], v[68:69], v[120:121]
	global_store_dwordx4 v[132:133], v[108:111], off offset:512
	global_load_dwordx4 v[108:111], v[132:133], off offset:576
	s_waitcnt vmcnt(0)
	v_pk_fma_f32 v[106:107], v[106:107], v[50:51], v[110:111]
	v_pk_fma_f32 v[104:105], v[104:105], v[48:49], v[108:109]
	global_store_dwordx4 v[132:133], v[104:107], off offset:576
	s_nop 1
	v_or_b32_e32 v104, 32, v162
	v_ashrrev_i32_e32 v105, 31, v104
	v_lshlrev_b64 v[104:105], 13, v[104:105]
	v_lshl_add_u64 v[104:105], s[82:83], 0, v[104:105]
	v_lshl_add_u64 v[108:109], v[104:105], 0, v[160:161]
	global_load_dwordx4 v[104:107], v[108:109], off
	s_waitcnt vmcnt(0)
	v_pk_fma_f32 v[106:107], v[118:119], v[78:79], v[106:107]
	v_pk_fma_f32 v[104:105], v[116:117], v[76:77], v[104:105]
	global_store_dwordx4 v[108:109], v[104:107], off
	global_load_dwordx4 v[104:107], v[108:109], off offset:64
	s_waitcnt vmcnt(0)
	v_pk_fma_f32 v[106:107], v[114:115], v[74:75], v[106:107]
	v_pk_fma_f32 v[104:105], v[112:113], v[72:73], v[104:105]
	global_store_dwordx4 v[108:109], v[104:107], off offset:64
	global_load_dwordx4 v[104:107], v[108:109], off offset:512
	s_waitcnt vmcnt(0)
	v_pk_fma_f32 v[94:95], v[94:95], v[70:71], v[106:107]
	v_pk_fma_f32 v[92:93], v[92:93], v[68:69], v[104:105]
	global_store_dwordx4 v[108:109], v[92:95], off offset:512
	global_load_dwordx4 v[92:95], v[108:109], off offset:576
	s_waitcnt vmcnt(0)
	v_pk_fma_f32 v[90:91], v[90:91], v[50:51], v[94:95]
	v_pk_fma_f32 v[88:89], v[88:89], v[48:49], v[92:93]
	global_store_dwordx4 v[108:109], v[88:91], off offset:576
	s_nop 1
	v_or_b32_e32 v88, 48, v162
	v_ashrrev_i32_e32 v89, 31, v88
	v_lshlrev_b64 v[88:89], 13, v[88:89]
	v_lshl_add_u64 v[88:89], s[82:83], 0, v[88:89]
	v_lshl_add_u64 v[92:93], v[88:89], 0, v[160:161]
	global_load_dwordx4 v[88:91], v[92:93], off
	s_waitcnt vmcnt(0)
	v_pk_fma_f32 v[90:91], v[102:103], v[78:79], v[90:91]
	v_pk_fma_f32 v[88:89], v[100:101], v[76:77], v[88:89]
	global_store_dwordx4 v[92:93], v[88:91], off
	global_load_dwordx4 v[88:91], v[92:93], off offset:64
	s_waitcnt vmcnt(0)
	v_pk_fma_f32 v[90:91], v[98:99], v[74:75], v[90:91]
	v_pk_fma_f32 v[88:89], v[96:97], v[72:73], v[88:89]
	global_store_dwordx4 v[92:93], v[88:91], off offset:64
	global_load_dwordx4 v[88:91], v[92:93], off offset:512
	s_waitcnt vmcnt(0)
	v_pk_fma_f32 v[86:87], v[86:87], v[70:71], v[90:91]
	v_pk_fma_f32 v[84:85], v[84:85], v[68:69], v[88:89]
	global_store_dwordx4 v[92:93], v[84:87], off offset:512
	global_load_dwordx4 v[84:87], v[92:93], off offset:576
	s_waitcnt vmcnt(0)
	v_pk_fma_f32 v[82:83], v[82:83], v[50:51], v[86:87]
	v_pk_fma_f32 v[80:81], v[80:81], v[48:49], v[84:85]
	global_store_dwordx4 v[92:93], v[80:83], off offset:576
	s_nop 1
	v_lshl_add_u64 v[80:81], v[150:151], 0, s[10:11]
	s_mov_b32 s10, 0x100000
	v_add_co_u32_e32 v86, vcc, s10, v150
	s_mov_b64 s[10:11], 0x120000
	s_nop 0
	v_addc_co_u32_e32 v87, vcc, 0, v151, vcc
	global_load_dwordx4 v[82:85], v[86:87], off
	s_waitcnt vmcnt(0)
	v_pk_fma_f32 v[66:67], v[66:67], v[78:79], v[84:85]
	v_pk_fma_f32 v[64:65], v[64:65], v[76:77], v[82:83]
	global_store_dwordx4 v[86:87], v[64:67], off
	global_load_dwordx4 v[64:67], v[80:81], off offset:64
	s_waitcnt vmcnt(0)
	v_pk_fma_f32 v[62:63], v[62:63], v[74:75], v[66:67]
	v_pk_fma_f32 v[60:61], v[60:61], v[72:73], v[64:65]
	global_store_dwordx4 v[80:81], v[60:63], off offset:64
	global_load_dwordx4 v[60:63], v[80:81], off offset:512
	s_waitcnt vmcnt(0)
	v_pk_fma_f32 v[58:59], v[58:59], v[70:71], v[62:63]
	v_pk_fma_f32 v[56:57], v[56:57], v[68:69], v[60:61]
	global_store_dwordx4 v[80:81], v[56:59], off offset:512
	global_load_dwordx4 v[56:59], v[80:81], off offset:576
	s_waitcnt vmcnt(0)
	v_pk_fma_f32 v[52:53], v[52:53], v[48:49], v[56:57]
	v_lshl_add_u64 v[56:57], v[150:151], 0, s[10:11]
	s_mov_b32 s10, 0x120000
	v_pk_fma_f32 v[54:55], v[54:55], v[50:51], v[58:59]
	v_add_co_u32_e32 v58, vcc, s10, v150
	global_store_dwordx4 v[80:81], v[52:55], off offset:576
	s_nop 0
	v_addc_co_u32_e32 v59, vcc, 0, v151, vcc
	global_load_dwordx4 v[52:55], v[58:59], off
	s_mov_b64 s[10:11], 0x140000
	s_waitcnt vmcnt(0)
	v_pk_fma_f32 v[46:47], v[46:47], v[78:79], v[54:55]
	v_pk_fma_f32 v[44:45], v[44:45], v[76:77], v[52:53]
	global_store_dwordx4 v[58:59], v[44:47], off
	global_load_dwordx4 v[44:47], v[56:57], off offset:64
	s_waitcnt vmcnt(0)
	v_pk_fma_f32 v[42:43], v[42:43], v[74:75], v[46:47]
	v_pk_fma_f32 v[40:41], v[40:41], v[72:73], v[44:45]
	global_store_dwordx4 v[56:57], v[40:43], off offset:64
	global_load_dwordx4 v[40:43], v[56:57], off offset:512
	s_waitcnt vmcnt(0)
	v_pk_fma_f32 v[38:39], v[38:39], v[70:71], v[42:43]
	v_pk_fma_f32 v[36:37], v[36:37], v[68:69], v[40:41]
	global_store_dwordx4 v[56:57], v[36:39], off offset:512
	global_load_dwordx4 v[36:39], v[56:57], off offset:576
	s_waitcnt vmcnt(0)
	v_pk_fma_f32 v[34:35], v[34:35], v[50:51], v[38:39]
	v_pk_fma_f32 v[32:33], v[32:33], v[48:49], v[36:37]
	global_store_dwordx4 v[56:57], v[32:35], off offset:576
	s_nop 1
	v_lshl_add_u64 v[32:33], v[150:151], 0, s[10:11]
	s_mov_b32 s10, 0x140000
	v_add_co_u32_e32 v38, vcc, s10, v150
	s_mov_b64 s[10:11], 0x160000
	s_nop 0
	v_addc_co_u32_e32 v39, vcc, 0, v151, vcc
	global_load_dwordx4 v[34:37], v[38:39], off
	s_waitcnt vmcnt(0)
	v_pk_fma_f32 v[30:31], v[30:31], v[78:79], v[36:37]
	v_pk_fma_f32 v[28:29], v[28:29], v[76:77], v[34:35]
	global_store_dwordx4 v[38:39], v[28:31], off
	global_load_dwordx4 v[28:31], v[32:33], off offset:64
	s_waitcnt vmcnt(0)
	v_pk_fma_f32 v[26:27], v[26:27], v[74:75], v[30:31]
	v_pk_fma_f32 v[24:25], v[24:25], v[72:73], v[28:29]
	global_store_dwordx4 v[32:33], v[24:27], off offset:64
	global_load_dwordx4 v[24:27], v[32:33], off offset:512
	s_waitcnt vmcnt(0)
	v_pk_fma_f32 v[22:23], v[22:23], v[70:71], v[26:27]
	v_pk_fma_f32 v[20:21], v[20:21], v[68:69], v[24:25]
	global_store_dwordx4 v[32:33], v[20:23], off offset:512
	global_load_dwordx4 v[20:23], v[32:33], off offset:576
	s_waitcnt vmcnt(0)
	v_pk_fma_f32 v[18:19], v[18:19], v[50:51], v[22:23]
	v_pk_fma_f32 v[16:17], v[16:17], v[48:49], v[20:21]
	global_store_dwordx4 v[32:33], v[16:19], off offset:576
	s_nop 1
	v_lshl_add_u64 v[16:17], v[150:151], 0, s[10:11]
	s_mov_b32 s10, 0x160000
	v_add_co_u32_e32 v22, vcc, s10, v150
	s_nop 1
	v_addc_co_u32_e32 v23, vcc, 0, v151, vcc
	global_load_dwordx4 v[18:21], v[22:23], off
	s_and_b64 vcc, exec, s[4:5]
	s_waitcnt vmcnt(0)
	v_pk_fma_f32 v[14:15], v[14:15], v[78:79], v[20:21]
	v_pk_fma_f32 v[12:13], v[12:13], v[76:77], v[18:19]
	global_store_dwordx4 v[22:23], v[12:15], off
	global_load_dwordx4 v[12:15], v[16:17], off offset:64
	s_waitcnt vmcnt(0)
	v_pk_fma_f32 v[10:11], v[10:11], v[74:75], v[14:15]
	v_pk_fma_f32 v[8:9], v[8:9], v[72:73], v[12:13]
	global_store_dwordx4 v[16:17], v[8:11], off offset:64
	global_load_dwordx4 v[8:11], v[16:17], off offset:512
	s_waitcnt vmcnt(0)
	v_pk_fma_f32 v[6:7], v[6:7], v[70:71], v[10:11]
	v_pk_fma_f32 v[4:5], v[4:5], v[68:69], v[8:9]
	global_store_dwordx4 v[16:17], v[4:7], off offset:512
	global_load_dwordx4 v[4:7], v[16:17], off offset:576
	s_waitcnt vmcnt(0)
	v_pk_fma_f32 v[2:3], v[2:3], v[50:51], v[6:7]
	v_pk_fma_f32 v[0:1], v[0:1], v[48:49], v[4:5]
	global_store_dwordx4 v[16:17], v[0:3], off offset:576
	s_cbranch_vccz .LBB0_1360
	s_waitcnt vmcnt(0)
	s_mov_b32 s4, s86
	s_cmp_gt_u32 s4, 3
	s_movk_i32 s57, 0x404
	s_cbranch_scc1 .LBB0_1367
	s_barrier
